# GEMM units: peeled first K-tile with C=0 MFMAs replaces the 128 accumulator-zeroing v_movs per unit
# speedup vs baseline: 1.0055x; 1.0031x over previous
; #define PG8_STAGE(bufoff, gbase, voff) do { _Pragma("unroll") for (int _i = 0; _i < 2; ++_i) \
;         __builtin_amdgcn_global_load_lds((const unsigned*)((const char*)(gbase) + (voff)[_i]), (LAS unsigned*)(lds + (bufoff) + ldsw + _i * 8192), 16, 0, 0); } while (0)
; #define PG8_LDA(dst, b, h) do { _Pragma("unroll") for (int m = 0; m < 4; ++m) _Pragma("unroll") for (int k = 0; k < 2; ++k) dst[m][k] = *(const LAS bf16x8*)(lds + PG8_SA(b, h) + aoff + m * 2048 + k * 1024); } while (0)
; #define PG8_LDB(dst, b, h) do { _Pragma("unroll") for (int n = 0; n < 2; ++n) _Pragma("unroll") for (int k = 0; k < 2; ++k) dst[n][k] = *(const LAS bf16x8*)(lds + PG8_SB(b, h) + boff + n * 2048 + k * 1024); } while (0)
; #define PG8_MMA(ai, bj, At, Bt) do { __builtin_amdgcn_s_setprio(1); _Pragma("unroll") for (int m = 0; m < 4; ++m) _Pragma("unroll") for (int n = 0; n < 2; ++n) _Pragma("unroll") for (int k = 0; k < 2; ++k) \
;         acc[ai][bj][m][n] = __builtin_amdgcn_mfma_f32_16x16x32_bf16(Bt[n][k], At[m][k], acc[ai][bj][m][n], 0, 0, 0); __builtin_amdgcn_s_setprio(0); } while (0)
; #define PG8_WAIT_V(n) asm volatile("s_waitcnt vmcnt(" #n ")" ::: "memory")
; #define PG8_WAIT_L(n) asm volatile("s_waitcnt lgkmcnt(" #n ")" ::: "memory")
; #define PG8_BAR __builtin_amdgcn_s_barrier()
; #define PG8_SCHED __builtin_amdgcn_sched_barrier(0)
; template <class Epi, class Sched, bool ALIGN_EPI>
; __device__ __forceinline__ void gemm_phase(LAS unsigned char* lds, const int wid, const int lda_, const int ldb_, const int K_, const Sched& S, const Epi& E) {
;     ...
;         const bool has_next = S.next(ui + 1, nxt);
;         const int nt = S.nt(cur);
;         const char* nA = has_next ? S.a(nxt) : cA; const char* nB = has_next ? S.b(nxt) : cB;
; #pragma unroll 1
;         for (int t = 0; t < nt; t += 2) {
;             const bool last = (t == nt - 2);
;             const char* a1 = cA + (size_t)(t + 1) * kstep;
;             const char* a2 = last ? nA : cA + (size_t)(t + 2) * kstep; const char* b2 = last ? nB : cB + (size_t)(t + 2) * kstep;
;             const char* a3 = a2 + kstep; const char* b3 = b2 + kstep;
;             PG8_LDB(B0, 0, 0); PG8_LDB(B1, 0, 1); PG8_SCHED; PG8_LDA(At, 0, 0); PG8_STAGE(PG8_SA(1, 1), a1 + hstepA, voffA);
;             PG8_WAIT_V(8); PG8_WAIT_L(0); PG8_BAR; PG8_MMA(0, 0, At, B0); PG8_MMA(0, 1, At, B1); PG8_BAR; PG8_SCHED;
.LBB0_298:
	s_ashr_i32 s37, s36, 31
	s_xor_b64 s[40:41], s[4:5], -1
	s_lshl_b64 s[38:39], s[36:37], 20
	v_readlane_b32 s42, v253, 52
	v_readlane_b32 s43, v253, 53
	s_add_u32 s38, s42, s38
	s_addc_u32 s39, s43, s39
	s_and_b64 s[42:43], s[4:5], exec
	s_cselect_b32 s31, s39, s47
	s_cselect_b32 s37, s38, s46
	s_ashr_i32 s35, s34, 31
	s_lshl_b64 s[42:43], s[34:35], 20
	s_add_u32 s42, s7, s42
	s_addc_u32 s43, s14, s43
	s_and_b64 s[4:5], s[4:5], exec
	s_cselect_b32 s4, s43, s49
	s_cselect_b32 s5, s42, s48
	s_add_u32 s50, s46, 0x80
	s_addc_u32 s51, s47, 0
	s_add_u32 s35, s48, 0x100
	v_lshl_add_u64 v[156:157], s[50:51], 0, v[152:153]
	v_lshl_add_u64 v[158:159], s[50:51], 0, v[154:155]
	s_addc_u32 s45, s49, 0
	s_mov_b32 s76, -2
	s_mov_b64 s[48:49], 0
	s_add_u32 s17, s46, s48
	s_addc_u32 s27, s47, s49
	s_add_u32 s17, s17, 0x100
	s_addc_u32 s27, s27, 0
	s_add_u32 s77, s35, s48
	s_addc_u32 s78, s45, s49
	s_add_i32 s80, 0, 0x10000
	s_cmpk_eq_i32 s48, 0xf00
	s_cselect_b32 s51, s31, s27
	s_cselect_b32 s50, s37, s17
	v_add_u32_e32 v141, s80, v135
	s_cselect_b32 s79, s4, s78
	s_cselect_b32 s78, s5, s77
	s_add_i32 s17, 0, 0x14000
	ds_read_b128 v[160:163], v141
	ds_read_b128 v[164:167], v141 offset:1024
	ds_read_b128 v[168:171], v141 offset:2048
	ds_read_b128 v[172:175], v141 offset:3072
	v_add_u32_e32 v141, s17, v135
	ds_read_b128 v[180:183], v141
	ds_read_b128 v[184:187], v141 offset:1024
	ds_read_b128 v[188:191], v141 offset:2048
	ds_read_b128 v[192:195], v141 offset:3072
	v_lshl_add_u64 v[228:229], v[158:159], 0, s[48:49]
	s_add_i32 m0, s16, 0xc000
	ds_read_b128 v[196:199], v139
	ds_read_b128 v[200:203], v139 offset:1024
	ds_read_b128 v[204:207], v139 offset:2048
	ds_read_b128 v[208:211], v139 offset:3072
	ds_read_b128 v[212:215], v139 offset:4096
	ds_read_b128 v[216:219], v139 offset:5120
	ds_read_b128 v[220:223], v139 offset:6144
	ds_read_b128 v[224:227], v139 offset:7168
	global_load_lds_dwordx4 v[228:229], off
	v_lshl_add_u64 v[228:229], v[156:157], 0, s[48:49]
	s_add_i32 m0, s16, 0xe000
	s_nop 0
	global_load_lds_dwordx4 v[228:229], off
	s_waitcnt vmcnt(8)
	s_waitcnt lgkmcnt(0)
	s_barrier
	s_setprio 1
	s_waitcnt lgkmcnt(0)
	v_mfma_f32_16x16x32_bf16 v[124:127], v[160:163], v[196:199], 0
	v_mfma_f32_16x16x32_bf16 v[120:123], v[168:171], v[196:199], 0
	v_mfma_f32_16x16x32_bf16 v[116:119], v[160:163], v[204:207], 0
	v_mfma_f32_16x16x32_bf16 v[112:115], v[168:171], v[204:207], 0
	v_mfma_f32_16x16x32_bf16 v[100:103], v[160:163], v[212:215], 0
	v_mfma_f32_16x16x32_bf16 v[96:99], v[168:171], v[212:215], 0
	v_mfma_f32_16x16x32_bf16 v[84:87], v[160:163], v[220:223], 0
	v_mfma_f32_16x16x32_bf16 v[80:83], v[168:171], v[220:223], 0
	v_mfma_f32_16x16x32_bf16 v[124:127], v[164:167], v[200:203], v[124:127]
	v_mfma_f32_16x16x32_bf16 v[120:123], v[172:175], v[200:203], v[120:123]
	v_mfma_f32_16x16x32_bf16 v[116:119], v[164:167], v[208:211], v[116:119]
	v_mfma_f32_16x16x32_bf16 v[112:115], v[172:175], v[208:211], v[112:115]
	v_mfma_f32_16x16x32_bf16 v[100:103], v[164:167], v[216:219], v[100:103]
	v_mfma_f32_16x16x32_bf16 v[96:99], v[172:175], v[216:219], v[96:99]
	v_mfma_f32_16x16x32_bf16 v[84:87], v[164:167], v[224:227], v[84:87]
	v_mfma_f32_16x16x32_bf16 v[80:83], v[172:175], v[224:227], v[80:83]
	s_setprio 0
	s_setprio 1
	v_mfma_f32_16x16x32_bf16 v[108:111], v[180:183], v[196:199], 0
	v_mfma_f32_16x16x32_bf16 v[104:107], v[188:191], v[196:199], 0
	v_mfma_f32_16x16x32_bf16 v[92:95], v[180:183], v[204:207], 0
	v_mfma_f32_16x16x32_bf16 v[88:91], v[188:191], v[204:207], 0
	v_mfma_f32_16x16x32_bf16 v[76:79], v[180:183], v[212:215], 0
	v_mfma_f32_16x16x32_bf16 v[72:75], v[188:191], v[212:215], 0
	v_mfma_f32_16x16x32_bf16 v[68:71], v[180:183], v[220:223], 0
	v_mfma_f32_16x16x32_bf16 v[64:67], v[188:191], v[220:223], 0
	v_mfma_f32_16x16x32_bf16 v[108:111], v[184:187], v[200:203], v[108:111]
	v_mfma_f32_16x16x32_bf16 v[104:107], v[192:195], v[200:203], v[104:107]
	v_mfma_f32_16x16x32_bf16 v[92:95], v[184:187], v[208:211], v[92:95]
	v_mfma_f32_16x16x32_bf16 v[88:91], v[192:195], v[208:211], v[88:91]
	v_mfma_f32_16x16x32_bf16 v[76:79], v[184:187], v[216:219], v[76:79]
	v_mfma_f32_16x16x32_bf16 v[72:75], v[192:195], v[216:219], v[72:75]
	v_mfma_f32_16x16x32_bf16 v[68:71], v[184:187], v[224:227], v[68:71]
	v_mfma_f32_16x16x32_bf16 v[64:67], v[192:195], v[224:227], v[64:67]
	s_setprio 0
	s_barrier
; #define PG8_STAGE(bufoff, gbase, voff) do { _Pragma("unroll") for (int _i = 0; _i < 2; ++_i) \
;         __builtin_amdgcn_global_load_lds((const unsigned*)((const char*)(gbase) + (voff)[_i]), (LAS unsigned*)(lds + (bufoff) + ldsw + _i * 8192), 16, 0, 0); } while (0)
; #define PG8_LDA(dst, b, h) do { _Pragma("unroll") for (int m = 0; m < 4; ++m) _Pragma("unroll") for (int k = 0; k < 2; ++k) dst[m][k] = *(const LAS bf16x8*)(lds + PG8_SA(b, h) + aoff + m * 2048 + k * 1024); } while (0)
; #define PG8_MMA(ai, bj, At, Bt) do { __builtin_amdgcn_s_setprio(1); _Pragma("unroll") for (int m = 0; m < 4; ++m) _Pragma("unroll") for (int n = 0; n < 2; ++n) _Pragma("unroll") for (int k = 0; k < 2; ++k) \
;         acc[ai][bj][m][n] = __builtin_amdgcn_mfma_f32_16x16x32_bf16(Bt[n][k], At[m][k], acc[ai][bj][m][n], 0, 0, 0); __builtin_amdgcn_s_setprio(0); } while (0)
; #define PG8_WAIT_V(n) asm volatile("s_waitcnt vmcnt(" #n ")" ::: "memory")
; #define PG8_WAIT_L(n) asm volatile("s_waitcnt lgkmcnt(" #n ")" ::: "memory")
; #define PG8_BAR __builtin_amdgcn_s_barrier()
; #define PG8_SCHED __builtin_amdgcn_sched_barrier(0)
; template <class Epi, class Sched, bool ALIGN_EPI>
; __device__ __forceinline__ void gemm_phase(LAS unsigned char* lds, const int wid, const int lda_, const int ldb_, const int K_, const Sched& S, const Epi& E) {
;     ...
;             PG8_LDA(At, 0, 1); PG8_STAGE(PG8_SB(0, 0), b2, voffB); PG8_STAGE(PG8_SB(0, 1), b2 + hstepB, voffB); PG8_STAGE(PG8_SA(0, 0), a2, voffA);
;             PG8_WAIT_V(8); PG8_WAIT_L(0); PG8_BAR; PG8_MMA(1, 0, At, B0); PG8_MMA(1, 1, At, B1); PG8_BAR; PG8_SCHED;
	s_add_i32 s27, s80, s3
	v_lshl_add_u64 v[228:229], s[78:79], 0, v[176:177]
	s_mov_b32 m0, s27
	ds_read_b128 v[196:199], v139 offset:16384
	ds_read_b128 v[200:203], v139 offset:17408
	ds_read_b128 v[204:207], v139 offset:18432
	ds_read_b128 v[208:211], v139 offset:19456
	ds_read_b128 v[212:215], v139 offset:20480
	ds_read_b128 v[216:219], v139 offset:21504
	ds_read_b128 v[220:223], v139 offset:22528
	ds_read_b128 v[224:227], v139 offset:23552
	global_load_lds_dwordx4 v[228:229], off
	s_add_i32 m0, s27, 0x2000
	v_lshl_add_u64 v[230:231], s[78:79], 0, v[128:129]
	s_add_u32 s78, s78, s10
	s_addc_u32 s79, s79, s11
	s_add_i32 s17, s17, s3
	global_load_lds_dwordx4 v[230:231], off
	v_lshl_add_u64 v[232:233], s[78:79], 0, v[176:177]
	s_mov_b32 m0, s17
	v_lshl_add_u64 v[234:235], s[78:79], 0, v[128:129]
	global_load_lds_dwordx4 v[232:233], off
	s_add_i32 m0, s17, 0x2000
	v_lshl_add_u64 v[236:237], s[50:51], 0, v[132:133]
	global_load_lds_dwordx4 v[234:235], off
	s_mov_b32 m0, s16
	v_lshl_add_u64 v[246:247], s[50:51], 0, v[130:131]
	global_load_lds_dwordx4 v[236:237], off
	s_mov_b32 m0, s15
	s_nop 0
	global_load_lds_dwordx4 v[246:247], off
	s_waitcnt vmcnt(8)
	s_waitcnt lgkmcnt(0)
	s_barrier
	s_setprio 1
	s_waitcnt lgkmcnt(0)
	v_mfma_f32_16x16x32_bf16 v[60:63], v[160:163], v[196:199], 0
	v_mfma_f32_16x16x32_bf16 v[56:59], v[168:171], v[196:199], 0
	v_mfma_f32_16x16x32_bf16 v[52:55], v[160:163], v[204:207], 0
	v_mfma_f32_16x16x32_bf16 v[48:51], v[168:171], v[204:207], 0
	v_mfma_f32_16x16x32_bf16 v[36:39], v[160:163], v[212:215], 0
	v_mfma_f32_16x16x32_bf16 v[32:35], v[168:171], v[212:215], 0
	v_mfma_f32_16x16x32_bf16 v[20:23], v[160:163], v[220:223], 0
	v_mfma_f32_16x16x32_bf16 v[16:19], v[168:171], v[220:223], 0
	v_mfma_f32_16x16x32_bf16 v[60:63], v[164:167], v[200:203], v[60:63]
	v_mfma_f32_16x16x32_bf16 v[56:59], v[172:175], v[200:203], v[56:59]
	v_mfma_f32_16x16x32_bf16 v[52:55], v[164:167], v[208:211], v[52:55]
	v_mfma_f32_16x16x32_bf16 v[48:51], v[172:175], v[208:211], v[48:51]
	v_mfma_f32_16x16x32_bf16 v[36:39], v[164:167], v[216:219], v[36:39]
	v_mfma_f32_16x16x32_bf16 v[32:35], v[172:175], v[216:219], v[32:35]
	v_mfma_f32_16x16x32_bf16 v[20:23], v[164:167], v[224:227], v[20:23]
	v_mfma_f32_16x16x32_bf16 v[16:19], v[172:175], v[224:227], v[16:19]
	s_setprio 0
	s_setprio 1
	v_mfma_f32_16x16x32_bf16 v[44:47], v[180:183], v[196:199], 0
	v_mfma_f32_16x16x32_bf16 v[40:43], v[188:191], v[196:199], 0
	v_mfma_f32_16x16x32_bf16 v[28:31], v[180:183], v[204:207], 0
	v_mfma_f32_16x16x32_bf16 v[24:27], v[188:191], v[204:207], 0
	v_mfma_f32_16x16x32_bf16 v[12:15], v[180:183], v[212:215], 0
	v_mfma_f32_16x16x32_bf16 v[8:11], v[188:191], v[212:215], 0
	v_mfma_f32_16x16x32_bf16 v[4:7], v[180:183], v[220:223], 0
	v_mfma_f32_16x16x32_bf16 v[0:3], v[188:191], v[220:223], 0
	v_mfma_f32_16x16x32_bf16 v[44:47], v[184:187], v[200:203], v[44:47]
	v_mfma_f32_16x16x32_bf16 v[40:43], v[192:195], v[200:203], v[40:43]
	v_mfma_f32_16x16x32_bf16 v[28:31], v[184:187], v[208:211], v[28:31]
	v_mfma_f32_16x16x32_bf16 v[24:27], v[192:195], v[208:211], v[24:27]
	v_mfma_f32_16x16x32_bf16 v[12:15], v[184:187], v[216:219], v[12:15]
	v_mfma_f32_16x16x32_bf16 v[8:11], v[192:195], v[216:219], v[8:11]
	v_mfma_f32_16x16x32_bf16 v[4:7], v[184:187], v[224:227], v[4:7]
	v_mfma_f32_16x16x32_bf16 v[0:3], v[192:195], v[224:227], v[0:3]
	s_setprio 0
	s_barrier
	s_branch .Lgemm_join_299

; #define PG8_STAGE(bufoff, gbase, voff) do { _Pragma("unroll") for (int _i = 0; _i < 2; ++_i) \
;         __builtin_amdgcn_global_load_lds((const unsigned*)((const char*)(gbase) + (voff)[_i]), (LAS unsigned*)(lds + (bufoff) + ldsw + _i * 8192), 16, 0, 0); } while (0)
; #define PG8_LDA(dst, b, h) do { _Pragma("unroll") for (int m = 0; m < 4; ++m) _Pragma("unroll") for (int k = 0; k < 2; ++k) dst[m][k] = *(const LAS bf16x8*)(lds + PG8_SA(b, h) + aoff + m * 2048 + k * 1024); } while (0)
; #define PG8_LDB(dst, b, h) do { _Pragma("unroll") for (int n = 0; n < 2; ++n) _Pragma("unroll") for (int k = 0; k < 2; ++k) dst[n][k] = *(const LAS bf16x8*)(lds + PG8_SB(b, h) + boff + n * 2048 + k * 1024); } while (0)
; #define PG8_MMA(ai, bj, At, Bt) do { __builtin_amdgcn_s_setprio(1); _Pragma("unroll") for (int m = 0; m < 4; ++m) _Pragma("unroll") for (int n = 0; n < 2; ++n) _Pragma("unroll") for (int k = 0; k < 2; ++k) \
;         acc[ai][bj][m][n] = __builtin_amdgcn_mfma_f32_16x16x32_bf16(Bt[n][k], At[m][k], acc[ai][bj][m][n], 0, 0, 0); __builtin_amdgcn_s_setprio(0); } while (0)
; #define PG8_WAIT_V(n) asm volatile("s_waitcnt vmcnt(" #n ")" ::: "memory")
; #define PG8_WAIT_L(n) asm volatile("s_waitcnt lgkmcnt(" #n ")" ::: "memory")
; #define PG8_BAR __builtin_amdgcn_s_barrier()
; #define PG8_SCHED __builtin_amdgcn_sched_barrier(0)
; template <class Epi, class Sched, bool ALIGN_EPI>
; __device__ __forceinline__ void gemm_phase(LAS unsigned char* lds, const int wid, const int lda_, const int ldb_, const int K_, const Sched& S, const Epi& E) {
;     ...
;             PG8_LDB(B0, 1, 0); PG8_LDB(B1, 1, 1); PG8_SCHED; PG8_LDA(At, 1, 0); PG8_STAGE(PG8_SA(0, 1), a2 + hstepA, voffA);
;             PG8_WAIT_V(8); PG8_WAIT_L(0); PG8_BAR; PG8_MMA(0, 0, At, B0); PG8_MMA(0, 1, At, B1); PG8_BAR; PG8_SCHED;
.Lgemm_join_299:
	s_add_i32 s17, 0, 0x18000
	v_add_u32_e32 v141, s17, v135
	s_add_i32 s27, 0, 0x1c000
	ds_read_b128 v[160:163], v141
	ds_read_b128 v[164:167], v141 offset:1024
	ds_read_b128 v[168:171], v141 offset:2048
	ds_read_b128 v[172:175], v141 offset:3072
	v_add_u32_e32 v141, s27, v135
	ds_read_b128 v[180:183], v141
	ds_read_b128 v[184:187], v141 offset:1024
	ds_read_b128 v[188:191], v141 offset:2048
	ds_read_b128 v[192:195], v141 offset:3072
	s_add_u32 s50, s50, s0
	s_addc_u32 s51, s51, s1
	s_mov_b32 m0, s26
	v_lshl_add_u64 v[248:249], s[50:51], 0, v[132:133]
	ds_read_b128 v[196:199], v139 offset:32768
	ds_read_b128 v[200:203], v139 offset:33792
	ds_read_b128 v[204:207], v139 offset:34816
	ds_read_b128 v[208:211], v139 offset:35840
	ds_read_b128 v[212:215], v139 offset:36864
	ds_read_b128 v[216:219], v139 offset:37888
	ds_read_b128 v[220:223], v139 offset:38912
	ds_read_b128 v[224:227], v139 offset:39936
	global_load_lds_dwordx4 v[248:249], off
	v_lshl_add_u64 v[248:249], s[50:51], 0, v[130:131]
	s_mov_b32 m0, s72
	s_nop 0
	global_load_lds_dwordx4 v[248:249], off
	s_waitcnt vmcnt(8)
	s_waitcnt lgkmcnt(0)
	s_barrier
	s_setprio 1
	s_waitcnt lgkmcnt(0)
	v_mfma_f32_16x16x32_bf16 v[124:127], v[160:163], v[196:199], v[124:127]
	v_mfma_f32_16x16x32_bf16 v[120:123], v[168:171], v[196:199], v[120:123]
	v_mfma_f32_16x16x32_bf16 v[116:119], v[160:163], v[204:207], v[116:119]
	v_mfma_f32_16x16x32_bf16 v[112:115], v[168:171], v[204:207], v[112:115]
	v_mfma_f32_16x16x32_bf16 v[100:103], v[160:163], v[212:215], v[100:103]
	v_mfma_f32_16x16x32_bf16 v[96:99], v[168:171], v[212:215], v[96:99]
	v_mfma_f32_16x16x32_bf16 v[84:87], v[160:163], v[220:223], v[84:87]
	v_mfma_f32_16x16x32_bf16 v[80:83], v[168:171], v[220:223], v[80:83]
	v_mfma_f32_16x16x32_bf16 v[124:127], v[164:167], v[200:203], v[124:127]
	v_mfma_f32_16x16x32_bf16 v[120:123], v[172:175], v[200:203], v[120:123]
	v_mfma_f32_16x16x32_bf16 v[116:119], v[164:167], v[208:211], v[116:119]
	v_mfma_f32_16x16x32_bf16 v[112:115], v[172:175], v[208:211], v[112:115]
	v_mfma_f32_16x16x32_bf16 v[100:103], v[164:167], v[216:219], v[100:103]
	v_mfma_f32_16x16x32_bf16 v[96:99], v[172:175], v[216:219], v[96:99]
	v_mfma_f32_16x16x32_bf16 v[84:87], v[164:167], v[224:227], v[84:87]
	v_mfma_f32_16x16x32_bf16 v[80:83], v[172:175], v[224:227], v[80:83]
	s_setprio 0
	s_setprio 1
	v_mfma_f32_16x16x32_bf16 v[108:111], v[180:183], v[196:199], v[108:111]
	v_mfma_f32_16x16x32_bf16 v[104:107], v[188:191], v[196:199], v[104:107]
	v_mfma_f32_16x16x32_bf16 v[92:95], v[180:183], v[204:207], v[92:95]
	v_mfma_f32_16x16x32_bf16 v[88:91], v[188:191], v[204:207], v[88:91]
	v_mfma_f32_16x16x32_bf16 v[76:79], v[180:183], v[212:215], v[76:79]
	v_mfma_f32_16x16x32_bf16 v[72:75], v[188:191], v[212:215], v[72:75]
	v_mfma_f32_16x16x32_bf16 v[68:71], v[180:183], v[220:223], v[68:71]
	v_mfma_f32_16x16x32_bf16 v[64:67], v[188:191], v[220:223], v[64:67]
	v_mfma_f32_16x16x32_bf16 v[108:111], v[184:187], v[200:203], v[108:111]
	v_mfma_f32_16x16x32_bf16 v[104:107], v[192:195], v[200:203], v[104:107]
	v_mfma_f32_16x16x32_bf16 v[92:95], v[184:187], v[208:211], v[92:95]
	v_mfma_f32_16x16x32_bf16 v[88:91], v[192:195], v[208:211], v[88:91]
	v_mfma_f32_16x16x32_bf16 v[76:79], v[184:187], v[216:219], v[76:79]
	v_mfma_f32_16x16x32_bf16 v[72:75], v[192:195], v[216:219], v[72:75]
	v_mfma_f32_16x16x32_bf16 v[68:71], v[184:187], v[224:227], v[68:71]
	v_mfma_f32_16x16x32_bf16 v[64:67], v[192:195], v[224:227], v[64:67]
	s_setprio 0
	s_barrier
; #define PG8_STAGE(bufoff, gbase, voff) do { _Pragma("unroll") for (int _i = 0; _i < 2; ++_i) \
;         __builtin_amdgcn_global_load_lds((const unsigned*)((const char*)(gbase) + (voff)[_i]), (LAS unsigned*)(lds + (bufoff) + ldsw + _i * 8192), 16, 0, 0); } while (0)
; #define PG8_LDA(dst, b, h) do { _Pragma("unroll") for (int m = 0; m < 4; ++m) _Pragma("unroll") for (int k = 0; k < 2; ++k) dst[m][k] = *(const LAS bf16x8*)(lds + PG8_SA(b, h) + aoff + m * 2048 + k * 1024); } while (0)
; #define PG8_MMA(ai, bj, At, Bt) do { __builtin_amdgcn_s_setprio(1); _Pragma("unroll") for (int m = 0; m < 4; ++m) _Pragma("unroll") for (int n = 0; n < 2; ++n) _Pragma("unroll") for (int k = 0; k < 2; ++k) \
;         acc[ai][bj][m][n] = __builtin_amdgcn_mfma_f32_16x16x32_bf16(Bt[n][k], At[m][k], acc[ai][bj][m][n], 0, 0, 0); __builtin_amdgcn_s_setprio(0); } while (0)
; #define PG8_WAIT_V(n) asm volatile("s_waitcnt vmcnt(" #n ")" ::: "memory")
; #define PG8_WAIT_L(n) asm volatile("s_waitcnt lgkmcnt(" #n ")" ::: "memory")
; #define PG8_BAR __builtin_amdgcn_s_barrier()
; #define PG8_SCHED __builtin_amdgcn_sched_barrier(0)
; template <class Epi, class Sched, bool ALIGN_EPI>
; __device__ __forceinline__ void gemm_phase(LAS unsigned char* lds, const int wid, const int lda_, const int ldb_, const int K_, const Sched& S, const Epi& E) {
;     ...
;             PG8_LDA(At, 1, 1); PG8_STAGE(PG8_SB(1, 0), b3, voffB); PG8_STAGE(PG8_SB(1, 1), b3 + hstepB, voffB); PG8_STAGE(PG8_SA(1, 0), a3, voffA);
;             PG8_WAIT_V(8); PG8_WAIT_L(0); PG8_BAR; PG8_MMA(1, 0, At, B0); PG8_MMA(1, 1, At, B1); PG8_BAR; PG8_SCHED;
;         }
;         if constexpr (ALIGN_EPI) { if (wr == 0) PG8_BAR; }
;         E(acc, cur, S, wr, wc, fr, fq);
;         if (!has_next) break;
;     __device__ __forceinline__ void out(const pg8::Unit& u, char*& o, int& ldo, int& kind) const {
;         if (u.pn < 24) { o = (char*)ws + WS_XBCP + ((size_t)u.pm * 256 * XBC + (size_t)u.pn * 256) * 2; ldo = XBC; kind = 0; }
;         else if (u.pn < 40) { o = (char*)ws + WS_Z + ((size_t)u.pm * 256 * DI + (size_t)(u.pn - 24) * 256) * 2; ldo = DI; kind = 0; }
;         else { o = (char*)ws + WS_DT + (size_t)u.pm * 256 * 128 * 4; ldo = 128; kind = 1; } }
	s_add_i32 s17, s17, s3
	v_lshl_add_u64 v[228:229], v[228:229], 0, s[24:25]
	s_mov_b32 m0, s17
	ds_read_b128 v[196:199], v139 offset:49152
	ds_read_b128 v[200:203], v139 offset:50176
	ds_read_b128 v[204:207], v139 offset:51200
	ds_read_b128 v[208:211], v139 offset:52224
	ds_read_b128 v[212:215], v139 offset:53248
	ds_read_b128 v[216:219], v139 offset:54272
	ds_read_b128 v[220:223], v139 offset:55296
	ds_read_b128 v[224:227], v139 offset:56320
	global_load_lds_dwordx4 v[228:229], off
	v_lshl_add_u64 v[228:229], v[230:231], 0, s[24:25]
	s_add_i32 m0, s17, 0x2000
	s_add_i32 s17, s27, s3
	global_load_lds_dwordx4 v[228:229], off
	v_lshl_add_u64 v[228:229], v[232:233], 0, s[24:25]
	s_mov_b32 m0, s17
	s_nop 0
	global_load_lds_dwordx4 v[228:229], off
	v_lshl_add_u64 v[228:229], v[234:235], 0, s[24:25]
	s_add_i32 m0, s17, 0x2000
	s_nop 0
	global_load_lds_dwordx4 v[228:229], off
	v_lshl_add_u64 v[228:229], v[236:237], 0, s[24:25]
	s_mov_b32 m0, s73
	s_nop 0
	global_load_lds_dwordx4 v[228:229], off
	v_lshl_add_u64 v[228:229], v[246:247], 0, s[24:25]
	s_mov_b32 m0, s74
	s_nop 0
	global_load_lds_dwordx4 v[228:229], off
	s_waitcnt vmcnt(8)
	s_waitcnt lgkmcnt(0)
	s_barrier
	s_setprio 1
	s_waitcnt lgkmcnt(0)
	v_mfma_f32_16x16x32_bf16 v[60:63], v[160:163], v[196:199], v[60:63]
	v_mfma_f32_16x16x32_bf16 v[56:59], v[168:171], v[196:199], v[56:59]
	v_mfma_f32_16x16x32_bf16 v[52:55], v[160:163], v[204:207], v[52:55]
	v_mfma_f32_16x16x32_bf16 v[48:51], v[168:171], v[204:207], v[48:51]
	v_mfma_f32_16x16x32_bf16 v[36:39], v[160:163], v[212:215], v[36:39]
	v_mfma_f32_16x16x32_bf16 v[32:35], v[168:171], v[212:215], v[32:35]
	v_mfma_f32_16x16x32_bf16 v[20:23], v[160:163], v[220:223], v[20:23]
	v_mfma_f32_16x16x32_bf16 v[16:19], v[168:171], v[220:223], v[16:19]
	v_mfma_f32_16x16x32_bf16 v[60:63], v[164:167], v[200:203], v[60:63]
	v_mfma_f32_16x16x32_bf16 v[56:59], v[172:175], v[200:203], v[56:59]
	v_mfma_f32_16x16x32_bf16 v[52:55], v[164:167], v[208:211], v[52:55]
	v_mfma_f32_16x16x32_bf16 v[48:51], v[172:175], v[208:211], v[48:51]
	v_mfma_f32_16x16x32_bf16 v[36:39], v[164:167], v[216:219], v[36:39]
	v_mfma_f32_16x16x32_bf16 v[32:35], v[172:175], v[216:219], v[32:35]
	v_mfma_f32_16x16x32_bf16 v[20:23], v[164:167], v[224:227], v[20:23]
	v_mfma_f32_16x16x32_bf16 v[16:19], v[172:175], v[224:227], v[16:19]
	s_setprio 0
	s_setprio 1
	v_mfma_f32_16x16x32_bf16 v[44:47], v[180:183], v[196:199], v[44:47]
	v_mfma_f32_16x16x32_bf16 v[40:43], v[188:191], v[196:199], v[40:43]
	v_mfma_f32_16x16x32_bf16 v[28:31], v[180:183], v[204:207], v[28:31]
	v_mfma_f32_16x16x32_bf16 v[24:27], v[188:191], v[204:207], v[24:27]
	v_mfma_f32_16x16x32_bf16 v[12:15], v[180:183], v[212:215], v[12:15]
	v_mfma_f32_16x16x32_bf16 v[8:11], v[188:191], v[212:215], v[8:11]
	v_mfma_f32_16x16x32_bf16 v[4:7], v[180:183], v[220:223], v[4:7]
	v_mfma_f32_16x16x32_bf16 v[0:3], v[188:191], v[220:223], v[0:3]
	v_mfma_f32_16x16x32_bf16 v[44:47], v[184:187], v[200:203], v[44:47]
	v_mfma_f32_16x16x32_bf16 v[40:43], v[192:195], v[200:203], v[40:43]
	v_mfma_f32_16x16x32_bf16 v[28:31], v[184:187], v[208:211], v[28:31]
	v_mfma_f32_16x16x32_bf16 v[24:27], v[192:195], v[208:211], v[24:27]
	v_mfma_f32_16x16x32_bf16 v[12:15], v[184:187], v[216:219], v[12:15]
	v_mfma_f32_16x16x32_bf16 v[8:11], v[192:195], v[216:219], v[8:11]
	v_mfma_f32_16x16x32_bf16 v[4:7], v[184:187], v[224:227], v[4:7]
	v_mfma_f32_16x16x32_bf16 v[0:3], v[192:195], v[224:227], v[0:3]
	s_setprio 0
	s_barrier
	s_add_i32 s76, s76, 2
	s_add_u32 s48, s48, 0x100
	s_addc_u32 s49, s49, 0
	s_cmp_gt_u32 s76, 29
	s_cbranch_scc0 .LBB0_299
	s_ashr_i32 s45, s44, 31
	s_cmp_gt_i32 s30, 23
	s_mov_b64 s[48:49], -1
	s_cbranch_scc0 .LBB0_305
	s_cmp_gt_u32 s30, 39
	s_mov_b64 s[4:5], -1
	s_cbranch_scc0 .LBB0_303
	s_lshl_b64 s[4:5], s[44:45], 17
	v_readlane_b32 s46, v252, 60
	v_readlane_b32 s47, v252, 61
	s_add_u32 s46, s46, s4
	s_addc_u32 s47, s47, s5
	s_mov_b64 s[4:5], 0

; #define PG8_STAGE(bufoff, gbase, voff) do { _Pragma("unroll") for (int _i = 0; _i < 2; ++_i) \
;         __builtin_amdgcn_global_load_lds((const unsigned*)((const char*)(gbase) + (voff)[_i]), (LAS unsigned*)(lds + (bufoff) + ldsw + _i * 8192), 16, 0, 0); } while (0)
; #define PG8_LDA(dst, b, h) do { _Pragma("unroll") for (int m = 0; m < 4; ++m) _Pragma("unroll") for (int k = 0; k < 2; ++k) dst[m][k] = *(const LAS bf16x8*)(lds + PG8_SA(b, h) + aoff + m * 2048 + k * 1024); } while (0)
; #define PG8_LDB(dst, b, h) do { _Pragma("unroll") for (int n = 0; n < 2; ++n) _Pragma("unroll") for (int k = 0; k < 2; ++k) dst[n][k] = *(const LAS bf16x8*)(lds + PG8_SB(b, h) + boff + n * 2048 + k * 1024); } while (0)
; #define PG8_MMA(ai, bj, At, Bt) do { __builtin_amdgcn_s_setprio(1); _Pragma("unroll") for (int m = 0; m < 4; ++m) _Pragma("unroll") for (int n = 0; n < 2; ++n) _Pragma("unroll") for (int k = 0; k < 2; ++k) \
;         acc[ai][bj][m][n] = __builtin_amdgcn_mfma_f32_16x16x32_bf16(Bt[n][k], At[m][k], acc[ai][bj][m][n], 0, 0, 0); __builtin_amdgcn_s_setprio(0); } while (0)
; #define PG8_WAIT_V(n) asm volatile("s_waitcnt vmcnt(" #n ")" ::: "memory")
; #define PG8_WAIT_L(n) asm volatile("s_waitcnt lgkmcnt(" #n ")" ::: "memory")
; #define PG8_BAR __builtin_amdgcn_s_barrier()
; #define PG8_SCHED __builtin_amdgcn_sched_barrier(0)
; template <class Epi, class Sched, bool ALIGN_EPI>
; __device__ __forceinline__ void gemm_phase(LAS unsigned char* lds, const int wid, const int lda_, const int ldb_, const int K_, const Sched& S, const Epi& E) {
;     ...
;         const bool has_next = S.next(ui + 1, nxt);
;         const int nt = S.nt(cur);
;         const char* nA = has_next ? S.a(nxt) : cA; const char* nB = has_next ? S.b(nxt) : cB;
; #pragma unroll 1
;         for (int t = 0; t < nt; t += 2) {
;             const bool last = (t == nt - 2);
;             const char* a1 = cA + (size_t)(t + 1) * kstep;
;             const char* a2 = last ? nA : cA + (size_t)(t + 2) * kstep; const char* b2 = last ? nB : cB + (size_t)(t + 2) * kstep;
;             const char* a3 = a2 + kstep; const char* b3 = b2 + kstep;
;             PG8_LDB(B0, 0, 0); PG8_LDB(B1, 0, 1); PG8_SCHED; PG8_LDA(At, 0, 0); PG8_STAGE(PG8_SA(1, 1), a1 + hstepA, voffA);
;             PG8_WAIT_V(8); PG8_WAIT_L(0); PG8_BAR; PG8_MMA(0, 0, At, B0); PG8_MMA(0, 1, At, B1); PG8_BAR; PG8_SCHED;
.LBB0_670:
	s_xor_b64 s[44:45], s[4:5], -1
	s_cmp_gt_i32 s38, -1
	s_cselect_b64 s[50:51], -1, 0
	s_cmp_lt_i32 s38, 0
	s_cselect_b32 s35, 64, 16
	s_max_i32 s17, s75, 0
	s_ashr_i32 s43, s42, 31
	s_lshl_b32 s17, s17, 11
	s_lshl_b64 s[46:47], s[42:43], 21
	v_readlane_b32 s48, v252, 62
	v_readlane_b32 s49, v252, 63
	s_add_u32 s27, s48, s46
	s_addc_u32 s37, s49, s47
	s_add_u32 s46, s27, s17
	s_addc_u32 s47, s37, 0
	s_and_b64 s[48:49], s[4:5], exec
	s_cselect_b32 s37, s47, s95
	s_cselect_b32 s39, s46, s94
	s_ashr_i32 s41, s40, 31
	s_lshl_b64 s[48:49], s[40:41], 21
	s_add_u32 s27, s6, s48
	s_addc_u32 s41, s7, s49
	s_add_u32 s48, s27, s17
	s_addc_u32 s49, s41, 0
	s_and_b64 s[4:5], s[4:5], exec
	s_cselect_b32 s4, s49, s97
	s_cselect_b32 s5, s48, s96
	s_add_i32 s41, s35, -2
	s_add_u32 s94, s94, 0x80
	s_addc_u32 s95, s95, 0
	s_add_u32 s43, s96, 0x100
	s_mov_b32 s77, 0
	s_addc_u32 s76, s97, 0
	s_add_i32 s78, s77, 2
	s_add_u32 s17, s94, 0x80
	s_addc_u32 s27, s95, 0
	s_add_i32 s79, 0, 0x10000
	s_cmp_eq_u32 s41, s77
	s_cselect_b32 s97, s37, s27
	s_cselect_b32 s96, s39, s17
	v_add_u32_e32 v141, s79, v135
	s_cselect_b32 s81, s4, s76
	s_cselect_b32 s80, s5, s43
	s_add_i32 s17, 0, 0x14000
	ds_read_b128 v[156:159], v141
	ds_read_b128 v[160:163], v141 offset:1024
	ds_read_b128 v[164:167], v141 offset:2048
	ds_read_b128 v[168:171], v141 offset:3072
	v_add_u32_e32 v141, s17, v135
	ds_read_b128 v[172:175], v141
	ds_read_b128 v[180:183], v141 offset:1024
	ds_read_b128 v[184:187], v141 offset:2048
	ds_read_b128 v[188:191], v141 offset:3072
	v_lshl_add_u64 v[224:225], s[94:95], 0, v[152:153]
	s_add_i32 m0, s16, 0xc000
	ds_read_b128 v[192:195], v139
	ds_read_b128 v[196:199], v139 offset:1024
	ds_read_b128 v[200:203], v139 offset:2048
	ds_read_b128 v[204:207], v139 offset:3072
	ds_read_b128 v[208:211], v139 offset:4096
	ds_read_b128 v[212:215], v139 offset:5120
	ds_read_b128 v[216:219], v139 offset:6144
	ds_read_b128 v[220:223], v139 offset:7168
	global_load_lds_dwordx4 v[224:225], off
	v_lshl_add_u64 v[224:225], s[94:95], 0, v[154:155]
	s_add_i32 m0, s16, 0xe000
	s_nop 0
	global_load_lds_dwordx4 v[224:225], off
	s_waitcnt vmcnt(8)
	s_waitcnt lgkmcnt(0)
	s_barrier
	s_setprio 1
	s_waitcnt lgkmcnt(0)
	v_mfma_f32_16x16x32_bf16 v[124:127], v[156:159], v[192:195], 0
	v_mfma_f32_16x16x32_bf16 v[120:123], v[164:167], v[192:195], 0
	v_mfma_f32_16x16x32_bf16 v[116:119], v[156:159], v[200:203], 0
	v_mfma_f32_16x16x32_bf16 v[112:115], v[164:167], v[200:203], 0
	v_mfma_f32_16x16x32_bf16 v[100:103], v[156:159], v[208:211], 0
	v_mfma_f32_16x16x32_bf16 v[96:99], v[164:167], v[208:211], 0
	v_mfma_f32_16x16x32_bf16 v[84:87], v[156:159], v[216:219], 0
	v_mfma_f32_16x16x32_bf16 v[80:83], v[164:167], v[216:219], 0
	v_mfma_f32_16x16x32_bf16 v[124:127], v[160:163], v[196:199], v[124:127]
	v_mfma_f32_16x16x32_bf16 v[120:123], v[168:171], v[196:199], v[120:123]
	v_mfma_f32_16x16x32_bf16 v[116:119], v[160:163], v[204:207], v[116:119]
	v_mfma_f32_16x16x32_bf16 v[112:115], v[168:171], v[204:207], v[112:115]
	v_mfma_f32_16x16x32_bf16 v[100:103], v[160:163], v[212:215], v[100:103]
	v_mfma_f32_16x16x32_bf16 v[96:99], v[168:171], v[212:215], v[96:99]
	v_mfma_f32_16x16x32_bf16 v[84:87], v[160:163], v[220:223], v[84:87]
	v_mfma_f32_16x16x32_bf16 v[80:83], v[168:171], v[220:223], v[80:83]
	s_setprio 0
	s_setprio 1
	v_mfma_f32_16x16x32_bf16 v[108:111], v[172:175], v[192:195], 0
	v_mfma_f32_16x16x32_bf16 v[104:107], v[184:187], v[192:195], 0
	v_mfma_f32_16x16x32_bf16 v[92:95], v[172:175], v[200:203], 0
	v_mfma_f32_16x16x32_bf16 v[88:91], v[184:187], v[200:203], 0
	v_mfma_f32_16x16x32_bf16 v[76:79], v[172:175], v[208:211], 0
	v_mfma_f32_16x16x32_bf16 v[72:75], v[184:187], v[208:211], 0
	v_mfma_f32_16x16x32_bf16 v[68:71], v[172:175], v[216:219], 0
	v_mfma_f32_16x16x32_bf16 v[64:67], v[184:187], v[216:219], 0
	v_mfma_f32_16x16x32_bf16 v[108:111], v[180:183], v[196:199], v[108:111]
	v_mfma_f32_16x16x32_bf16 v[104:107], v[188:191], v[196:199], v[104:107]
	v_mfma_f32_16x16x32_bf16 v[92:95], v[180:183], v[204:207], v[92:95]
	v_mfma_f32_16x16x32_bf16 v[88:91], v[188:191], v[204:207], v[88:91]
	v_mfma_f32_16x16x32_bf16 v[76:79], v[180:183], v[212:215], v[76:79]
	v_mfma_f32_16x16x32_bf16 v[72:75], v[188:191], v[212:215], v[72:75]
	v_mfma_f32_16x16x32_bf16 v[68:71], v[180:183], v[220:223], v[68:71]
	v_mfma_f32_16x16x32_bf16 v[64:67], v[188:191], v[220:223], v[64:67]
	s_setprio 0
	s_barrier
; #define PG8_STAGE(bufoff, gbase, voff) do { _Pragma("unroll") for (int _i = 0; _i < 2; ++_i) \
;         __builtin_amdgcn_global_load_lds((const unsigned*)((const char*)(gbase) + (voff)[_i]), (LAS unsigned*)(lds + (bufoff) + ldsw + _i * 8192), 16, 0, 0); } while (0)
; #define PG8_LDA(dst, b, h) do { _Pragma("unroll") for (int m = 0; m < 4; ++m) _Pragma("unroll") for (int k = 0; k < 2; ++k) dst[m][k] = *(const LAS bf16x8*)(lds + PG8_SA(b, h) + aoff + m * 2048 + k * 1024); } while (0)
; #define PG8_MMA(ai, bj, At, Bt) do { __builtin_amdgcn_s_setprio(1); _Pragma("unroll") for (int m = 0; m < 4; ++m) _Pragma("unroll") for (int n = 0; n < 2; ++n) _Pragma("unroll") for (int k = 0; k < 2; ++k) \
;         acc[ai][bj][m][n] = __builtin_amdgcn_mfma_f32_16x16x32_bf16(Bt[n][k], At[m][k], acc[ai][bj][m][n], 0, 0, 0); __builtin_amdgcn_s_setprio(0); } while (0)
; #define PG8_WAIT_V(n) asm volatile("s_waitcnt vmcnt(" #n ")" ::: "memory")
; #define PG8_WAIT_L(n) asm volatile("s_waitcnt lgkmcnt(" #n ")" ::: "memory")
; #define PG8_BAR __builtin_amdgcn_s_barrier()
; #define PG8_SCHED __builtin_amdgcn_sched_barrier(0)
; template <class Epi, class Sched, bool ALIGN_EPI>
; __device__ __forceinline__ void gemm_phase(LAS unsigned char* lds, const int wid, const int lda_, const int ldb_, const int K_, const Sched& S, const Epi& E) {
;     ...
;             PG8_LDA(At, 0, 1); PG8_STAGE(PG8_SB(0, 0), b2, voffB); PG8_STAGE(PG8_SB(0, 1), b2 + hstepB, voffB); PG8_STAGE(PG8_SA(0, 0), a2, voffA);
;             PG8_WAIT_V(8); PG8_WAIT_L(0); PG8_BAR; PG8_MMA(1, 0, At, B0); PG8_MMA(1, 1, At, B1); PG8_BAR; PG8_SCHED;
	s_add_i32 s27, s79, s3
	v_lshl_add_u64 v[224:225], s[80:81], 0, v[176:177]
	s_mov_b32 m0, s27
	ds_read_b128 v[192:195], v139 offset:16384
	ds_read_b128 v[196:199], v139 offset:17408
	ds_read_b128 v[200:203], v139 offset:18432
	ds_read_b128 v[204:207], v139 offset:19456
	ds_read_b128 v[208:211], v139 offset:20480
	ds_read_b128 v[212:215], v139 offset:21504
	ds_read_b128 v[216:219], v139 offset:22528
	ds_read_b128 v[220:223], v139 offset:23552
	global_load_lds_dwordx4 v[224:225], off
	s_add_i32 m0, s27, 0x2000
	v_lshl_add_u64 v[226:227], s[80:81], 0, v[132:133]
	s_add_u32 s80, s80, s30
	s_addc_u32 s81, s81, s31
	s_add_i32 s17, s17, s3
	global_load_lds_dwordx4 v[226:227], off
	v_lshl_add_u64 v[228:229], s[80:81], 0, v[176:177]
	s_mov_b32 m0, s17
	v_lshl_add_u64 v[230:231], s[80:81], 0, v[132:133]
	global_load_lds_dwordx4 v[228:229], off
	s_add_i32 m0, s17, 0x2000
	v_lshl_add_u64 v[232:233], s[96:97], 0, v[128:129]
	global_load_lds_dwordx4 v[230:231], off
	s_mov_b32 m0, s16
	v_lshl_add_u64 v[234:235], s[96:97], 0, v[130:131]
	global_load_lds_dwordx4 v[232:233], off
	s_mov_b32 m0, s14
	s_nop 0
	global_load_lds_dwordx4 v[234:235], off
	s_waitcnt vmcnt(8)
	s_waitcnt lgkmcnt(0)
	s_barrier
	s_setprio 1
	s_waitcnt lgkmcnt(0)
	v_mfma_f32_16x16x32_bf16 v[60:63], v[156:159], v[192:195], 0
	v_mfma_f32_16x16x32_bf16 v[56:59], v[164:167], v[192:195], 0
	v_mfma_f32_16x16x32_bf16 v[52:55], v[156:159], v[200:203], 0
	v_mfma_f32_16x16x32_bf16 v[48:51], v[164:167], v[200:203], 0
	v_mfma_f32_16x16x32_bf16 v[36:39], v[156:159], v[208:211], 0
	v_mfma_f32_16x16x32_bf16 v[32:35], v[164:167], v[208:211], 0
	v_mfma_f32_16x16x32_bf16 v[20:23], v[156:159], v[216:219], 0
	v_mfma_f32_16x16x32_bf16 v[16:19], v[164:167], v[216:219], 0
	v_mfma_f32_16x16x32_bf16 v[60:63], v[160:163], v[196:199], v[60:63]
	v_mfma_f32_16x16x32_bf16 v[56:59], v[168:171], v[196:199], v[56:59]
	v_mfma_f32_16x16x32_bf16 v[52:55], v[160:163], v[204:207], v[52:55]
	v_mfma_f32_16x16x32_bf16 v[48:51], v[168:171], v[204:207], v[48:51]
	v_mfma_f32_16x16x32_bf16 v[36:39], v[160:163], v[212:215], v[36:39]
	v_mfma_f32_16x16x32_bf16 v[32:35], v[168:171], v[212:215], v[32:35]
	v_mfma_f32_16x16x32_bf16 v[20:23], v[160:163], v[220:223], v[20:23]
	v_mfma_f32_16x16x32_bf16 v[16:19], v[168:171], v[220:223], v[16:19]
	s_setprio 0
	s_setprio 1
	v_mfma_f32_16x16x32_bf16 v[44:47], v[172:175], v[192:195], 0
	v_mfma_f32_16x16x32_bf16 v[40:43], v[184:187], v[192:195], 0
	v_mfma_f32_16x16x32_bf16 v[28:31], v[172:175], v[200:203], 0
	v_mfma_f32_16x16x32_bf16 v[24:27], v[184:187], v[200:203], 0
	v_mfma_f32_16x16x32_bf16 v[12:15], v[172:175], v[208:211], 0
	v_mfma_f32_16x16x32_bf16 v[8:11], v[184:187], v[208:211], 0
	v_mfma_f32_16x16x32_bf16 v[4:7], v[172:175], v[216:219], 0
	v_mfma_f32_16x16x32_bf16 v[0:3], v[184:187], v[216:219], 0
	v_mfma_f32_16x16x32_bf16 v[44:47], v[180:183], v[196:199], v[44:47]
	v_mfma_f32_16x16x32_bf16 v[40:43], v[188:191], v[196:199], v[40:43]
	v_mfma_f32_16x16x32_bf16 v[28:31], v[180:183], v[204:207], v[28:31]
	v_mfma_f32_16x16x32_bf16 v[24:27], v[188:191], v[204:207], v[24:27]
	v_mfma_f32_16x16x32_bf16 v[12:15], v[180:183], v[212:215], v[12:15]
	v_mfma_f32_16x16x32_bf16 v[8:11], v[188:191], v[212:215], v[8:11]
	v_mfma_f32_16x16x32_bf16 v[4:7], v[180:183], v[220:223], v[4:7]
	v_mfma_f32_16x16x32_bf16 v[0:3], v[188:191], v[220:223], v[0:3]
	s_setprio 0
	s_barrier
	s_branch .Lgemm_join_671

; #define PG8_STAGE(bufoff, gbase, voff) do { _Pragma("unroll") for (int _i = 0; _i < 2; ++_i) \
;         __builtin_amdgcn_global_load_lds((const unsigned*)((const char*)(gbase) + (voff)[_i]), (LAS unsigned*)(lds + (bufoff) + ldsw + _i * 8192), 16, 0, 0); } while (0)
; #define PG8_LDA(dst, b, h) do { _Pragma("unroll") for (int m = 0; m < 4; ++m) _Pragma("unroll") for (int k = 0; k < 2; ++k) dst[m][k] = *(const LAS bf16x8*)(lds + PG8_SA(b, h) + aoff + m * 2048 + k * 1024); } while (0)
; #define PG8_LDB(dst, b, h) do { _Pragma("unroll") for (int n = 0; n < 2; ++n) _Pragma("unroll") for (int k = 0; k < 2; ++k) dst[n][k] = *(const LAS bf16x8*)(lds + PG8_SB(b, h) + boff + n * 2048 + k * 1024); } while (0)
; #define PG8_MMA(ai, bj, At, Bt) do { __builtin_amdgcn_s_setprio(1); _Pragma("unroll") for (int m = 0; m < 4; ++m) _Pragma("unroll") for (int n = 0; n < 2; ++n) _Pragma("unroll") for (int k = 0; k < 2; ++k) \
;         acc[ai][bj][m][n] = __builtin_amdgcn_mfma_f32_16x16x32_bf16(Bt[n][k], At[m][k], acc[ai][bj][m][n], 0, 0, 0); __builtin_amdgcn_s_setprio(0); } while (0)
; #define PG8_WAIT_V(n) asm volatile("s_waitcnt vmcnt(" #n ")" ::: "memory")
; #define PG8_WAIT_L(n) asm volatile("s_waitcnt lgkmcnt(" #n ")" ::: "memory")
; #define PG8_BAR __builtin_amdgcn_s_barrier()
; #define PG8_SCHED __builtin_amdgcn_sched_barrier(0)
; template <class Epi, class Sched, bool ALIGN_EPI>
; __device__ __forceinline__ void gemm_phase(LAS unsigned char* lds, const int wid, const int lda_, const int ldb_, const int K_, const Sched& S, const Epi& E) {
;     ...
;             PG8_LDB(B0, 1, 0); PG8_LDB(B1, 1, 1); PG8_SCHED; PG8_LDA(At, 1, 0); PG8_STAGE(PG8_SA(0, 1), a2 + hstepA, voffA);
;             PG8_WAIT_V(8); PG8_WAIT_L(0); PG8_BAR; PG8_MMA(0, 0, At, B0); PG8_MMA(0, 1, At, B1); PG8_BAR; PG8_SCHED;
.Lgemm_join_671:
	s_add_i32 s17, 0, 0x18000
	v_add_u32_e32 v141, s17, v135
	s_add_i32 s27, 0, 0x1c000
	ds_read_b128 v[156:159], v141
	ds_read_b128 v[160:163], v141 offset:1024
	ds_read_b128 v[164:167], v141 offset:2048
	ds_read_b128 v[168:171], v141 offset:3072
	v_add_u32_e32 v141, s27, v135
	ds_read_b128 v[172:175], v141
	ds_read_b128 v[180:183], v141 offset:1024
	ds_read_b128 v[184:187], v141 offset:2048
	ds_read_b128 v[188:191], v141 offset:3072
	s_add_u32 s80, s96, s10
	s_addc_u32 s81, s97, s11
	s_mov_b32 m0, s15
	v_lshl_add_u64 v[236:237], s[80:81], 0, v[128:129]
	ds_read_b128 v[192:195], v139 offset:32768
	ds_read_b128 v[196:199], v139 offset:33792
	ds_read_b128 v[200:203], v139 offset:34816
	ds_read_b128 v[204:207], v139 offset:35840
	ds_read_b128 v[208:211], v139 offset:36864
	ds_read_b128 v[212:215], v139 offset:37888
	ds_read_b128 v[216:219], v139 offset:38912
	ds_read_b128 v[220:223], v139 offset:39936
	global_load_lds_dwordx4 v[236:237], off
	v_lshl_add_u64 v[236:237], s[80:81], 0, v[130:131]
	s_mov_b32 m0, s26
	s_nop 0
	global_load_lds_dwordx4 v[236:237], off
	s_waitcnt vmcnt(8)
	s_waitcnt lgkmcnt(0)
	s_barrier
	s_setprio 1
	s_waitcnt lgkmcnt(0)
	v_mfma_f32_16x16x32_bf16 v[124:127], v[156:159], v[192:195], v[124:127]
	v_mfma_f32_16x16x32_bf16 v[120:123], v[164:167], v[192:195], v[120:123]
	v_mfma_f32_16x16x32_bf16 v[116:119], v[156:159], v[200:203], v[116:119]
	v_mfma_f32_16x16x32_bf16 v[112:115], v[164:167], v[200:203], v[112:115]
	v_mfma_f32_16x16x32_bf16 v[100:103], v[156:159], v[208:211], v[100:103]
	v_mfma_f32_16x16x32_bf16 v[96:99], v[164:167], v[208:211], v[96:99]
	v_mfma_f32_16x16x32_bf16 v[84:87], v[156:159], v[216:219], v[84:87]
	v_mfma_f32_16x16x32_bf16 v[80:83], v[164:167], v[216:219], v[80:83]
	v_mfma_f32_16x16x32_bf16 v[124:127], v[160:163], v[196:199], v[124:127]
	v_mfma_f32_16x16x32_bf16 v[120:123], v[168:171], v[196:199], v[120:123]
	v_mfma_f32_16x16x32_bf16 v[116:119], v[160:163], v[204:207], v[116:119]
	v_mfma_f32_16x16x32_bf16 v[112:115], v[168:171], v[204:207], v[112:115]
	v_mfma_f32_16x16x32_bf16 v[100:103], v[160:163], v[212:215], v[100:103]
	v_mfma_f32_16x16x32_bf16 v[96:99], v[168:171], v[212:215], v[96:99]
	v_mfma_f32_16x16x32_bf16 v[84:87], v[160:163], v[220:223], v[84:87]
	v_mfma_f32_16x16x32_bf16 v[80:83], v[168:171], v[220:223], v[80:83]
	s_setprio 0
	s_setprio 1
	v_mfma_f32_16x16x32_bf16 v[108:111], v[172:175], v[192:195], v[108:111]
	v_mfma_f32_16x16x32_bf16 v[104:107], v[184:187], v[192:195], v[104:107]
	v_mfma_f32_16x16x32_bf16 v[92:95], v[172:175], v[200:203], v[92:95]
	v_mfma_f32_16x16x32_bf16 v[88:91], v[184:187], v[200:203], v[88:91]
	v_mfma_f32_16x16x32_bf16 v[76:79], v[172:175], v[208:211], v[76:79]
	v_mfma_f32_16x16x32_bf16 v[72:75], v[184:187], v[208:211], v[72:75]
	v_mfma_f32_16x16x32_bf16 v[68:71], v[172:175], v[216:219], v[68:71]
	v_mfma_f32_16x16x32_bf16 v[64:67], v[184:187], v[216:219], v[64:67]
	v_mfma_f32_16x16x32_bf16 v[108:111], v[180:183], v[196:199], v[108:111]
	v_mfma_f32_16x16x32_bf16 v[104:107], v[188:191], v[196:199], v[104:107]
	v_mfma_f32_16x16x32_bf16 v[92:95], v[180:183], v[204:207], v[92:95]
	v_mfma_f32_16x16x32_bf16 v[88:91], v[188:191], v[204:207], v[88:91]
	v_mfma_f32_16x16x32_bf16 v[76:79], v[180:183], v[212:215], v[76:79]
	v_mfma_f32_16x16x32_bf16 v[72:75], v[188:191], v[212:215], v[72:75]
	v_mfma_f32_16x16x32_bf16 v[68:71], v[180:183], v[220:223], v[68:71]
	v_mfma_f32_16x16x32_bf16 v[64:67], v[188:191], v[220:223], v[64:67]
	s_setprio 0
	s_barrier
; #define PG8_STAGE(bufoff, gbase, voff) do { _Pragma("unroll") for (int _i = 0; _i < 2; ++_i) \
;         __builtin_amdgcn_global_load_lds((const unsigned*)((const char*)(gbase) + (voff)[_i]), (LAS unsigned*)(lds + (bufoff) + ldsw + _i * 8192), 16, 0, 0); } while (0)
; #define PG8_LDA(dst, b, h) do { _Pragma("unroll") for (int m = 0; m < 4; ++m) _Pragma("unroll") for (int k = 0; k < 2; ++k) dst[m][k] = *(const LAS bf16x8*)(lds + PG8_SA(b, h) + aoff + m * 2048 + k * 1024); } while (0)
; #define PG8_MMA(ai, bj, At, Bt) do { __builtin_amdgcn_s_setprio(1); _Pragma("unroll") for (int m = 0; m < 4; ++m) _Pragma("unroll") for (int n = 0; n < 2; ++n) _Pragma("unroll") for (int k = 0; k < 2; ++k) \
;         acc[ai][bj][m][n] = __builtin_amdgcn_mfma_f32_16x16x32_bf16(Bt[n][k], At[m][k], acc[ai][bj][m][n], 0, 0, 0); __builtin_amdgcn_s_setprio(0); } while (0)
; #define PG8_WAIT_V(n) asm volatile("s_waitcnt vmcnt(" #n ")" ::: "memory")
; #define PG8_WAIT_L(n) asm volatile("s_waitcnt lgkmcnt(" #n ")" ::: "memory")
; #define PG8_BAR __builtin_amdgcn_s_barrier()
; #define PG8_SCHED __builtin_amdgcn_sched_barrier(0)
; template <class Epi, class Sched, bool ALIGN_EPI>
; __device__ __forceinline__ void gemm_phase(LAS unsigned char* lds, const int wid, const int lda_, const int ldb_, const int K_, const Sched& S, const Epi& E) {
;     ...
;             PG8_LDA(At, 1, 1); PG8_STAGE(PG8_SB(1, 0), b3, voffB); PG8_STAGE(PG8_SB(1, 1), b3 + hstepB, voffB); PG8_STAGE(PG8_SA(1, 0), a3, voffA);
;             PG8_WAIT_V(8); PG8_WAIT_L(0); PG8_BAR; PG8_MMA(1, 0, At, B0); PG8_MMA(1, 1, At, B1); PG8_BAR; PG8_SCHED;
;         }
;         if constexpr (ALIGN_EPI) { if (wr == 0) PG8_BAR; }
;         E(acc, cur, S, wr, wc, fr, fq);
;         if (!has_next) break;
;     __device__ __forceinline__ void out(const pg8::Unit& u, char*& o, int& ldo, int& kind) const { ldo = D;
;         if (u.kq < 0) { o = (char*)ws + YOFF + ((size_t)u.pm * 256 * D + (size_t)u.pn * 256) * 2; kind = 0; }
;         else { o = (char*)ws + WS_PART + (((size_t)u.kq * MCTX + (size_t)(u.pm - 64) * 256) * D + (size_t)u.pn * 256) * 2; kind = 0; } }
	s_add_i32 s17, s17, s3
	v_lshl_add_u64 v[224:225], v[224:225], 0, s[24:25]
	s_mov_b32 m0, s17
	ds_read_b128 v[192:195], v139 offset:49152
	ds_read_b128 v[196:199], v139 offset:50176
	ds_read_b128 v[200:203], v139 offset:51200
	ds_read_b128 v[204:207], v139 offset:52224
	ds_read_b128 v[208:211], v139 offset:53248
	ds_read_b128 v[212:215], v139 offset:54272
	ds_read_b128 v[216:219], v139 offset:55296
	ds_read_b128 v[220:223], v139 offset:56320
	global_load_lds_dwordx4 v[224:225], off
	v_lshl_add_u64 v[224:225], v[226:227], 0, s[24:25]
	s_add_i32 m0, s17, 0x2000
	s_add_i32 s17, s27, s3
	global_load_lds_dwordx4 v[224:225], off
	v_lshl_add_u64 v[224:225], v[228:229], 0, s[24:25]
	s_mov_b32 m0, s17
	s_nop 0
	global_load_lds_dwordx4 v[224:225], off
	v_lshl_add_u64 v[224:225], v[230:231], 0, s[24:25]
	s_add_i32 m0, s17, 0x2000
	s_nop 0
	global_load_lds_dwordx4 v[224:225], off
	v_lshl_add_u64 v[224:225], v[232:233], 0, s[24:25]
	s_mov_b32 m0, s72
	s_nop 0
	global_load_lds_dwordx4 v[224:225], off
	v_lshl_add_u64 v[224:225], v[234:235], 0, s[24:25]
	s_mov_b32 m0, s73
	s_nop 0
	global_load_lds_dwordx4 v[224:225], off
	s_waitcnt vmcnt(8)
	s_waitcnt lgkmcnt(0)
	s_barrier
	s_setprio 1
	s_waitcnt lgkmcnt(0)
	v_mfma_f32_16x16x32_bf16 v[60:63], v[156:159], v[192:195], v[60:63]
	v_mfma_f32_16x16x32_bf16 v[56:59], v[164:167], v[192:195], v[56:59]
	v_mfma_f32_16x16x32_bf16 v[52:55], v[156:159], v[200:203], v[52:55]
	v_mfma_f32_16x16x32_bf16 v[48:51], v[164:167], v[200:203], v[48:51]
	v_mfma_f32_16x16x32_bf16 v[36:39], v[156:159], v[208:211], v[36:39]
	v_mfma_f32_16x16x32_bf16 v[32:35], v[164:167], v[208:211], v[32:35]
	v_mfma_f32_16x16x32_bf16 v[20:23], v[156:159], v[216:219], v[20:23]
	v_mfma_f32_16x16x32_bf16 v[16:19], v[164:167], v[216:219], v[16:19]
	v_mfma_f32_16x16x32_bf16 v[60:63], v[160:163], v[196:199], v[60:63]
	v_mfma_f32_16x16x32_bf16 v[56:59], v[168:171], v[196:199], v[56:59]
	v_mfma_f32_16x16x32_bf16 v[52:55], v[160:163], v[204:207], v[52:55]
	v_mfma_f32_16x16x32_bf16 v[48:51], v[168:171], v[204:207], v[48:51]
	v_mfma_f32_16x16x32_bf16 v[36:39], v[160:163], v[212:215], v[36:39]
	v_mfma_f32_16x16x32_bf16 v[32:35], v[168:171], v[212:215], v[32:35]
	v_mfma_f32_16x16x32_bf16 v[20:23], v[160:163], v[220:223], v[20:23]
	v_mfma_f32_16x16x32_bf16 v[16:19], v[168:171], v[220:223], v[16:19]
	s_setprio 0
	s_setprio 1
	v_mfma_f32_16x16x32_bf16 v[44:47], v[172:175], v[192:195], v[44:47]
	v_mfma_f32_16x16x32_bf16 v[40:43], v[184:187], v[192:195], v[40:43]
	v_mfma_f32_16x16x32_bf16 v[28:31], v[172:175], v[200:203], v[28:31]
	v_mfma_f32_16x16x32_bf16 v[24:27], v[184:187], v[200:203], v[24:27]
	v_mfma_f32_16x16x32_bf16 v[12:15], v[172:175], v[208:211], v[12:15]
	v_mfma_f32_16x16x32_bf16 v[8:11], v[184:187], v[208:211], v[8:11]
	v_mfma_f32_16x16x32_bf16 v[4:7], v[172:175], v[216:219], v[4:7]
	v_mfma_f32_16x16x32_bf16 v[0:3], v[184:187], v[216:219], v[0:3]
	v_mfma_f32_16x16x32_bf16 v[44:47], v[180:183], v[196:199], v[44:47]
	v_mfma_f32_16x16x32_bf16 v[40:43], v[188:191], v[196:199], v[40:43]
	v_mfma_f32_16x16x32_bf16 v[28:31], v[180:183], v[204:207], v[28:31]
	v_mfma_f32_16x16x32_bf16 v[24:27], v[188:191], v[204:207], v[24:27]
	v_mfma_f32_16x16x32_bf16 v[12:15], v[180:183], v[212:215], v[12:15]
	v_mfma_f32_16x16x32_bf16 v[8:11], v[188:191], v[212:215], v[8:11]
	v_mfma_f32_16x16x32_bf16 v[4:7], v[180:183], v[220:223], v[4:7]
	v_mfma_f32_16x16x32_bf16 v[0:3], v[188:191], v[220:223], v[0:3]
	s_setprio 0
	s_barrier
	s_add_u32 s94, s94, 0x100
	s_addc_u32 s95, s95, 0
	s_add_u32 s43, s43, 0x100
	s_addc_u32 s76, s76, 0
	s_cmp_ge_u32 s78, s35
	s_mov_b32 s77, s78
	s_cbranch_scc0 .LBB0_671
	s_mov_b64 s[94:95], -1
	s_and_b64 vcc, exec, s[50:51]
	s_cbranch_vccz .LBB0_674
	s_mov_b32 s39, s92
	s_ashr_i32 s35, s34, 31
	s_ashr_i32 s37, s36, 31
	s_lshl_b64 s[4:5], s[34:35], 20
	s_lshl_b64 s[50:51], s[36:37], 9
	s_lshl_b64 s[38:39], s[38:39], 23
	v_readlane_b32 s76, v251, 28
	v_readlane_b32 s77, v251, 29
	s_add_u32 s17, s76, s50
	s_addc_u32 s27, s77, s51
	s_add_u32 s17, s17, s38
	s_addc_u32 s27, s27, s39
	s_add_u32 s4, s17, s4
	s_addc_u32 s5, s27, s5
	s_add_u32 s4, s4, 0xfc000000
	s_addc_u32 s5, s5, -1
	s_mov_b64 s[94:95], 0

; #define PG8_STAGE(bufoff, gbase, voff) do { _Pragma("unroll") for (int _i = 0; _i < 2; ++_i) \
;         __builtin_amdgcn_global_load_lds((const unsigned*)((const char*)(gbase) + (voff)[_i]), (LAS unsigned*)(lds + (bufoff) + ldsw + _i * 8192), 16, 0, 0); } while (0)
; #define PG8_LDA(dst, b, h) do { _Pragma("unroll") for (int m = 0; m < 4; ++m) _Pragma("unroll") for (int k = 0; k < 2; ++k) dst[m][k] = *(const LAS bf16x8*)(lds + PG8_SA(b, h) + aoff + m * 2048 + k * 1024); } while (0)
; #define PG8_LDB(dst, b, h) do { _Pragma("unroll") for (int n = 0; n < 2; ++n) _Pragma("unroll") for (int k = 0; k < 2; ++k) dst[n][k] = *(const LAS bf16x8*)(lds + PG8_SB(b, h) + boff + n * 2048 + k * 1024); } while (0)
; #define PG8_WAIT_V(n) asm volatile("s_waitcnt vmcnt(" #n ")" ::: "memory")
; #define PG8_WAIT_L(n) asm volatile("s_waitcnt lgkmcnt(" #n ")" ::: "memory")
; #define PG8_BAR __builtin_amdgcn_s_barrier()
; #define PG8_SCHED __builtin_amdgcn_sched_barrier(0)
; template <class Epi, class Sched, bool ALIGN_EPI>
; __device__ __forceinline__ void gemm_phase(LAS unsigned char* lds, const int wid, const int lda_, const int ldb_, const int K_, const Sched& S, const Epi& E) {
;     ...
;         const bool has_next = S.next(ui + 1, nxt);
;         const int nt = S.nt(cur);
;         const char* nA = has_next ? S.a(nxt) : cA; const char* nB = has_next ? S.b(nxt) : cB;
; #pragma unroll 1
;         for (int t = 0; t < nt; t += 2) {
;             const bool last = (t == nt - 2);
;             const char* a1 = cA + (size_t)(t + 1) * kstep;
;             const char* a2 = last ? nA : cA + (size_t)(t + 2) * kstep; const char* b2 = last ? nB : cB + (size_t)(t + 2) * kstep;
;             const char* a3 = a2 + kstep; const char* b3 = b2 + kstep;
;             PG8_LDB(B0, 0, 0); PG8_LDB(B1, 0, 1); PG8_SCHED; PG8_LDA(At, 0, 0); PG8_STAGE(PG8_SA(1, 1), a1 + hstepA, voffA);
;             PG8_WAIT_V(8); PG8_WAIT_L(0); PG8_BAR; PG8_MMA(0, 0, At, B0); PG8_MMA(0, 1, At, B1); PG8_BAR; PG8_SCHED;
;     __device__ __forceinline__ const char* a(const pg8::Unit& u) const { return (const char*)ws + WS_W1 + (size_t)(u.pm & 1) * 256 * 256 * 2; }
;     __device__ __forceinline__ const char* b(const pg8::Unit& u) const { return (const char*)ws + WS_A + ((size_t)u.pn * 256 * D + (size_t)(u.pm >> 1) * 256) * 2; }
.LBB0_696:
	v_mov_b64_e32 v[0:1], 0x480
	v_cmp_lt_i64_e32 vcc, s[4:5], v[0:1]
	s_lshl_b32 s4, s73, 17
	s_and_b32 s4, s4, 0x20000
	v_readlane_b32 s5, v253, 31
	s_add_u32 s34, s5, s4
	v_readlane_b32 s4, v253, 32
	s_addc_u32 s35, s4, 0
	s_and_b64 s[4:5], vcc, exec
	s_cselect_b32 s4, s35, s45
	s_cselect_b32 s5, s34, s44
	s_ashr_i32 s36, s73, 1
	s_ashr_i32 s31, s30, 31
	s_ashr_i32 s37, s36, 31
	s_lshl_b64 s[36:37], s[36:37], 9
	s_lshl_b64 s[42:43], s[30:31], 20
	v_readlane_b32 s46, v253, 52
	v_readlane_b32 s47, v253, 53
	s_add_u32 s31, s46, s42
	s_addc_u32 s42, s47, s43
	s_add_u32 s36, s31, s36
	s_addc_u32 s37, s42, s37
	s_and_b64 s[42:43], vcc, exec
	s_cselect_b32 s31, s37, s41
	s_cselect_b32 s76, s36, s40
	s_mov_b64 s[50:51], 0
	s_mov_b64 s[46:47], -1
	s_mov_b64 s[48:49], 0
	s_add_u32 s77, s44, s50
	s_addc_u32 s78, s45, s51
	s_add_u32 s79, s77, 0x100
	s_addc_u32 s80, s78, 0
	s_and_b64 s[42:43], s[48:49], exec
	s_cselect_b32 s95, s4, s80
	s_cselect_b32 s94, s5, s79
	s_add_u32 s42, s40, s50
	s_addc_u32 s43, s41, s51
	s_add_u32 s50, s42, 0x100
	s_addc_u32 s51, s43, 0
	s_add_i32 s93, 0, 0x10000
	s_and_b64 s[42:43], s[48:49], exec
	s_cselect_b32 s51, s31, s51
	s_cselect_b32 s50, s76, s50
	s_add_i32 s42, 0, 0x14000
	v_add_u32_e32 v141, s93, v135
	s_add_u32 vcc_lo, s77, s0
	ds_read_b128 v[152:155], v141
	ds_read_b128 v[156:159], v141 offset:1024
	ds_read_b128 v[160:163], v141 offset:2048
	ds_read_b128 v[164:167], v141 offset:3072
	v_add_u32_e32 v141, s42, v135
	s_addc_u32 vcc_hi, s78, s1
	s_add_i32 s87, s93, s3
	ds_read_b128 v[168:171], v141
	ds_read_b128 v[172:175], v141 offset:1024
	ds_read_b128 v[180:183], v141 offset:2048
	ds_read_b128 v[184:187], v141 offset:3072
	s_add_i32 m0, s16, 0xc000
	s_add_i32 s27, s16, 0xe000
	s_add_i32 s80, s87, 0x2000
	s_add_u32 s96, s50, s10
	s_addc_u32 s97, s51, s11
	s_add_i32 s86, s42, s3
	s_add_i32 s81, s86, 0x2000
	s_add_i32 s79, 0, 0x18000
	s_add_i32 s78, 0, 0x1c000
	s_add_u32 s48, s94, s0
	s_addc_u32 s49, s95, s1
	s_add_i32 s77, s79, s3
	s_add_i32 s93, s78, s3
	s_add_i32 s43, s77, 0x2000
	s_add_i32 s42, s93, 0x2000
	v_lshl_add_u64 v[220:221], vcc, 0, v[132:133]
	v_lshl_add_u64 v[220:221], v[220:221], 0, s[24:25]
	ds_read_b128 v[188:191], v139
	ds_read_b128 v[192:195], v139 offset:1024
	ds_read_b128 v[196:199], v139 offset:2048
	ds_read_b128 v[200:203], v139 offset:3072
	ds_read_b128 v[204:207], v139 offset:4096
	ds_read_b128 v[208:211], v139 offset:5120
	ds_read_b128 v[212:215], v139 offset:6144
	ds_read_b128 v[216:219], v139 offset:7168
	global_load_lds_dwordx4 v[220:221], off
	v_lshl_add_u64 v[220:221], vcc, 0, v[130:131]
	v_lshl_add_u64 v[220:221], v[220:221], 0, s[24:25]
	s_mov_b32 m0, s27
	s_nop 0
	global_load_lds_dwordx4 v[220:221], off
	s_waitcnt vmcnt(8)
	s_waitcnt lgkmcnt(0)
	s_barrier
	s_setprio 1
	s_waitcnt lgkmcnt(0)
	v_mfma_f32_16x16x32_bf16 v[124:127], v[152:155], v[188:191], 0
	v_mfma_f32_16x16x32_bf16 v[120:123], v[160:163], v[188:191], 0
	v_mfma_f32_16x16x32_bf16 v[116:119], v[152:155], v[196:199], 0
	v_mfma_f32_16x16x32_bf16 v[112:115], v[160:163], v[196:199], 0
	v_mfma_f32_16x16x32_bf16 v[100:103], v[152:155], v[204:207], 0
	v_mfma_f32_16x16x32_bf16 v[96:99], v[160:163], v[204:207], 0
	v_mfma_f32_16x16x32_bf16 v[84:87], v[152:155], v[212:215], 0
	v_mfma_f32_16x16x32_bf16 v[80:83], v[160:163], v[212:215], 0
	v_mfma_f32_16x16x32_bf16 v[124:127], v[156:159], v[192:195], v[124:127]
	v_mfma_f32_16x16x32_bf16 v[120:123], v[164:167], v[192:195], v[120:123]
	v_mfma_f32_16x16x32_bf16 v[116:119], v[156:159], v[200:203], v[116:119]
	v_mfma_f32_16x16x32_bf16 v[112:115], v[164:167], v[200:203], v[112:115]
	v_mfma_f32_16x16x32_bf16 v[100:103], v[156:159], v[208:211], v[100:103]
	v_mfma_f32_16x16x32_bf16 v[96:99], v[164:167], v[208:211], v[96:99]
	v_mfma_f32_16x16x32_bf16 v[84:87], v[156:159], v[216:219], v[84:87]
	v_mfma_f32_16x16x32_bf16 v[80:83], v[164:167], v[216:219], v[80:83]
	s_setprio 0
	s_setprio 1
	v_mfma_f32_16x16x32_bf16 v[108:111], v[168:171], v[188:191], 0
	v_mfma_f32_16x16x32_bf16 v[104:107], v[180:183], v[188:191], 0
	v_mfma_f32_16x16x32_bf16 v[92:95], v[168:171], v[196:199], 0
	v_mfma_f32_16x16x32_bf16 v[88:91], v[180:183], v[196:199], 0
	v_mfma_f32_16x16x32_bf16 v[76:79], v[168:171], v[204:207], 0
	v_mfma_f32_16x16x32_bf16 v[72:75], v[180:183], v[204:207], 0
	v_mfma_f32_16x16x32_bf16 v[68:71], v[168:171], v[212:215], 0
	v_mfma_f32_16x16x32_bf16 v[64:67], v[180:183], v[212:215], 0
	v_mfma_f32_16x16x32_bf16 v[108:111], v[172:175], v[192:195], v[108:111]
	v_mfma_f32_16x16x32_bf16 v[104:107], v[184:187], v[192:195], v[104:107]
	v_mfma_f32_16x16x32_bf16 v[92:95], v[172:175], v[200:203], v[92:95]
	v_mfma_f32_16x16x32_bf16 v[88:91], v[184:187], v[200:203], v[88:91]
	v_mfma_f32_16x16x32_bf16 v[76:79], v[172:175], v[208:211], v[76:79]
	v_mfma_f32_16x16x32_bf16 v[72:75], v[184:187], v[208:211], v[72:75]
	v_mfma_f32_16x16x32_bf16 v[68:71], v[172:175], v[216:219], v[68:71]
	v_mfma_f32_16x16x32_bf16 v[64:67], v[184:187], v[216:219], v[64:67]
	s_setprio 0
	s_barrier
; #define PG8_STAGE(bufoff, gbase, voff) do { _Pragma("unroll") for (int _i = 0; _i < 2; ++_i) \
;         __builtin_amdgcn_global_load_lds((const unsigned*)((const char*)(gbase) + (voff)[_i]), (LAS unsigned*)(lds + (bufoff) + ldsw + _i * 8192), 16, 0, 0); } while (0)
; #define PG8_LDA(dst, b, h) do { _Pragma("unroll") for (int m = 0; m < 4; ++m) _Pragma("unroll") for (int k = 0; k < 2; ++k) dst[m][k] = *(const LAS bf16x8*)(lds + PG8_SA(b, h) + aoff + m * 2048 + k * 1024); } while (0)
; #define PG8_MMA(ai, bj, At, Bt) do { __builtin_amdgcn_s_setprio(1); _Pragma("unroll") for (int m = 0; m < 4; ++m) _Pragma("unroll") for (int n = 0; n < 2; ++n) _Pragma("unroll") for (int k = 0; k < 2; ++k) \
;         acc[ai][bj][m][n] = __builtin_amdgcn_mfma_f32_16x16x32_bf16(Bt[n][k], At[m][k], acc[ai][bj][m][n], 0, 0, 0); __builtin_amdgcn_s_setprio(0); } while (0)
; #define PG8_WAIT_V(n) asm volatile("s_waitcnt vmcnt(" #n ")" ::: "memory")
; #define PG8_WAIT_L(n) asm volatile("s_waitcnt lgkmcnt(" #n ")" ::: "memory")
; #define PG8_BAR __builtin_amdgcn_s_barrier()
; #define PG8_SCHED __builtin_amdgcn_sched_barrier(0)
; template <class Epi, class Sched, bool ALIGN_EPI>
; __device__ __forceinline__ void gemm_phase(LAS unsigned char* lds, const int wid, const int lda_, const int ldb_, const int K_, const Sched& S, const Epi& E) {
;     ...
;             PG8_LDA(At, 0, 1); PG8_STAGE(PG8_SB(0, 0), b2, voffB); PG8_STAGE(PG8_SB(0, 1), b2 + hstepB, voffB); PG8_STAGE(PG8_SA(0, 0), a2, voffA);
;             PG8_WAIT_V(8); PG8_WAIT_L(0); PG8_BAR; PG8_MMA(1, 0, At, B0); PG8_MMA(1, 1, At, B1); PG8_BAR; PG8_SCHED;
	s_mov_b32 m0, s87
	v_lshl_add_u64 v[220:221], s[50:51], 0, v[176:177]
	ds_read_b128 v[188:191], v139 offset:16384
	ds_read_b128 v[192:195], v139 offset:17408
	ds_read_b128 v[196:199], v139 offset:18432
	ds_read_b128 v[200:203], v139 offset:19456
	ds_read_b128 v[204:207], v139 offset:20480
	ds_read_b128 v[208:211], v139 offset:21504
	ds_read_b128 v[212:215], v139 offset:22528
	ds_read_b128 v[216:219], v139 offset:23552
	global_load_lds_dwordx4 v[220:221], off
	v_lshl_add_u64 v[222:223], s[50:51], 0, v[128:129]
	s_mov_b32 m0, s80
	v_lshl_add_u64 v[224:225], s[96:97], 0, v[176:177]
	global_load_lds_dwordx4 v[222:223], off
	s_mov_b32 m0, s86
	v_lshl_add_u64 v[226:227], s[96:97], 0, v[128:129]
	global_load_lds_dwordx4 v[224:225], off
	s_mov_b32 m0, s81
	v_lshl_add_u64 v[228:229], s[94:95], 0, v[132:133]
	global_load_lds_dwordx4 v[226:227], off
	s_mov_b32 m0, s16
	v_lshl_add_u64 v[230:231], s[94:95], 0, v[130:131]
	global_load_lds_dwordx4 v[228:229], off
	s_mov_b32 m0, s6
	s_nop 0
	global_load_lds_dwordx4 v[230:231], off
	s_waitcnt vmcnt(8)
	s_waitcnt lgkmcnt(0)
	s_barrier
	s_setprio 1
	s_waitcnt lgkmcnt(0)
	v_mfma_f32_16x16x32_bf16 v[60:63], v[152:155], v[188:191], 0
	v_mfma_f32_16x16x32_bf16 v[56:59], v[160:163], v[188:191], 0
	v_mfma_f32_16x16x32_bf16 v[52:55], v[152:155], v[196:199], 0
	v_mfma_f32_16x16x32_bf16 v[48:51], v[160:163], v[196:199], 0
	v_mfma_f32_16x16x32_bf16 v[36:39], v[152:155], v[204:207], 0
	v_mfma_f32_16x16x32_bf16 v[32:35], v[160:163], v[204:207], 0
	v_mfma_f32_16x16x32_bf16 v[20:23], v[152:155], v[212:215], 0
	v_mfma_f32_16x16x32_bf16 v[16:19], v[160:163], v[212:215], 0
	v_mfma_f32_16x16x32_bf16 v[60:63], v[156:159], v[192:195], v[60:63]
	v_mfma_f32_16x16x32_bf16 v[56:59], v[164:167], v[192:195], v[56:59]
	v_mfma_f32_16x16x32_bf16 v[52:55], v[156:159], v[200:203], v[52:55]
	v_mfma_f32_16x16x32_bf16 v[48:51], v[164:167], v[200:203], v[48:51]
	v_mfma_f32_16x16x32_bf16 v[36:39], v[156:159], v[208:211], v[36:39]
	v_mfma_f32_16x16x32_bf16 v[32:35], v[164:167], v[208:211], v[32:35]
	v_mfma_f32_16x16x32_bf16 v[20:23], v[156:159], v[216:219], v[20:23]
	v_mfma_f32_16x16x32_bf16 v[16:19], v[164:167], v[216:219], v[16:19]
	s_setprio 0
	s_setprio 1
	v_mfma_f32_16x16x32_bf16 v[44:47], v[168:171], v[188:191], 0
	v_mfma_f32_16x16x32_bf16 v[40:43], v[180:183], v[188:191], 0
	v_mfma_f32_16x16x32_bf16 v[28:31], v[168:171], v[196:199], 0
	v_mfma_f32_16x16x32_bf16 v[24:27], v[180:183], v[196:199], 0
	v_mfma_f32_16x16x32_bf16 v[12:15], v[168:171], v[204:207], 0
	v_mfma_f32_16x16x32_bf16 v[8:11], v[180:183], v[204:207], 0
	v_mfma_f32_16x16x32_bf16 v[4:7], v[168:171], v[212:215], 0
	v_mfma_f32_16x16x32_bf16 v[0:3], v[180:183], v[212:215], 0
	v_mfma_f32_16x16x32_bf16 v[44:47], v[172:175], v[192:195], v[44:47]
	v_mfma_f32_16x16x32_bf16 v[40:43], v[184:187], v[192:195], v[40:43]
	v_mfma_f32_16x16x32_bf16 v[28:31], v[172:175], v[200:203], v[28:31]
	v_mfma_f32_16x16x32_bf16 v[24:27], v[184:187], v[200:203], v[24:27]
	v_mfma_f32_16x16x32_bf16 v[12:15], v[172:175], v[208:211], v[12:15]
	v_mfma_f32_16x16x32_bf16 v[8:11], v[184:187], v[208:211], v[8:11]
	v_mfma_f32_16x16x32_bf16 v[4:7], v[172:175], v[216:219], v[4:7]
	v_mfma_f32_16x16x32_bf16 v[0:3], v[184:187], v[216:219], v[0:3]
	s_setprio 0
	s_barrier
	s_branch .Lgemm_join_697

; #define PG8_STAGE(bufoff, gbase, voff) do { _Pragma("unroll") for (int _i = 0; _i < 2; ++_i) \
;         __builtin_amdgcn_global_load_lds((const unsigned*)((const char*)(gbase) + (voff)[_i]), (LAS unsigned*)(lds + (bufoff) + ldsw + _i * 8192), 16, 0, 0); } while (0)
; #define PG8_LDA(dst, b, h) do { _Pragma("unroll") for (int m = 0; m < 4; ++m) _Pragma("unroll") for (int k = 0; k < 2; ++k) dst[m][k] = *(const LAS bf16x8*)(lds + PG8_SA(b, h) + aoff + m * 2048 + k * 1024); } while (0)
; #define PG8_LDB(dst, b, h) do { _Pragma("unroll") for (int n = 0; n < 2; ++n) _Pragma("unroll") for (int k = 0; k < 2; ++k) dst[n][k] = *(const LAS bf16x8*)(lds + PG8_SB(b, h) + boff + n * 2048 + k * 1024); } while (0)
; #define PG8_MMA(ai, bj, At, Bt) do { __builtin_amdgcn_s_setprio(1); _Pragma("unroll") for (int m = 0; m < 4; ++m) _Pragma("unroll") for (int n = 0; n < 2; ++n) _Pragma("unroll") for (int k = 0; k < 2; ++k) \
;         acc[ai][bj][m][n] = __builtin_amdgcn_mfma_f32_16x16x32_bf16(Bt[n][k], At[m][k], acc[ai][bj][m][n], 0, 0, 0); __builtin_amdgcn_s_setprio(0); } while (0)
; #define PG8_WAIT_V(n) asm volatile("s_waitcnt vmcnt(" #n ")" ::: "memory")
; #define PG8_WAIT_L(n) asm volatile("s_waitcnt lgkmcnt(" #n ")" ::: "memory")
; #define PG8_BAR __builtin_amdgcn_s_barrier()
; #define PG8_SCHED __builtin_amdgcn_sched_barrier(0)
; template <class Epi, class Sched, bool ALIGN_EPI>
; __device__ __forceinline__ void gemm_phase(LAS unsigned char* lds, const int wid, const int lda_, const int ldb_, const int K_, const Sched& S, const Epi& E) {
;     ...
;             PG8_LDB(B0, 1, 0); PG8_LDB(B1, 1, 1); PG8_SCHED; PG8_LDA(At, 1, 0); PG8_STAGE(PG8_SA(0, 1), a2 + hstepA, voffA);
;             PG8_WAIT_V(8); PG8_WAIT_L(0); PG8_BAR; PG8_MMA(0, 0, At, B0); PG8_MMA(0, 1, At, B1); PG8_BAR; PG8_SCHED;
.Lgemm_join_697:
	v_add_u32_e32 v141, s79, v135
	ds_read_b128 v[152:155], v141
	ds_read_b128 v[156:159], v141 offset:1024
	ds_read_b128 v[160:163], v141 offset:2048
	ds_read_b128 v[164:167], v141 offset:3072
	v_add_u32_e32 v141, s78, v135
	ds_read_b128 v[168:171], v141
	ds_read_b128 v[172:175], v141 offset:1024
	ds_read_b128 v[180:183], v141 offset:2048
	ds_read_b128 v[184:187], v141 offset:3072
	s_mov_b32 m0, s7
	v_lshl_add_u64 v[232:233], s[48:49], 0, v[132:133]
	ds_read_b128 v[188:191], v139 offset:32768
	ds_read_b128 v[192:195], v139 offset:33792
	ds_read_b128 v[196:199], v139 offset:34816
	ds_read_b128 v[200:203], v139 offset:35840
	ds_read_b128 v[204:207], v139 offset:36864
	ds_read_b128 v[208:211], v139 offset:37888
	ds_read_b128 v[212:215], v139 offset:38912
	ds_read_b128 v[216:219], v139 offset:39936
	global_load_lds_dwordx4 v[232:233], off
	v_lshl_add_u64 v[232:233], s[48:49], 0, v[130:131]
	s_mov_b32 m0, s14
	s_nop 0
	global_load_lds_dwordx4 v[232:233], off
	s_waitcnt vmcnt(8)
	s_waitcnt lgkmcnt(0)
	s_barrier
	s_setprio 1
	s_waitcnt lgkmcnt(0)
	v_mfma_f32_16x16x32_bf16 v[124:127], v[152:155], v[188:191], v[124:127]
	v_mfma_f32_16x16x32_bf16 v[120:123], v[160:163], v[188:191], v[120:123]
	v_mfma_f32_16x16x32_bf16 v[116:119], v[152:155], v[196:199], v[116:119]
	v_mfma_f32_16x16x32_bf16 v[112:115], v[160:163], v[196:199], v[112:115]
	v_mfma_f32_16x16x32_bf16 v[100:103], v[152:155], v[204:207], v[100:103]
	v_mfma_f32_16x16x32_bf16 v[96:99], v[160:163], v[204:207], v[96:99]
	v_mfma_f32_16x16x32_bf16 v[84:87], v[152:155], v[212:215], v[84:87]
	v_mfma_f32_16x16x32_bf16 v[80:83], v[160:163], v[212:215], v[80:83]
	v_mfma_f32_16x16x32_bf16 v[124:127], v[156:159], v[192:195], v[124:127]
	v_mfma_f32_16x16x32_bf16 v[120:123], v[164:167], v[192:195], v[120:123]
	v_mfma_f32_16x16x32_bf16 v[116:119], v[156:159], v[200:203], v[116:119]
	v_mfma_f32_16x16x32_bf16 v[112:115], v[164:167], v[200:203], v[112:115]
	v_mfma_f32_16x16x32_bf16 v[100:103], v[156:159], v[208:211], v[100:103]
	v_mfma_f32_16x16x32_bf16 v[96:99], v[164:167], v[208:211], v[96:99]
	v_mfma_f32_16x16x32_bf16 v[84:87], v[156:159], v[216:219], v[84:87]
	v_mfma_f32_16x16x32_bf16 v[80:83], v[164:167], v[216:219], v[80:83]
	s_setprio 0
	s_setprio 1
	v_mfma_f32_16x16x32_bf16 v[108:111], v[168:171], v[188:191], v[108:111]
	v_mfma_f32_16x16x32_bf16 v[104:107], v[180:183], v[188:191], v[104:107]
	v_mfma_f32_16x16x32_bf16 v[92:95], v[168:171], v[196:199], v[92:95]
	v_mfma_f32_16x16x32_bf16 v[88:91], v[180:183], v[196:199], v[88:91]
	v_mfma_f32_16x16x32_bf16 v[76:79], v[168:171], v[204:207], v[76:79]
	v_mfma_f32_16x16x32_bf16 v[72:75], v[180:183], v[204:207], v[72:75]
	v_mfma_f32_16x16x32_bf16 v[68:71], v[168:171], v[212:215], v[68:71]
	v_mfma_f32_16x16x32_bf16 v[64:67], v[180:183], v[212:215], v[64:67]
	v_mfma_f32_16x16x32_bf16 v[108:111], v[172:175], v[192:195], v[108:111]
	v_mfma_f32_16x16x32_bf16 v[104:107], v[184:187], v[192:195], v[104:107]
	v_mfma_f32_16x16x32_bf16 v[92:95], v[172:175], v[200:203], v[92:95]
	v_mfma_f32_16x16x32_bf16 v[88:91], v[184:187], v[200:203], v[88:91]
	v_mfma_f32_16x16x32_bf16 v[76:79], v[172:175], v[208:211], v[76:79]
	v_mfma_f32_16x16x32_bf16 v[72:75], v[184:187], v[208:211], v[72:75]
	v_mfma_f32_16x16x32_bf16 v[68:71], v[172:175], v[216:219], v[68:71]
	v_mfma_f32_16x16x32_bf16 v[64:67], v[184:187], v[216:219], v[64:67]
	s_setprio 0
	s_barrier
; #define PG8_STAGE(bufoff, gbase, voff) do { _Pragma("unroll") for (int _i = 0; _i < 2; ++_i) \
;         __builtin_amdgcn_global_load_lds((const unsigned*)((const char*)(gbase) + (voff)[_i]), (LAS unsigned*)(lds + (bufoff) + ldsw + _i * 8192), 16, 0, 0); } while (0)
; #define PG8_LDA(dst, b, h) do { _Pragma("unroll") for (int m = 0; m < 4; ++m) _Pragma("unroll") for (int k = 0; k < 2; ++k) dst[m][k] = *(const LAS bf16x8*)(lds + PG8_SA(b, h) + aoff + m * 2048 + k * 1024); } while (0)
; #define PG8_MMA(ai, bj, At, Bt) do { __builtin_amdgcn_s_setprio(1); _Pragma("unroll") for (int m = 0; m < 4; ++m) _Pragma("unroll") for (int n = 0; n < 2; ++n) _Pragma("unroll") for (int k = 0; k < 2; ++k) \
;         acc[ai][bj][m][n] = __builtin_amdgcn_mfma_f32_16x16x32_bf16(Bt[n][k], At[m][k], acc[ai][bj][m][n], 0, 0, 0); __builtin_amdgcn_s_setprio(0); } while (0)
; #define PG8_WAIT_V(n) asm volatile("s_waitcnt vmcnt(" #n ")" ::: "memory")
; #define PG8_WAIT_L(n) asm volatile("s_waitcnt lgkmcnt(" #n ")" ::: "memory")
; #define PG8_BAR __builtin_amdgcn_s_barrier()
; #define PG8_SCHED __builtin_amdgcn_sched_barrier(0)
;     __device__ __forceinline__ const char* b(const pg8::Unit& u) const { return (const char*)ws + boff + (size_t)u.pn * 256 * K_ * 2 + (u.kq < 0 ? 0 : u.kq * (K_ / 4) * 2); }
; template <class Epi, class Sched, bool ALIGN_EPI>
; __device__ __forceinline__ void gemm_phase(LAS unsigned char* lds, const int wid, const int lda_, const int ldb_, const int K_, const Sched& S, const Epi& E) {
;     ...
;             PG8_LDA(At, 1, 1); PG8_STAGE(PG8_SB(1, 0), b3, voffB); PG8_STAGE(PG8_SB(1, 1), b3 + hstepB, voffB); PG8_STAGE(PG8_SA(1, 0), a3, voffA);
;             PG8_WAIT_V(8); PG8_WAIT_L(0); PG8_BAR; PG8_MMA(1, 0, At, B0); PG8_MMA(1, 1, At, B1); PG8_BAR; PG8_SCHED;
;         }
;         if constexpr (ALIGN_EPI) { if (wr == 0) PG8_BAR; }
;         E(acc, cur, S, wr, wc, fr, fq);
;         if (!has_next) break;
;     __device__ __forceinline__ void out(const pg8::Unit& u, char*& o, int& ldo, int& kind) const { const int g = u.pm >> 1, cs = u.pm & 1;
;         if (u.pn < 64) { const int b = u.pn >> 3, p0 = (u.pn & 7) * 256; o = (char*)ws + WS_PQT + (((size_t)(b * 2048 + g * 256)) * 4096 + (size_t)cs * 2048 + p0) * 2; ldo = 4096; }
;         else { const int b = u.pn - 64; o = (char*)ws + WS_PQTC + (((size_t)(b * 2048 + g * 256)) * 512 + (size_t)cs * 256) * 2; ldo = 512; }
	s_mov_b32 m0, s77
	v_lshl_add_u64 v[220:221], v[220:221], 0, s[24:25]
	ds_read_b128 v[188:191], v139 offset:49152
	ds_read_b128 v[192:195], v139 offset:50176
	ds_read_b128 v[196:199], v139 offset:51200
	ds_read_b128 v[200:203], v139 offset:52224
	ds_read_b128 v[204:207], v139 offset:53248
	ds_read_b128 v[208:211], v139 offset:54272
	ds_read_b128 v[212:215], v139 offset:55296
	ds_read_b128 v[216:219], v139 offset:56320
	global_load_lds_dwordx4 v[220:221], off
	v_lshl_add_u64 v[220:221], v[222:223], 0, s[24:25]
	s_mov_b32 m0, s43
	s_nop 0
	global_load_lds_dwordx4 v[220:221], off
	v_lshl_add_u64 v[220:221], v[224:225], 0, s[24:25]
	s_mov_b32 m0, s93
	s_nop 0
	global_load_lds_dwordx4 v[220:221], off
	v_lshl_add_u64 v[220:221], v[226:227], 0, s[24:25]
	s_mov_b32 m0, s42
	s_nop 0
	global_load_lds_dwordx4 v[220:221], off
	v_lshl_add_u64 v[220:221], v[228:229], 0, s[24:25]
	s_mov_b32 m0, s15
	s_nop 0
	global_load_lds_dwordx4 v[220:221], off
	v_lshl_add_u64 v[220:221], v[230:231], 0, s[24:25]
	s_mov_b32 m0, s26
	s_nop 0
	global_load_lds_dwordx4 v[220:221], off
	s_waitcnt vmcnt(8)
	s_waitcnt lgkmcnt(0)
	s_barrier
	s_setprio 1
	s_waitcnt lgkmcnt(0)
	v_mfma_f32_16x16x32_bf16 v[60:63], v[152:155], v[188:191], v[60:63]
	v_mfma_f32_16x16x32_bf16 v[56:59], v[160:163], v[188:191], v[56:59]
	v_mfma_f32_16x16x32_bf16 v[52:55], v[152:155], v[196:199], v[52:55]
	v_mfma_f32_16x16x32_bf16 v[48:51], v[160:163], v[196:199], v[48:51]
	v_mfma_f32_16x16x32_bf16 v[36:39], v[152:155], v[204:207], v[36:39]
	v_mfma_f32_16x16x32_bf16 v[32:35], v[160:163], v[204:207], v[32:35]
	v_mfma_f32_16x16x32_bf16 v[20:23], v[152:155], v[212:215], v[20:23]
	v_mfma_f32_16x16x32_bf16 v[16:19], v[160:163], v[212:215], v[16:19]
	v_mfma_f32_16x16x32_bf16 v[60:63], v[156:159], v[192:195], v[60:63]
	v_mfma_f32_16x16x32_bf16 v[56:59], v[164:167], v[192:195], v[56:59]
	v_mfma_f32_16x16x32_bf16 v[52:55], v[156:159], v[200:203], v[52:55]
	v_mfma_f32_16x16x32_bf16 v[48:51], v[164:167], v[200:203], v[48:51]
	v_mfma_f32_16x16x32_bf16 v[36:39], v[156:159], v[208:211], v[36:39]
	v_mfma_f32_16x16x32_bf16 v[32:35], v[164:167], v[208:211], v[32:35]
	v_mfma_f32_16x16x32_bf16 v[20:23], v[156:159], v[216:219], v[20:23]
	v_mfma_f32_16x16x32_bf16 v[16:19], v[164:167], v[216:219], v[16:19]
	s_setprio 0
	s_setprio 1
	v_mfma_f32_16x16x32_bf16 v[44:47], v[168:171], v[188:191], v[44:47]
	v_mfma_f32_16x16x32_bf16 v[40:43], v[180:183], v[188:191], v[40:43]
	v_mfma_f32_16x16x32_bf16 v[28:31], v[168:171], v[196:199], v[28:31]
	v_mfma_f32_16x16x32_bf16 v[24:27], v[180:183], v[196:199], v[24:27]
	v_mfma_f32_16x16x32_bf16 v[12:15], v[168:171], v[204:207], v[12:15]
	v_mfma_f32_16x16x32_bf16 v[8:11], v[180:183], v[204:207], v[8:11]
	v_mfma_f32_16x16x32_bf16 v[4:7], v[168:171], v[212:215], v[4:7]
	v_mfma_f32_16x16x32_bf16 v[0:3], v[180:183], v[212:215], v[0:3]
	v_mfma_f32_16x16x32_bf16 v[44:47], v[172:175], v[192:195], v[44:47]
	v_mfma_f32_16x16x32_bf16 v[40:43], v[184:187], v[192:195], v[40:43]
	v_mfma_f32_16x16x32_bf16 v[28:31], v[172:175], v[200:203], v[28:31]
	v_mfma_f32_16x16x32_bf16 v[24:27], v[184:187], v[200:203], v[24:27]
	v_mfma_f32_16x16x32_bf16 v[12:15], v[172:175], v[208:211], v[12:15]
	v_mfma_f32_16x16x32_bf16 v[8:11], v[184:187], v[208:211], v[8:11]
	v_mfma_f32_16x16x32_bf16 v[4:7], v[172:175], v[216:219], v[4:7]
	v_mfma_f32_16x16x32_bf16 v[0:3], v[184:187], v[216:219], v[0:3]
	s_setprio 0
	s_barrier
	s_andn2_b64 vcc, exec, s[46:47]
	s_mov_b64 s[48:49], -1
	s_mov_b64 s[46:47], 0
	s_mov_b64 s[50:51], 0x100
	s_cbranch_vccz .LBB0_697
	s_ashr_i32 s43, s75, 1
	s_and_b32 s42, s75, 1
	s_cmp_gt_i32 s74, 63
	s_mov_b64 s[40:41], -1
	s_cbranch_scc0 .LBB0_700
	s_lshl_b32 s4, s74, 11
	s_lshl_b32 s5, s43, 8
	s_add_i32 s4, s4, s5
	s_add_i32 s4, s4, 0xfffe0000
	s_ashr_i32 s5, s4, 31
	s_lshl_b32 s31, s42, 9
	s_lshl_b64 s[4:5], s[4:5], 10
	v_readlane_b32 s17, v254, 2
	s_add_u32 s4, s17, s4
	v_readlane_b32 s17, v254, 3
	s_addc_u32 s5, s17, s5
	s_add_u32 s4, s4, s31
	s_addc_u32 s5, s5, 0
	s_mov_b64 s[40:41], 0

; #define PG8_STAGE(bufoff, gbase, voff) do { _Pragma("unroll") for (int _i = 0; _i < 2; ++_i) \
;         __builtin_amdgcn_global_load_lds((const unsigned*)((const char*)(gbase) + (voff)[_i]), (LAS unsigned*)(lds + (bufoff) + ldsw + _i * 8192), 16, 0, 0); } while (0)
; #define PG8_LDA(dst, b, h) do { _Pragma("unroll") for (int m = 0; m < 4; ++m) _Pragma("unroll") for (int k = 0; k < 2; ++k) dst[m][k] = *(const LAS bf16x8*)(lds + PG8_SA(b, h) + aoff + m * 2048 + k * 1024); } while (0)
; #define PG8_LDB(dst, b, h) do { _Pragma("unroll") for (int n = 0; n < 2; ++n) _Pragma("unroll") for (int k = 0; k < 2; ++k) dst[n][k] = *(const LAS bf16x8*)(lds + PG8_SB(b, h) + boff + n * 2048 + k * 1024); } while (0)
; #define PG8_MMA(ai, bj, At, Bt) do { __builtin_amdgcn_s_setprio(1); _Pragma("unroll") for (int m = 0; m < 4; ++m) _Pragma("unroll") for (int n = 0; n < 2; ++n) _Pragma("unroll") for (int k = 0; k < 2; ++k) \
;         acc[ai][bj][m][n] = __builtin_amdgcn_mfma_f32_16x16x32_bf16(Bt[n][k], At[m][k], acc[ai][bj][m][n], 0, 0, 0); __builtin_amdgcn_s_setprio(0); } while (0)
; #define PG8_WAIT_V(n) asm volatile("s_waitcnt vmcnt(" #n ")" ::: "memory")
; #define PG8_WAIT_L(n) asm volatile("s_waitcnt lgkmcnt(" #n ")" ::: "memory")
; template <class Epi, class Sched, bool ALIGN_EPI>
; __device__ __forceinline__ void gemm_phase(LAS unsigned char* lds, const int wid, const int lda_, const int ldb_, const int K_, const Sched& S, const Epi& E) {
;     ...
;         const bool has_next = S.next(ui + 1, nxt);
;         const int nt = S.nt(cur);
;         const char* nA = has_next ? S.a(nxt) : cA; const char* nB = has_next ? S.b(nxt) : cB;
; #pragma unroll 1
;         for (int t = 0; t < nt; t += 2) {
;             const bool last = (t == nt - 2);
;             const char* a1 = cA + (size_t)(t + 1) * kstep;
;             const char* a2 = last ? nA : cA + (size_t)(t + 2) * kstep; const char* b2 = last ? nB : cB + (size_t)(t + 2) * kstep;
;             const char* a3 = a2 + kstep; const char* b3 = b2 + kstep;
;             PG8_LDB(B0, 0, 0); PG8_LDB(B1, 0, 1); PG8_SCHED; PG8_LDA(At, 0, 0); PG8_STAGE(PG8_SA(1, 1), a1 + hstepA, voffA);
;             PG8_WAIT_V(8); PG8_WAIT_L(0); PG8_BAR; PG8_MMA(0, 0, At, B0); PG8_MMA(0, 1, At, B1); PG8_BAR; PG8_SCHED;
;     __device__ __forceinline__ const char* a(const pg8::Unit& u) const { return (const char*)ws + (u.pm < 64 ? WS_W2 : WS_W2C); }
.LBB0_882:
	s_and_b64 s[4:5], s[4:5], exec
	s_cselect_b32 s4, s27, 0x380000
	s_add_u32 s44, s66, s4
	s_addc_u32 s45, s67, 0
	s_and_b64 s[4:5], s[50:51], exec
	s_cselect_b32 s4, s45, s47
	s_cselect_b32 s5, s44, s46
	s_add_u32 s42, s46, 0x80
	s_addc_u32 s43, s47, 0
	s_add_u32 s31, s48, 0x100
	v_lshl_add_u64 v[156:157], s[42:43], 0, v[152:153]
	v_lshl_add_u64 v[158:159], s[42:43], 0, v[154:155]
	s_addc_u32 s35, s49, 0
	s_mov_b32 s73, -2
	s_mov_b64 s[48:49], 0
	s_add_u32 s17, s46, s48
	s_addc_u32 s27, s47, s49
	s_add_u32 s17, s17, 0x100
	s_addc_u32 s27, s27, 0
	s_add_u32 s42, s31, s48
	s_addc_u32 s43, s35, s49
	s_add_i32 s74, 0, 0x10000
	s_cmpk_eq_i32 s48, 0x300
	s_cselect_b32 s51, s4, s27
	s_cselect_b32 s50, s5, s17
	v_add_u32_e32 v141, s74, v135
	s_cselect_b32 s43, s39, s43
	s_cselect_b32 s42, s38, s42
	s_add_i32 s17, 0, 0x14000
	ds_read_b128 v[160:163], v141
	ds_read_b128 v[164:167], v141 offset:1024
	ds_read_b128 v[168:171], v141 offset:2048
	ds_read_b128 v[172:175], v141 offset:3072
	v_add_u32_e32 v141, s17, v135
	ds_read_b128 v[180:183], v141
	ds_read_b128 v[184:187], v141 offset:1024
	ds_read_b128 v[188:191], v141 offset:2048
	ds_read_b128 v[192:195], v141 offset:3072
	v_lshl_add_u64 v[228:229], v[158:159], 0, s[48:49]
	s_add_i32 m0, s16, 0xc000
	ds_read_b128 v[196:199], v139
	ds_read_b128 v[200:203], v139 offset:1024
	ds_read_b128 v[204:207], v139 offset:2048
	ds_read_b128 v[208:211], v139 offset:3072
	ds_read_b128 v[212:215], v139 offset:4096
	ds_read_b128 v[216:219], v139 offset:5120
	ds_read_b128 v[220:223], v139 offset:6144
	ds_read_b128 v[224:227], v139 offset:7168
	global_load_lds_dwordx4 v[228:229], off
	v_lshl_add_u64 v[228:229], v[156:157], 0, s[48:49]
	s_add_i32 m0, s16, 0xe000
	s_nop 0
	global_load_lds_dwordx4 v[228:229], off
	s_waitcnt vmcnt(8)
	s_waitcnt lgkmcnt(0)
	s_barrier
	s_setprio 1
	s_waitcnt lgkmcnt(0)
	v_mfma_f32_16x16x32_bf16 v[124:127], v[160:163], v[196:199], 0
	v_mfma_f32_16x16x32_bf16 v[120:123], v[168:171], v[196:199], 0
	v_mfma_f32_16x16x32_bf16 v[116:119], v[160:163], v[204:207], 0
	v_mfma_f32_16x16x32_bf16 v[112:115], v[168:171], v[204:207], 0
	v_mfma_f32_16x16x32_bf16 v[100:103], v[160:163], v[212:215], 0
	v_mfma_f32_16x16x32_bf16 v[96:99], v[168:171], v[212:215], 0
	v_mfma_f32_16x16x32_bf16 v[84:87], v[160:163], v[220:223], 0
	v_mfma_f32_16x16x32_bf16 v[80:83], v[168:171], v[220:223], 0
	v_mfma_f32_16x16x32_bf16 v[124:127], v[164:167], v[200:203], v[124:127]
	v_mfma_f32_16x16x32_bf16 v[120:123], v[172:175], v[200:203], v[120:123]
	v_mfma_f32_16x16x32_bf16 v[116:119], v[164:167], v[208:211], v[116:119]
	v_mfma_f32_16x16x32_bf16 v[112:115], v[172:175], v[208:211], v[112:115]
	v_mfma_f32_16x16x32_bf16 v[100:103], v[164:167], v[216:219], v[100:103]
	v_mfma_f32_16x16x32_bf16 v[96:99], v[172:175], v[216:219], v[96:99]
	v_mfma_f32_16x16x32_bf16 v[84:87], v[164:167], v[224:227], v[84:87]
	v_mfma_f32_16x16x32_bf16 v[80:83], v[172:175], v[224:227], v[80:83]
	s_setprio 0
	s_setprio 1
	v_mfma_f32_16x16x32_bf16 v[108:111], v[180:183], v[196:199], 0
	v_mfma_f32_16x16x32_bf16 v[104:107], v[188:191], v[196:199], 0
	v_mfma_f32_16x16x32_bf16 v[92:95], v[180:183], v[204:207], 0
	v_mfma_f32_16x16x32_bf16 v[88:91], v[188:191], v[204:207], 0
	v_mfma_f32_16x16x32_bf16 v[76:79], v[180:183], v[212:215], 0
	v_mfma_f32_16x16x32_bf16 v[72:75], v[188:191], v[212:215], 0
	v_mfma_f32_16x16x32_bf16 v[68:71], v[180:183], v[220:223], 0
	v_mfma_f32_16x16x32_bf16 v[64:67], v[188:191], v[220:223], 0
	v_mfma_f32_16x16x32_bf16 v[108:111], v[184:187], v[200:203], v[108:111]
	v_mfma_f32_16x16x32_bf16 v[104:107], v[192:195], v[200:203], v[104:107]
	v_mfma_f32_16x16x32_bf16 v[92:95], v[184:187], v[208:211], v[92:95]
	v_mfma_f32_16x16x32_bf16 v[88:91], v[192:195], v[208:211], v[88:91]
	v_mfma_f32_16x16x32_bf16 v[76:79], v[184:187], v[216:219], v[76:79]
	v_mfma_f32_16x16x32_bf16 v[72:75], v[192:195], v[216:219], v[72:75]
	v_mfma_f32_16x16x32_bf16 v[68:71], v[184:187], v[224:227], v[68:71]
	v_mfma_f32_16x16x32_bf16 v[64:67], v[192:195], v[224:227], v[64:67]
	s_setprio 0
	s_barrier
; #define PG8_STAGE(bufoff, gbase, voff) do { _Pragma("unroll") for (int _i = 0; _i < 2; ++_i) \
;         __builtin_amdgcn_global_load_lds((const unsigned*)((const char*)(gbase) + (voff)[_i]), (LAS unsigned*)(lds + (bufoff) + ldsw + _i * 8192), 16, 0, 0); } while (0)
; #define PG8_LDA(dst, b, h) do { _Pragma("unroll") for (int m = 0; m < 4; ++m) _Pragma("unroll") for (int k = 0; k < 2; ++k) dst[m][k] = *(const LAS bf16x8*)(lds + PG8_SA(b, h) + aoff + m * 2048 + k * 1024); } while (0)
; #define PG8_MMA(ai, bj, At, Bt) do { __builtin_amdgcn_s_setprio(1); _Pragma("unroll") for (int m = 0; m < 4; ++m) _Pragma("unroll") for (int n = 0; n < 2; ++n) _Pragma("unroll") for (int k = 0; k < 2; ++k) \
;         acc[ai][bj][m][n] = __builtin_amdgcn_mfma_f32_16x16x32_bf16(Bt[n][k], At[m][k], acc[ai][bj][m][n], 0, 0, 0); __builtin_amdgcn_s_setprio(0); } while (0)
; #define PG8_WAIT_V(n) asm volatile("s_waitcnt vmcnt(" #n ")" ::: "memory")
; #define PG8_WAIT_L(n) asm volatile("s_waitcnt lgkmcnt(" #n ")" ::: "memory")
; #define PG8_BAR __builtin_amdgcn_s_barrier()
; #define PG8_SCHED __builtin_amdgcn_sched_barrier(0)
; template <class Epi, class Sched, bool ALIGN_EPI>
; __device__ __forceinline__ void gemm_phase(LAS unsigned char* lds, const int wid, const int lda_, const int ldb_, const int K_, const Sched& S, const Epi& E) {
;     ...
;             PG8_LDA(At, 0, 1); PG8_STAGE(PG8_SB(0, 0), b2, voffB); PG8_STAGE(PG8_SB(0, 1), b2 + hstepB, voffB); PG8_STAGE(PG8_SA(0, 0), a2, voffA);
;             PG8_WAIT_V(8); PG8_WAIT_L(0); PG8_BAR; PG8_MMA(1, 0, At, B0); PG8_MMA(1, 1, At, B1); PG8_BAR; PG8_SCHED;
	s_add_i32 s27, s74, s3
	v_lshl_add_u64 v[228:229], s[42:43], 0, v[176:177]
	s_mov_b32 m0, s27
	ds_read_b128 v[196:199], v139 offset:16384
	ds_read_b128 v[200:203], v139 offset:17408
	ds_read_b128 v[204:207], v139 offset:18432
	ds_read_b128 v[208:211], v139 offset:19456
	ds_read_b128 v[212:215], v139 offset:20480
	ds_read_b128 v[216:219], v139 offset:21504
	ds_read_b128 v[220:223], v139 offset:22528
	ds_read_b128 v[224:227], v139 offset:23552
	global_load_lds_dwordx4 v[228:229], off
	s_add_i32 m0, s27, 0x2000
	v_lshl_add_u64 v[230:231], s[42:43], 0, v[132:133]
	s_add_u32 s42, s42, s10
	s_addc_u32 s43, s43, s11
	s_add_i32 s17, s17, s3
	global_load_lds_dwordx4 v[230:231], off
	v_lshl_add_u64 v[232:233], s[42:43], 0, v[176:177]
	s_mov_b32 m0, s17
	v_lshl_add_u64 v[234:235], s[42:43], 0, v[132:133]
	global_load_lds_dwordx4 v[232:233], off
	s_add_i32 m0, s17, 0x2000
	v_lshl_add_u64 v[236:237], s[50:51], 0, v[128:129]
	global_load_lds_dwordx4 v[234:235], off
	s_mov_b32 m0, s16
	v_lshl_add_u64 v[246:247], s[50:51], 0, v[130:131]
	global_load_lds_dwordx4 v[236:237], off
	s_mov_b32 m0, s6
	s_nop 0
	global_load_lds_dwordx4 v[246:247], off
	s_waitcnt vmcnt(8)
	s_waitcnt lgkmcnt(0)
	s_barrier
	s_setprio 1
	s_waitcnt lgkmcnt(0)
	v_mfma_f32_16x16x32_bf16 v[60:63], v[160:163], v[196:199], 0
	v_mfma_f32_16x16x32_bf16 v[56:59], v[168:171], v[196:199], 0
	v_mfma_f32_16x16x32_bf16 v[52:55], v[160:163], v[204:207], 0
	v_mfma_f32_16x16x32_bf16 v[48:51], v[168:171], v[204:207], 0
	v_mfma_f32_16x16x32_bf16 v[36:39], v[160:163], v[212:215], 0
	v_mfma_f32_16x16x32_bf16 v[32:35], v[168:171], v[212:215], 0
	v_mfma_f32_16x16x32_bf16 v[20:23], v[160:163], v[220:223], 0
	v_mfma_f32_16x16x32_bf16 v[16:19], v[168:171], v[220:223], 0
	v_mfma_f32_16x16x32_bf16 v[60:63], v[164:167], v[200:203], v[60:63]
	v_mfma_f32_16x16x32_bf16 v[56:59], v[172:175], v[200:203], v[56:59]
	v_mfma_f32_16x16x32_bf16 v[52:55], v[164:167], v[208:211], v[52:55]
	v_mfma_f32_16x16x32_bf16 v[48:51], v[172:175], v[208:211], v[48:51]
	v_mfma_f32_16x16x32_bf16 v[36:39], v[164:167], v[216:219], v[36:39]
	v_mfma_f32_16x16x32_bf16 v[32:35], v[172:175], v[216:219], v[32:35]
	v_mfma_f32_16x16x32_bf16 v[20:23], v[164:167], v[224:227], v[20:23]
	v_mfma_f32_16x16x32_bf16 v[16:19], v[172:175], v[224:227], v[16:19]
	s_setprio 0
	s_setprio 1
	v_mfma_f32_16x16x32_bf16 v[44:47], v[180:183], v[196:199], 0
	v_mfma_f32_16x16x32_bf16 v[40:43], v[188:191], v[196:199], 0
	v_mfma_f32_16x16x32_bf16 v[28:31], v[180:183], v[204:207], 0
	v_mfma_f32_16x16x32_bf16 v[24:27], v[188:191], v[204:207], 0
	v_mfma_f32_16x16x32_bf16 v[12:15], v[180:183], v[212:215], 0
	v_mfma_f32_16x16x32_bf16 v[8:11], v[188:191], v[212:215], 0
	v_mfma_f32_16x16x32_bf16 v[4:7], v[180:183], v[220:223], 0
	v_mfma_f32_16x16x32_bf16 v[0:3], v[188:191], v[220:223], 0
	v_mfma_f32_16x16x32_bf16 v[44:47], v[184:187], v[200:203], v[44:47]
	v_mfma_f32_16x16x32_bf16 v[40:43], v[192:195], v[200:203], v[40:43]
	v_mfma_f32_16x16x32_bf16 v[28:31], v[184:187], v[208:211], v[28:31]
	v_mfma_f32_16x16x32_bf16 v[24:27], v[192:195], v[208:211], v[24:27]
	v_mfma_f32_16x16x32_bf16 v[12:15], v[184:187], v[216:219], v[12:15]
	v_mfma_f32_16x16x32_bf16 v[8:11], v[192:195], v[216:219], v[8:11]
	v_mfma_f32_16x16x32_bf16 v[4:7], v[184:187], v[224:227], v[4:7]
	v_mfma_f32_16x16x32_bf16 v[0:3], v[192:195], v[224:227], v[0:3]
	s_setprio 0
	s_barrier
	s_branch .Lgemm_join_883

; #define PG8_STAGE(bufoff, gbase, voff) do { _Pragma("unroll") for (int _i = 0; _i < 2; ++_i) \
;         __builtin_amdgcn_global_load_lds((const unsigned*)((const char*)(gbase) + (voff)[_i]), (LAS unsigned*)(lds + (bufoff) + ldsw + _i * 8192), 16, 0, 0); } while (0)
; #define PG8_LDA(dst, b, h) do { _Pragma("unroll") for (int m = 0; m < 4; ++m) _Pragma("unroll") for (int k = 0; k < 2; ++k) dst[m][k] = *(const LAS bf16x8*)(lds + PG8_SA(b, h) + aoff + m * 2048 + k * 1024); } while (0)
; #define PG8_LDB(dst, b, h) do { _Pragma("unroll") for (int n = 0; n < 2; ++n) _Pragma("unroll") for (int k = 0; k < 2; ++k) dst[n][k] = *(const LAS bf16x8*)(lds + PG8_SB(b, h) + boff + n * 2048 + k * 1024); } while (0)
; #define PG8_MMA(ai, bj, At, Bt) do { __builtin_amdgcn_s_setprio(1); _Pragma("unroll") for (int m = 0; m < 4; ++m) _Pragma("unroll") for (int n = 0; n < 2; ++n) _Pragma("unroll") for (int k = 0; k < 2; ++k) \
;         acc[ai][bj][m][n] = __builtin_amdgcn_mfma_f32_16x16x32_bf16(Bt[n][k], At[m][k], acc[ai][bj][m][n], 0, 0, 0); __builtin_amdgcn_s_setprio(0); } while (0)
; #define PG8_WAIT_V(n) asm volatile("s_waitcnt vmcnt(" #n ")" ::: "memory")
; #define PG8_WAIT_L(n) asm volatile("s_waitcnt lgkmcnt(" #n ")" ::: "memory")
; #define PG8_BAR __builtin_amdgcn_s_barrier()
; #define PG8_SCHED __builtin_amdgcn_sched_barrier(0)
; template <class Epi, class Sched, bool ALIGN_EPI>
; __device__ __forceinline__ void gemm_phase(LAS unsigned char* lds, const int wid, const int lda_, const int ldb_, const int K_, const Sched& S, const Epi& E) {
;     ...
;             PG8_LDB(B0, 1, 0); PG8_LDB(B1, 1, 1); PG8_SCHED; PG8_LDA(At, 1, 0); PG8_STAGE(PG8_SA(0, 1), a2 + hstepA, voffA);
;             PG8_WAIT_V(8); PG8_WAIT_L(0); PG8_BAR; PG8_MMA(0, 0, At, B0); PG8_MMA(0, 1, At, B1); PG8_BAR; PG8_SCHED;
;             PG8_LDA(At, 1, 1); PG8_STAGE(PG8_SB(1, 0), b3, voffB); PG8_STAGE(PG8_SB(1, 1), b3 + hstepB, voffB); PG8_STAGE(PG8_SA(1, 0), a3, voffA);
;             PG8_WAIT_V(8); PG8_WAIT_L(0); PG8_BAR; PG8_MMA(1, 0, At, B0); PG8_MMA(1, 1, At, B1); PG8_BAR; PG8_SCHED;
.Lgemm_join_883:
	s_add_i32 s17, 0, 0x18000
	v_add_u32_e32 v141, s17, v135
	s_add_i32 s27, 0, 0x1c000
	ds_read_b128 v[160:163], v141
	ds_read_b128 v[164:167], v141 offset:1024
	ds_read_b128 v[168:171], v141 offset:2048
	ds_read_b128 v[172:175], v141 offset:3072
	v_add_u32_e32 v141, s27, v135
	ds_read_b128 v[180:183], v141
	ds_read_b128 v[184:187], v141 offset:1024
	ds_read_b128 v[188:191], v141 offset:2048
	ds_read_b128 v[192:195], v141 offset:3072
	s_add_u32 s42, s50, s0
	s_addc_u32 s43, s51, s1
	s_mov_b32 m0, s7
	v_lshl_add_u64 v[248:249], s[42:43], 0, v[128:129]
	ds_read_b128 v[196:199], v139 offset:32768
	ds_read_b128 v[200:203], v139 offset:33792
	ds_read_b128 v[204:207], v139 offset:34816
	ds_read_b128 v[208:211], v139 offset:35840
	ds_read_b128 v[212:215], v139 offset:36864
	ds_read_b128 v[216:219], v139 offset:37888
	ds_read_b128 v[220:223], v139 offset:38912
	ds_read_b128 v[224:227], v139 offset:39936
	global_load_lds_dwordx4 v[248:249], off
	v_lshl_add_u64 v[248:249], s[42:43], 0, v[130:131]
	s_mov_b32 m0, s14
	s_nop 0
	global_load_lds_dwordx4 v[248:249], off
	s_waitcnt vmcnt(8)
	s_waitcnt lgkmcnt(0)
	s_barrier
	s_setprio 1
	s_waitcnt lgkmcnt(0)
	v_mfma_f32_16x16x32_bf16 v[124:127], v[160:163], v[196:199], v[124:127]
	v_mfma_f32_16x16x32_bf16 v[120:123], v[168:171], v[196:199], v[120:123]
	v_mfma_f32_16x16x32_bf16 v[116:119], v[160:163], v[204:207], v[116:119]
	v_mfma_f32_16x16x32_bf16 v[112:115], v[168:171], v[204:207], v[112:115]
	v_mfma_f32_16x16x32_bf16 v[100:103], v[160:163], v[212:215], v[100:103]
	v_mfma_f32_16x16x32_bf16 v[96:99], v[168:171], v[212:215], v[96:99]
	v_mfma_f32_16x16x32_bf16 v[84:87], v[160:163], v[220:223], v[84:87]
	v_mfma_f32_16x16x32_bf16 v[80:83], v[168:171], v[220:223], v[80:83]
	v_mfma_f32_16x16x32_bf16 v[124:127], v[164:167], v[200:203], v[124:127]
	v_mfma_f32_16x16x32_bf16 v[120:123], v[172:175], v[200:203], v[120:123]
	v_mfma_f32_16x16x32_bf16 v[116:119], v[164:167], v[208:211], v[116:119]
	v_mfma_f32_16x16x32_bf16 v[112:115], v[172:175], v[208:211], v[112:115]
	v_mfma_f32_16x16x32_bf16 v[100:103], v[164:167], v[216:219], v[100:103]
	v_mfma_f32_16x16x32_bf16 v[96:99], v[172:175], v[216:219], v[96:99]
	v_mfma_f32_16x16x32_bf16 v[84:87], v[164:167], v[224:227], v[84:87]
	v_mfma_f32_16x16x32_bf16 v[80:83], v[172:175], v[224:227], v[80:83]
	s_setprio 0
	s_setprio 1
	v_mfma_f32_16x16x32_bf16 v[108:111], v[180:183], v[196:199], v[108:111]
	v_mfma_f32_16x16x32_bf16 v[104:107], v[188:191], v[196:199], v[104:107]
	v_mfma_f32_16x16x32_bf16 v[92:95], v[180:183], v[204:207], v[92:95]
	v_mfma_f32_16x16x32_bf16 v[88:91], v[188:191], v[204:207], v[88:91]
	v_mfma_f32_16x16x32_bf16 v[76:79], v[180:183], v[212:215], v[76:79]
	v_mfma_f32_16x16x32_bf16 v[72:75], v[188:191], v[212:215], v[72:75]
	v_mfma_f32_16x16x32_bf16 v[68:71], v[180:183], v[220:223], v[68:71]
	v_mfma_f32_16x16x32_bf16 v[64:67], v[188:191], v[220:223], v[64:67]
	v_mfma_f32_16x16x32_bf16 v[108:111], v[184:187], v[200:203], v[108:111]
	v_mfma_f32_16x16x32_bf16 v[104:107], v[192:195], v[200:203], v[104:107]
	v_mfma_f32_16x16x32_bf16 v[92:95], v[184:187], v[208:211], v[92:95]
	v_mfma_f32_16x16x32_bf16 v[88:91], v[192:195], v[208:211], v[88:91]
	v_mfma_f32_16x16x32_bf16 v[76:79], v[184:187], v[216:219], v[76:79]
	v_mfma_f32_16x16x32_bf16 v[72:75], v[192:195], v[216:219], v[72:75]
	v_mfma_f32_16x16x32_bf16 v[68:71], v[184:187], v[224:227], v[68:71]
	v_mfma_f32_16x16x32_bf16 v[64:67], v[192:195], v[224:227], v[64:67]
	s_setprio 0
	s_barrier
	s_add_i32 s17, s17, s3
	v_lshl_add_u64 v[228:229], v[228:229], 0, s[24:25]
	s_mov_b32 m0, s17
	ds_read_b128 v[196:199], v139 offset:49152
	ds_read_b128 v[200:203], v139 offset:50176
	ds_read_b128 v[204:207], v139 offset:51200
	ds_read_b128 v[208:211], v139 offset:52224
	ds_read_b128 v[212:215], v139 offset:53248
	ds_read_b128 v[216:219], v139 offset:54272
	ds_read_b128 v[220:223], v139 offset:55296
	ds_read_b128 v[224:227], v139 offset:56320
	global_load_lds_dwordx4 v[228:229], off
	v_lshl_add_u64 v[228:229], v[230:231], 0, s[24:25]
	s_add_i32 m0, s17, 0x2000
	s_add_i32 s17, s27, s3
	global_load_lds_dwordx4 v[228:229], off
	v_lshl_add_u64 v[228:229], v[232:233], 0, s[24:25]
	s_mov_b32 m0, s17
	s_nop 0
	global_load_lds_dwordx4 v[228:229], off
	v_lshl_add_u64 v[228:229], v[234:235], 0, s[24:25]
	s_add_i32 m0, s17, 0x2000
	s_nop 0
	global_load_lds_dwordx4 v[228:229], off
	v_lshl_add_u64 v[228:229], v[236:237], 0, s[24:25]
	s_mov_b32 m0, s15
	s_nop 0
	global_load_lds_dwordx4 v[228:229], off
	v_lshl_add_u64 v[228:229], v[246:247], 0, s[24:25]
	s_mov_b32 m0, s26
	s_nop 0
	global_load_lds_dwordx4 v[228:229], off
	s_waitcnt vmcnt(8)
	s_waitcnt lgkmcnt(0)
	s_barrier
; __device__ __forceinline__ unsigned cvt_pk_bf16(float lo, float hi) { const f32x2 v = {lo, hi}; return __builtin_bit_cast(unsigned, __builtin_convertvector(v, bf16x2_t)); }
; #define PG8_MMA(ai, bj, At, Bt) do { __builtin_amdgcn_s_setprio(1); _Pragma("unroll") for (int m = 0; m < 4; ++m) _Pragma("unroll") for (int n = 0; n < 2; ++n) _Pragma("unroll") for (int k = 0; k < 2; ++k) \
;         acc[ai][bj][m][n] = __builtin_amdgcn_mfma_f32_16x16x32_bf16(Bt[n][k], At[m][k], acc[ai][bj][m][n], 0, 0, 0); __builtin_amdgcn_s_setprio(0); } while (0)
; #define PG8_WAIT_V(n) asm volatile("s_waitcnt vmcnt(" #n ")" ::: "memory")
; #define PG8_WAIT_L(n) asm volatile("s_waitcnt lgkmcnt(" #n ")" ::: "memory")
; #define PG8_BAR __builtin_amdgcn_s_barrier()
; #define PG8_SCHED __builtin_amdgcn_sched_barrier(0)
;     template <class Sched> __device__ __forceinline__ void operator()(const f32x4 (&acc)[2][2][4][2], const Unit& u, const Sched& S, int wr, int wc, int fr, int fq) const {
;     ...
;                 for (int m = 0; m < 4; ++m) { bf16_t* rowp = base + (size_t)(rl0 + ai * HALF + m * 16) * ldo + cl0;
; #pragma unroll
;                     for (int bj = 0; bj < 2; ++bj) { const f32x4 v0 = acc[ai][bj][m][0], v1 = acc[ai][bj][m][1];
;                         u32x4 w; w.x = cvt_pk_bf16(v0[0], v0[1]); w.y = cvt_pk_bf16(v0[2], v0[3]); w.z = cvt_pk_bf16(v1[0], v1[1]); w.w = cvt_pk_bf16(v1[2], v1[3]);
;                         *(u32x4*)(rowp + bj * HALF) = w; } }
; template <class Epi, class Sched, bool ALIGN_EPI>
; __device__ __forceinline__ void gemm_phase(LAS unsigned char* lds, const int wid, const int lda_, const int ldb_, const int K_, const Sched& S, const Epi& E) {
;     ...
;             PG8_WAIT_V(8); PG8_WAIT_L(0); PG8_BAR; PG8_MMA(1, 0, At, B0); PG8_MMA(1, 1, At, B1); PG8_BAR; PG8_SCHED;
;         }
;         if constexpr (ALIGN_EPI) { if (wr == 0) PG8_BAR; }
;         E(acc, cur, S, wr, wc, fr, fq);
;         if (!has_next) break;
	s_setprio 1
	s_waitcnt lgkmcnt(0)
	v_mfma_f32_16x16x32_bf16 v[60:63], v[160:163], v[196:199], v[60:63]
	v_mfma_f32_16x16x32_bf16 v[56:59], v[168:171], v[196:199], v[56:59]
	v_mfma_f32_16x16x32_bf16 v[52:55], v[160:163], v[204:207], v[52:55]
	v_mfma_f32_16x16x32_bf16 v[48:51], v[168:171], v[204:207], v[48:51]
	v_mfma_f32_16x16x32_bf16 v[36:39], v[160:163], v[212:215], v[36:39]
	v_mfma_f32_16x16x32_bf16 v[32:35], v[168:171], v[212:215], v[32:35]
	v_mfma_f32_16x16x32_bf16 v[20:23], v[160:163], v[220:223], v[20:23]
	v_mfma_f32_16x16x32_bf16 v[16:19], v[168:171], v[220:223], v[16:19]
	v_mfma_f32_16x16x32_bf16 v[60:63], v[164:167], v[200:203], v[60:63]
	v_mfma_f32_16x16x32_bf16 v[56:59], v[172:175], v[200:203], v[56:59]
	v_mfma_f32_16x16x32_bf16 v[52:55], v[164:167], v[208:211], v[52:55]
	v_mfma_f32_16x16x32_bf16 v[48:51], v[172:175], v[208:211], v[48:51]
	v_mfma_f32_16x16x32_bf16 v[36:39], v[164:167], v[216:219], v[36:39]
	v_mfma_f32_16x16x32_bf16 v[32:35], v[172:175], v[216:219], v[32:35]
	v_mfma_f32_16x16x32_bf16 v[20:23], v[164:167], v[224:227], v[20:23]
	v_mfma_f32_16x16x32_bf16 v[16:19], v[172:175], v[224:227], v[16:19]
	s_setprio 0
	s_setprio 1
	v_mfma_f32_16x16x32_bf16 v[44:47], v[180:183], v[196:199], v[44:47]
	v_mfma_f32_16x16x32_bf16 v[40:43], v[188:191], v[196:199], v[40:43]
	v_mfma_f32_16x16x32_bf16 v[28:31], v[180:183], v[204:207], v[28:31]
	v_mfma_f32_16x16x32_bf16 v[24:27], v[188:191], v[204:207], v[24:27]
	v_mfma_f32_16x16x32_bf16 v[12:15], v[180:183], v[212:215], v[12:15]
	v_mfma_f32_16x16x32_bf16 v[8:11], v[188:191], v[212:215], v[8:11]
	v_mfma_f32_16x16x32_bf16 v[4:7], v[180:183], v[220:223], v[4:7]
	v_mfma_f32_16x16x32_bf16 v[0:3], v[188:191], v[220:223], v[0:3]
	v_mfma_f32_16x16x32_bf16 v[44:47], v[184:187], v[200:203], v[44:47]
	v_mfma_f32_16x16x32_bf16 v[40:43], v[192:195], v[200:203], v[40:43]
	v_mfma_f32_16x16x32_bf16 v[28:31], v[184:187], v[208:211], v[28:31]
	v_mfma_f32_16x16x32_bf16 v[24:27], v[192:195], v[208:211], v[24:27]
	v_mfma_f32_16x16x32_bf16 v[12:15], v[184:187], v[216:219], v[12:15]
	v_mfma_f32_16x16x32_bf16 v[8:11], v[192:195], v[216:219], v[8:11]
	v_mfma_f32_16x16x32_bf16 v[4:7], v[184:187], v[224:227], v[4:7]
	v_mfma_f32_16x16x32_bf16 v[0:3], v[192:195], v[224:227], v[0:3]
	s_setprio 0
	s_barrier
	s_add_i32 s73, s73, 2
	s_add_u32 s48, s48, 0x100
	s_addc_u32 s49, s49, 0
	s_cmp_gt_u32 s73, 5
	s_cbranch_scc0 .LBB0_883
	s_lshl_b32 s4, s41, 8
	s_and_b32 s5, s4, 0xfffff800
	s_and_b32 s17, s41, 7
	s_or_b32 s17, s5, s17
	s_ashr_i32 s5, s17, 31
	s_cmp_lt_i32 s41, 64
	s_cselect_b32 s4, s17, s4
	s_movk_i32 s17, 0x800
	s_cselect_b32 s5, s5, 0
	s_cselect_b32 s17, 0x4000, s17
	s_ashr_i32 s41, s40, 31
	s_lshl_b64 s[40:41], s[40:41], 9
	s_lshl_b64 s[4:5], s[4:5], 12
	v_readlane_b32 s27, v254, 19
	s_add_u32 s4, s27, s4
	v_readlane_b32 s27, v254, 20
	s_addc_u32 s5, s27, s5
	s_add_u32 s4, s4, s40
	s_addc_u32 s5, s5, s41
	v_lshl_add_u64 v[156:157], v[136:137], 1, s[4:5]
	v_mad_i64_i32 v[158:159], s[4:5], s17, v134, 0
	v_lshl_add_u64 v[158:159], v[158:159], 1, v[156:157]
	v_cvt_pk_bf16_f32 v108, v108, v109
	v_cvt_pk_bf16_f32 v109, v110, v111
	v_cvt_pk_bf16_f32 v110, v104, v105
	v_cvt_pk_bf16_f32 v111, v106, v107
	v_mad_i64_i32 v[104:105], s[4:5], s17, v138, 0
	v_cvt_pk_bf16_f32 v124, v124, v125
	v_cvt_pk_bf16_f32 v125, v126, v127
	v_cvt_pk_bf16_f32 v126, v120, v121
	v_cvt_pk_bf16_f32 v127, v122, v123
	global_store_dwordx4 v[158:159], v[108:111], off offset:256
	v_cvt_pk_bf16_f32 v92, v92, v93
	v_cvt_pk_bf16_f32 v93, v94, v95
	v_lshl_add_u64 v[108:109], v[104:105], 1, v[156:157]
	v_cvt_pk_bf16_f32 v94, v88, v89
	v_cvt_pk_bf16_f32 v95, v90, v91
	v_mad_i64_i32 v[88:89], s[4:5], s17, v140, 0
	global_store_dwordx4 v[158:159], v[124:127], off
	v_cvt_pk_bf16_f32 v104, v116, v117
	v_cvt_pk_bf16_f32 v105, v118, v119
	v_cvt_pk_bf16_f32 v106, v112, v113
	v_cvt_pk_bf16_f32 v107, v114, v115
	global_store_dwordx4 v[108:109], v[92:95], off offset:256
	v_cvt_pk_bf16_f32 v76, v76, v77
	v_cvt_pk_bf16_f32 v77, v78, v79
	v_lshl_add_u64 v[92:93], v[88:89], 1, v[156:157]
	v_cvt_pk_bf16_f32 v78, v72, v73
	v_cvt_pk_bf16_f32 v79, v74, v75
	v_mad_i64_i32 v[72:73], s[4:5], s17, v142, 0
	v_cvt_pk_bf16_f32 v68, v68, v69
	v_cvt_pk_bf16_f32 v69, v70, v71
	v_cvt_pk_bf16_f32 v70, v64, v65
	v_mad_i64_i32 v[64:65], s[4:5], s17, v144, 0
	global_store_dwordx4 v[108:109], v[104:107], off
	v_cvt_pk_bf16_f32 v88, v100, v101
	v_cvt_pk_bf16_f32 v89, v102, v103
	v_cvt_pk_bf16_f32 v90, v96, v97
	v_cvt_pk_bf16_f32 v91, v98, v99
	global_store_dwordx4 v[92:93], v[76:79], off offset:256
	v_cvt_pk_bf16_f32 v74, v80, v81
	v_cvt_pk_bf16_f32 v75, v82, v83
	v_lshl_add_u64 v[76:77], v[72:73], 1, v[156:157]
	v_cvt_pk_bf16_f32 v72, v84, v85
	v_cvt_pk_bf16_f32 v73, v86, v87
	v_cvt_pk_bf16_f32 v71, v66, v67
	v_lshl_add_u64 v[64:65], v[64:65], 1, v[156:157]
	v_cvt_pk_bf16_f32 v44, v44, v45
	v_cvt_pk_bf16_f32 v45, v46, v47
	v_cvt_pk_bf16_f32 v46, v40, v41
	v_cvt_pk_bf16_f32 v47, v42, v43
	v_mad_i64_i32 v[40:41], s[4:5], s17, v146, 0
	global_store_dwordx4 v[92:93], v[88:91], off
	global_store_dwordx4 v[76:77], v[72:75], off
	global_store_dwordx4 v[76:77], v[68:71], off offset:256
	v_cvt_pk_bf16_f32 v60, v60, v61
	v_cvt_pk_bf16_f32 v61, v62, v63
	v_cvt_pk_bf16_f32 v62, v56, v57
	v_cvt_pk_bf16_f32 v63, v58, v59
	global_store_dwordx4 v[64:65], v[44:47], off offset:256
	v_cvt_pk_bf16_f32 v28, v28, v29
	v_cvt_pk_bf16_f32 v29, v30, v31
	v_lshl_add_u64 v[44:45], v[40:41], 1, v[156:157]
	v_cvt_pk_bf16_f32 v30, v24, v25
	v_cvt_pk_bf16_f32 v31, v26, v27
	v_mad_i64_i32 v[24:25], s[4:5], s17, v148, 0
	global_store_dwordx4 v[64:65], v[60:63], off
	v_cvt_pk_bf16_f32 v40, v52, v53
	v_cvt_pk_bf16_f32 v41, v54, v55
	v_cvt_pk_bf16_f32 v42, v48, v49
	v_cvt_pk_bf16_f32 v43, v50, v51
	global_store_dwordx4 v[44:45], v[28:31], off offset:256
	v_cvt_pk_bf16_f32 v12, v12, v13
	v_cvt_pk_bf16_f32 v13, v14, v15
	v_lshl_add_u64 v[28:29], v[24:25], 1, v[156:157]
	v_cvt_pk_bf16_f32 v14, v8, v9
	v_cvt_pk_bf16_f32 v15, v10, v11
	v_mad_i64_i32 v[8:9], s[4:5], s17, v150, 0
	global_store_dwordx4 v[44:45], v[40:43], off
	v_cvt_pk_bf16_f32 v24, v36, v37
	v_cvt_pk_bf16_f32 v25, v38, v39
	v_cvt_pk_bf16_f32 v26, v32, v33
	v_cvt_pk_bf16_f32 v27, v34, v35
	global_store_dwordx4 v[28:29], v[12:15], off offset:256
	v_cvt_pk_bf16_f32 v10, v16, v17
	v_cvt_pk_bf16_f32 v11, v18, v19
	v_lshl_add_u64 v[12:13], v[8:9], 1, v[156:157]
	v_cvt_pk_bf16_f32 v8, v20, v21
	v_cvt_pk_bf16_f32 v9, v22, v23
	v_cvt_pk_bf16_f32 v4, v4, v5
	v_cvt_pk_bf16_f32 v5, v6, v7
	v_cvt_pk_bf16_f32 v6, v0, v1
	v_cvt_pk_bf16_f32 v7, v2, v3
	s_and_b64 vcc, exec, s[36:37]
	s_mov_b32 s40, s30
	s_mov_b32 s41, s34
	s_mov_b64 s[48:49], s[38:39]
	s_mov_b64 s[46:47], s[44:45]
	global_store_dwordx4 v[28:29], v[24:27], off
	global_store_dwordx4 v[12:13], v[8:11], off
	global_store_dwordx4 v[12:13], v[4:7], off offset:256
	s_cbranch_vccz .LBB0_868
	v_readlane_b32 s0, v253, 1
	s_waitcnt vmcnt(0)
	v_readlane_b32 s1, v253, 2
	v_readlane_b32 s72, v255, 28
	s_andn2_b64 vcc, exec, s[0:1]
	v_readlane_b32 s73, v255, 29
	s_cbranch_vccnz .LBB0_887
	s_barrier

; #define PG8_STAGE(bufoff, gbase, voff) do { _Pragma("unroll") for (int _i = 0; _i < 2; ++_i) \
;         __builtin_amdgcn_global_load_lds((const unsigned*)((const char*)(gbase) + (voff)[_i]), (LAS unsigned*)(lds + (bufoff) + ldsw + _i * 8192), 16, 0, 0); } while (0)
; #define PG8_LDA(dst, b, h) do { _Pragma("unroll") for (int m = 0; m < 4; ++m) _Pragma("unroll") for (int k = 0; k < 2; ++k) dst[m][k] = *(const LAS bf16x8*)(lds + PG8_SA(b, h) + aoff + m * 2048 + k * 1024); } while (0)
; #define PG8_LDB(dst, b, h) do { _Pragma("unroll") for (int n = 0; n < 2; ++n) _Pragma("unroll") for (int k = 0; k < 2; ++k) dst[n][k] = *(const LAS bf16x8*)(lds + PG8_SB(b, h) + boff + n * 2048 + k * 1024); } while (0)
; #define PG8_MMA(ai, bj, At, Bt) do { __builtin_amdgcn_s_setprio(1); _Pragma("unroll") for (int m = 0; m < 4; ++m) _Pragma("unroll") for (int n = 0; n < 2; ++n) _Pragma("unroll") for (int k = 0; k < 2; ++k) \
;         acc[ai][bj][m][n] = __builtin_amdgcn_mfma_f32_16x16x32_bf16(Bt[n][k], At[m][k], acc[ai][bj][m][n], 0, 0, 0); __builtin_amdgcn_s_setprio(0); } while (0)
; #define PG8_WAIT_V(n) asm volatile("s_waitcnt vmcnt(" #n ")" ::: "memory")
; #define PG8_WAIT_L(n) asm volatile("s_waitcnt lgkmcnt(" #n ")" ::: "memory")
; #define PG8_BAR __builtin_amdgcn_s_barrier()
; #define PG8_SCHED __builtin_amdgcn_sched_barrier(0)
; template <class Epi, class Sched, bool ALIGN_EPI>
; __device__ __forceinline__ void gemm_phase(LAS unsigned char* lds, const int wid, const int lda_, const int ldb_, const int K_, const Sched& S, const Epi& E) {
;     ...
;         const bool has_next = S.next(ui + 1, nxt);
;         const int nt = S.nt(cur);
;         const char* nA = has_next ? S.a(nxt) : cA; const char* nB = has_next ? S.b(nxt) : cB;
; #pragma unroll 1
;         for (int t = 0; t < nt; t += 2) {
;             const bool last = (t == nt - 2);
;             const char* a1 = cA + (size_t)(t + 1) * kstep;
;             const char* a2 = last ? nA : cA + (size_t)(t + 2) * kstep; const char* b2 = last ? nB : cB + (size_t)(t + 2) * kstep;
;             const char* a3 = a2 + kstep; const char* b3 = b2 + kstep;
;             PG8_LDB(B0, 0, 0); PG8_LDB(B1, 0, 1); PG8_SCHED; PG8_LDA(At, 0, 0); PG8_STAGE(PG8_SA(1, 1), a1 + hstepA, voffA);
;             PG8_WAIT_V(8); PG8_WAIT_L(0); PG8_BAR; PG8_MMA(0, 0, At, B0); PG8_MMA(0, 1, At, B1); PG8_BAR; PG8_SCHED;
.LBB0_961:
	s_xor_b64 s[36:37], s[4:5], -1
	s_cmp_gt_i32 s48, -1
	s_cselect_b64 s[50:51], -1, 0
	s_cmp_lt_i32 s48, 0
	s_cselect_b32 s45, 32, 8
	s_max_i32 s17, s75, 0
	s_ashr_i32 s35, s34, 31
	s_lshl_b32 s17, s17, 10
	s_lshl_b64 s[38:39], s[34:35], 20
	v_readlane_b32 s27, v254, 19
	s_add_u32 s27, s27, s38
	v_readlane_b32 s31, v254, 20
	s_addc_u32 s31, s31, s39
	s_add_u32 s38, s27, s17
	s_addc_u32 s39, s31, 0
	s_and_b64 s[40:41], s[4:5], exec
	s_cselect_b32 s35, s39, s95
	s_cselect_b32 s47, s38, s94
	s_ashr_i32 s31, s30, 31
	s_lshl_b64 s[40:41], s[30:31], 20
	s_add_u32 s27, s6, s40
	s_addc_u32 s31, s7, s41
	s_add_u32 s40, s27, s17
	s_addc_u32 s41, s31, 0
	s_and_b64 s[4:5], s[4:5], exec
	s_cselect_b32 s4, s41, s97
	s_cselect_b32 s5, s40, s96
	s_add_i32 s31, s45, -2
	s_add_u32 s94, s94, 0x80
	s_addc_u32 s95, s95, 0
	s_add_u32 s49, s96, 0x100
	s_mov_b32 s77, 0
	s_addc_u32 s76, s97, 0
	s_add_i32 s78, s77, 2
	s_add_u32 s17, s94, 0x80
	s_addc_u32 s27, s95, 0
	s_add_i32 s79, 0, 0x10000
	s_cmp_eq_u32 s31, s77
	s_cselect_b32 s97, s35, s27
	s_cselect_b32 s96, s47, s17
	v_add_u32_e32 v141, s79, v135
	s_cselect_b32 s43, s4, s76
	s_cselect_b32 s42, s5, s49
	s_add_i32 s17, 0, 0x14000
	ds_read_b128 v[156:159], v141
	ds_read_b128 v[160:163], v141 offset:1024
	ds_read_b128 v[164:167], v141 offset:2048
	ds_read_b128 v[168:171], v141 offset:3072
	v_add_u32_e32 v141, s17, v135
	ds_read_b128 v[172:175], v141
	ds_read_b128 v[180:183], v141 offset:1024
	ds_read_b128 v[184:187], v141 offset:2048
	ds_read_b128 v[188:191], v141 offset:3072
	v_lshl_add_u64 v[224:225], s[94:95], 0, v[152:153]
	s_add_i32 m0, s16, 0xc000
	ds_read_b128 v[192:195], v139
	ds_read_b128 v[196:199], v139 offset:1024
	ds_read_b128 v[200:203], v139 offset:2048
	ds_read_b128 v[204:207], v139 offset:3072
	ds_read_b128 v[208:211], v139 offset:4096
	ds_read_b128 v[212:215], v139 offset:5120
	ds_read_b128 v[216:219], v139 offset:6144
	ds_read_b128 v[220:223], v139 offset:7168
	global_load_lds_dwordx4 v[224:225], off
	v_lshl_add_u64 v[224:225], s[94:95], 0, v[154:155]
	s_add_i32 m0, s16, 0xe000
	s_nop 0
	global_load_lds_dwordx4 v[224:225], off
	s_waitcnt vmcnt(8)
	s_waitcnt lgkmcnt(0)
	s_barrier
	s_setprio 1
	s_waitcnt lgkmcnt(0)
	v_mfma_f32_16x16x32_bf16 v[124:127], v[156:159], v[192:195], 0
	v_mfma_f32_16x16x32_bf16 v[120:123], v[164:167], v[192:195], 0
	v_mfma_f32_16x16x32_bf16 v[116:119], v[156:159], v[200:203], 0
	v_mfma_f32_16x16x32_bf16 v[112:115], v[164:167], v[200:203], 0
	v_mfma_f32_16x16x32_bf16 v[100:103], v[156:159], v[208:211], 0
	v_mfma_f32_16x16x32_bf16 v[96:99], v[164:167], v[208:211], 0
	v_mfma_f32_16x16x32_bf16 v[84:87], v[156:159], v[216:219], 0
	v_mfma_f32_16x16x32_bf16 v[80:83], v[164:167], v[216:219], 0
	v_mfma_f32_16x16x32_bf16 v[124:127], v[160:163], v[196:199], v[124:127]
	v_mfma_f32_16x16x32_bf16 v[120:123], v[168:171], v[196:199], v[120:123]
	v_mfma_f32_16x16x32_bf16 v[116:119], v[160:163], v[204:207], v[116:119]
	v_mfma_f32_16x16x32_bf16 v[112:115], v[168:171], v[204:207], v[112:115]
	v_mfma_f32_16x16x32_bf16 v[100:103], v[160:163], v[212:215], v[100:103]
	v_mfma_f32_16x16x32_bf16 v[96:99], v[168:171], v[212:215], v[96:99]
	v_mfma_f32_16x16x32_bf16 v[84:87], v[160:163], v[220:223], v[84:87]
	v_mfma_f32_16x16x32_bf16 v[80:83], v[168:171], v[220:223], v[80:83]
	s_setprio 0
	s_setprio 1
	v_mfma_f32_16x16x32_bf16 v[108:111], v[172:175], v[192:195], 0
	v_mfma_f32_16x16x32_bf16 v[104:107], v[184:187], v[192:195], 0
	v_mfma_f32_16x16x32_bf16 v[92:95], v[172:175], v[200:203], 0
	v_mfma_f32_16x16x32_bf16 v[88:91], v[184:187], v[200:203], 0
	v_mfma_f32_16x16x32_bf16 v[76:79], v[172:175], v[208:211], 0
	v_mfma_f32_16x16x32_bf16 v[72:75], v[184:187], v[208:211], 0
	v_mfma_f32_16x16x32_bf16 v[68:71], v[172:175], v[216:219], 0
	v_mfma_f32_16x16x32_bf16 v[64:67], v[184:187], v[216:219], 0
	v_mfma_f32_16x16x32_bf16 v[108:111], v[180:183], v[196:199], v[108:111]
	v_mfma_f32_16x16x32_bf16 v[104:107], v[188:191], v[196:199], v[104:107]
	v_mfma_f32_16x16x32_bf16 v[92:95], v[180:183], v[204:207], v[92:95]
	v_mfma_f32_16x16x32_bf16 v[88:91], v[188:191], v[204:207], v[88:91]
	v_mfma_f32_16x16x32_bf16 v[76:79], v[180:183], v[212:215], v[76:79]
	v_mfma_f32_16x16x32_bf16 v[72:75], v[188:191], v[212:215], v[72:75]
	v_mfma_f32_16x16x32_bf16 v[68:71], v[180:183], v[220:223], v[68:71]
	v_mfma_f32_16x16x32_bf16 v[64:67], v[188:191], v[220:223], v[64:67]
	s_setprio 0
	s_barrier
; #define PG8_STAGE(bufoff, gbase, voff) do { _Pragma("unroll") for (int _i = 0; _i < 2; ++_i) \
;         __builtin_amdgcn_global_load_lds((const unsigned*)((const char*)(gbase) + (voff)[_i]), (LAS unsigned*)(lds + (bufoff) + ldsw + _i * 8192), 16, 0, 0); } while (0)
; #define PG8_LDA(dst, b, h) do { _Pragma("unroll") for (int m = 0; m < 4; ++m) _Pragma("unroll") for (int k = 0; k < 2; ++k) dst[m][k] = *(const LAS bf16x8*)(lds + PG8_SA(b, h) + aoff + m * 2048 + k * 1024); } while (0)
; #define PG8_MMA(ai, bj, At, Bt) do { __builtin_amdgcn_s_setprio(1); _Pragma("unroll") for (int m = 0; m < 4; ++m) _Pragma("unroll") for (int n = 0; n < 2; ++n) _Pragma("unroll") for (int k = 0; k < 2; ++k) \
;         acc[ai][bj][m][n] = __builtin_amdgcn_mfma_f32_16x16x32_bf16(Bt[n][k], At[m][k], acc[ai][bj][m][n], 0, 0, 0); __builtin_amdgcn_s_setprio(0); } while (0)
; #define PG8_WAIT_V(n) asm volatile("s_waitcnt vmcnt(" #n ")" ::: "memory")
; #define PG8_WAIT_L(n) asm volatile("s_waitcnt lgkmcnt(" #n ")" ::: "memory")
; #define PG8_BAR __builtin_amdgcn_s_barrier()
; #define PG8_SCHED __builtin_amdgcn_sched_barrier(0)
; template <class Epi, class Sched, bool ALIGN_EPI>
; __device__ __forceinline__ void gemm_phase(LAS unsigned char* lds, const int wid, const int lda_, const int ldb_, const int K_, const Sched& S, const Epi& E) {
;     ...
;             PG8_LDA(At, 0, 1); PG8_STAGE(PG8_SB(0, 0), b2, voffB); PG8_STAGE(PG8_SB(0, 1), b2 + hstepB, voffB); PG8_STAGE(PG8_SA(0, 0), a2, voffA);
;             PG8_WAIT_V(8); PG8_WAIT_L(0); PG8_BAR; PG8_MMA(1, 0, At, B0); PG8_MMA(1, 1, At, B1); PG8_BAR; PG8_SCHED;
	s_add_i32 s27, s79, s3
	v_lshl_add_u64 v[224:225], s[42:43], 0, v[176:177]
	s_mov_b32 m0, s27
	ds_read_b128 v[192:195], v139 offset:16384
	ds_read_b128 v[196:199], v139 offset:17408
	ds_read_b128 v[200:203], v139 offset:18432
	ds_read_b128 v[204:207], v139 offset:19456
	ds_read_b128 v[208:211], v139 offset:20480
	ds_read_b128 v[212:215], v139 offset:21504
	ds_read_b128 v[216:219], v139 offset:22528
	ds_read_b128 v[220:223], v139 offset:23552
	global_load_lds_dwordx4 v[224:225], off
	s_add_i32 m0, s27, 0x2000
	v_lshl_add_u64 v[226:227], s[42:43], 0, v[128:129]
	s_add_u32 s42, s42, s10
	s_addc_u32 s43, s43, s11
	s_add_i32 s17, s17, s3
	global_load_lds_dwordx4 v[226:227], off
	v_lshl_add_u64 v[228:229], s[42:43], 0, v[176:177]
	s_mov_b32 m0, s17
	v_lshl_add_u64 v[230:231], s[42:43], 0, v[128:129]
	global_load_lds_dwordx4 v[228:229], off
	s_add_i32 m0, s17, 0x2000
	v_lshl_add_u64 v[232:233], s[96:97], 0, v[132:133]
	global_load_lds_dwordx4 v[230:231], off
	s_mov_b32 m0, s16
	v_lshl_add_u64 v[234:235], s[96:97], 0, v[130:131]
	global_load_lds_dwordx4 v[232:233], off
	s_mov_b32 m0, s14
	s_nop 0
	global_load_lds_dwordx4 v[234:235], off
	s_waitcnt vmcnt(8)
	s_waitcnt lgkmcnt(0)
	s_barrier
	s_setprio 1
	s_waitcnt lgkmcnt(0)
	v_mfma_f32_16x16x32_bf16 v[60:63], v[156:159], v[192:195], 0
	v_mfma_f32_16x16x32_bf16 v[56:59], v[164:167], v[192:195], 0
	v_mfma_f32_16x16x32_bf16 v[52:55], v[156:159], v[200:203], 0
	v_mfma_f32_16x16x32_bf16 v[48:51], v[164:167], v[200:203], 0
	v_mfma_f32_16x16x32_bf16 v[36:39], v[156:159], v[208:211], 0
	v_mfma_f32_16x16x32_bf16 v[32:35], v[164:167], v[208:211], 0
	v_mfma_f32_16x16x32_bf16 v[20:23], v[156:159], v[216:219], 0
	v_mfma_f32_16x16x32_bf16 v[16:19], v[164:167], v[216:219], 0
	v_mfma_f32_16x16x32_bf16 v[60:63], v[160:163], v[196:199], v[60:63]
	v_mfma_f32_16x16x32_bf16 v[56:59], v[168:171], v[196:199], v[56:59]
	v_mfma_f32_16x16x32_bf16 v[52:55], v[160:163], v[204:207], v[52:55]
	v_mfma_f32_16x16x32_bf16 v[48:51], v[168:171], v[204:207], v[48:51]
	v_mfma_f32_16x16x32_bf16 v[36:39], v[160:163], v[212:215], v[36:39]
	v_mfma_f32_16x16x32_bf16 v[32:35], v[168:171], v[212:215], v[32:35]
	v_mfma_f32_16x16x32_bf16 v[20:23], v[160:163], v[220:223], v[20:23]
	v_mfma_f32_16x16x32_bf16 v[16:19], v[168:171], v[220:223], v[16:19]
	s_setprio 0
	s_setprio 1
	v_mfma_f32_16x16x32_bf16 v[44:47], v[172:175], v[192:195], 0
	v_mfma_f32_16x16x32_bf16 v[40:43], v[184:187], v[192:195], 0
	v_mfma_f32_16x16x32_bf16 v[28:31], v[172:175], v[200:203], 0
	v_mfma_f32_16x16x32_bf16 v[24:27], v[184:187], v[200:203], 0
	v_mfma_f32_16x16x32_bf16 v[12:15], v[172:175], v[208:211], 0
	v_mfma_f32_16x16x32_bf16 v[8:11], v[184:187], v[208:211], 0
	v_mfma_f32_16x16x32_bf16 v[4:7], v[172:175], v[216:219], 0
	v_mfma_f32_16x16x32_bf16 v[0:3], v[184:187], v[216:219], 0
	v_mfma_f32_16x16x32_bf16 v[44:47], v[180:183], v[196:199], v[44:47]
	v_mfma_f32_16x16x32_bf16 v[40:43], v[188:191], v[196:199], v[40:43]
	v_mfma_f32_16x16x32_bf16 v[28:31], v[180:183], v[204:207], v[28:31]
	v_mfma_f32_16x16x32_bf16 v[24:27], v[188:191], v[204:207], v[24:27]
	v_mfma_f32_16x16x32_bf16 v[12:15], v[180:183], v[212:215], v[12:15]
	v_mfma_f32_16x16x32_bf16 v[8:11], v[188:191], v[212:215], v[8:11]
	v_mfma_f32_16x16x32_bf16 v[4:7], v[180:183], v[220:223], v[4:7]
	v_mfma_f32_16x16x32_bf16 v[0:3], v[188:191], v[220:223], v[0:3]
	s_setprio 0
	s_barrier
	s_branch .Lgemm_join_962

; #define PG8_STAGE(bufoff, gbase, voff) do { _Pragma("unroll") for (int _i = 0; _i < 2; ++_i) \
;         __builtin_amdgcn_global_load_lds((const unsigned*)((const char*)(gbase) + (voff)[_i]), (LAS unsigned*)(lds + (bufoff) + ldsw + _i * 8192), 16, 0, 0); } while (0)
; #define PG8_LDA(dst, b, h) do { _Pragma("unroll") for (int m = 0; m < 4; ++m) _Pragma("unroll") for (int k = 0; k < 2; ++k) dst[m][k] = *(const LAS bf16x8*)(lds + PG8_SA(b, h) + aoff + m * 2048 + k * 1024); } while (0)
; #define PG8_LDB(dst, b, h) do { _Pragma("unroll") for (int n = 0; n < 2; ++n) _Pragma("unroll") for (int k = 0; k < 2; ++k) dst[n][k] = *(const LAS bf16x8*)(lds + PG8_SB(b, h) + boff + n * 2048 + k * 1024); } while (0)
; #define PG8_MMA(ai, bj, At, Bt) do { __builtin_amdgcn_s_setprio(1); _Pragma("unroll") for (int m = 0; m < 4; ++m) _Pragma("unroll") for (int n = 0; n < 2; ++n) _Pragma("unroll") for (int k = 0; k < 2; ++k) \
;         acc[ai][bj][m][n] = __builtin_amdgcn_mfma_f32_16x16x32_bf16(Bt[n][k], At[m][k], acc[ai][bj][m][n], 0, 0, 0); __builtin_amdgcn_s_setprio(0); } while (0)
; #define PG8_WAIT_V(n) asm volatile("s_waitcnt vmcnt(" #n ")" ::: "memory")
; #define PG8_WAIT_L(n) asm volatile("s_waitcnt lgkmcnt(" #n ")" ::: "memory")
; #define PG8_BAR __builtin_amdgcn_s_barrier()
; #define PG8_SCHED __builtin_amdgcn_sched_barrier(0)
; template <class Epi, class Sched, bool ALIGN_EPI>
; __device__ __forceinline__ void gemm_phase(LAS unsigned char* lds, const int wid, const int lda_, const int ldb_, const int K_, const Sched& S, const Epi& E) {
;     ...
;             PG8_LDB(B0, 1, 0); PG8_LDB(B1, 1, 1); PG8_SCHED; PG8_LDA(At, 1, 0); PG8_STAGE(PG8_SA(0, 1), a2 + hstepA, voffA);
;             PG8_WAIT_V(8); PG8_WAIT_L(0); PG8_BAR; PG8_MMA(0, 0, At, B0); PG8_MMA(0, 1, At, B1); PG8_BAR; PG8_SCHED;
.Lgemm_join_962:
	s_add_i32 s17, 0, 0x18000
	v_add_u32_e32 v141, s17, v135
	s_add_i32 s27, 0, 0x1c000
	ds_read_b128 v[156:159], v141
	ds_read_b128 v[160:163], v141 offset:1024
	ds_read_b128 v[164:167], v141 offset:2048
	ds_read_b128 v[168:171], v141 offset:3072
	v_add_u32_e32 v141, s27, v135
	ds_read_b128 v[172:175], v141
	ds_read_b128 v[180:183], v141 offset:1024
	ds_read_b128 v[184:187], v141 offset:2048
	ds_read_b128 v[188:191], v141 offset:3072
	s_add_u32 s42, s96, s0
	s_addc_u32 s43, s97, s1
	s_mov_b32 m0, s15
	v_lshl_add_u64 v[236:237], s[42:43], 0, v[132:133]
	ds_read_b128 v[192:195], v139 offset:32768
	ds_read_b128 v[196:199], v139 offset:33792
	ds_read_b128 v[200:203], v139 offset:34816
	ds_read_b128 v[204:207], v139 offset:35840
	ds_read_b128 v[208:211], v139 offset:36864
	ds_read_b128 v[212:215], v139 offset:37888
	ds_read_b128 v[216:219], v139 offset:38912
	ds_read_b128 v[220:223], v139 offset:39936
	global_load_lds_dwordx4 v[236:237], off
	v_lshl_add_u64 v[236:237], s[42:43], 0, v[130:131]
	s_mov_b32 m0, s26
	s_nop 0
	global_load_lds_dwordx4 v[236:237], off
	s_waitcnt vmcnt(8)
	s_waitcnt lgkmcnt(0)
	s_barrier
	s_setprio 1
	s_waitcnt lgkmcnt(0)
	v_mfma_f32_16x16x32_bf16 v[124:127], v[156:159], v[192:195], v[124:127]
	v_mfma_f32_16x16x32_bf16 v[120:123], v[164:167], v[192:195], v[120:123]
	v_mfma_f32_16x16x32_bf16 v[116:119], v[156:159], v[200:203], v[116:119]
	v_mfma_f32_16x16x32_bf16 v[112:115], v[164:167], v[200:203], v[112:115]
	v_mfma_f32_16x16x32_bf16 v[100:103], v[156:159], v[208:211], v[100:103]
	v_mfma_f32_16x16x32_bf16 v[96:99], v[164:167], v[208:211], v[96:99]
	v_mfma_f32_16x16x32_bf16 v[84:87], v[156:159], v[216:219], v[84:87]
	v_mfma_f32_16x16x32_bf16 v[80:83], v[164:167], v[216:219], v[80:83]
	v_mfma_f32_16x16x32_bf16 v[124:127], v[160:163], v[196:199], v[124:127]
	v_mfma_f32_16x16x32_bf16 v[120:123], v[168:171], v[196:199], v[120:123]
	v_mfma_f32_16x16x32_bf16 v[116:119], v[160:163], v[204:207], v[116:119]
	v_mfma_f32_16x16x32_bf16 v[112:115], v[168:171], v[204:207], v[112:115]
	v_mfma_f32_16x16x32_bf16 v[100:103], v[160:163], v[212:215], v[100:103]
	v_mfma_f32_16x16x32_bf16 v[96:99], v[168:171], v[212:215], v[96:99]
	v_mfma_f32_16x16x32_bf16 v[84:87], v[160:163], v[220:223], v[84:87]
	v_mfma_f32_16x16x32_bf16 v[80:83], v[168:171], v[220:223], v[80:83]
	s_setprio 0
	s_setprio 1
	v_mfma_f32_16x16x32_bf16 v[108:111], v[172:175], v[192:195], v[108:111]
	v_mfma_f32_16x16x32_bf16 v[104:107], v[184:187], v[192:195], v[104:107]
	v_mfma_f32_16x16x32_bf16 v[92:95], v[172:175], v[200:203], v[92:95]
	v_mfma_f32_16x16x32_bf16 v[88:91], v[184:187], v[200:203], v[88:91]
	v_mfma_f32_16x16x32_bf16 v[76:79], v[172:175], v[208:211], v[76:79]
	v_mfma_f32_16x16x32_bf16 v[72:75], v[184:187], v[208:211], v[72:75]
	v_mfma_f32_16x16x32_bf16 v[68:71], v[172:175], v[216:219], v[68:71]
	v_mfma_f32_16x16x32_bf16 v[64:67], v[184:187], v[216:219], v[64:67]
	v_mfma_f32_16x16x32_bf16 v[108:111], v[180:183], v[196:199], v[108:111]
	v_mfma_f32_16x16x32_bf16 v[104:107], v[188:191], v[196:199], v[104:107]
	v_mfma_f32_16x16x32_bf16 v[92:95], v[180:183], v[204:207], v[92:95]
	v_mfma_f32_16x16x32_bf16 v[88:91], v[188:191], v[204:207], v[88:91]
	v_mfma_f32_16x16x32_bf16 v[76:79], v[180:183], v[212:215], v[76:79]
	v_mfma_f32_16x16x32_bf16 v[72:75], v[188:191], v[212:215], v[72:75]
	v_mfma_f32_16x16x32_bf16 v[68:71], v[180:183], v[220:223], v[68:71]
	v_mfma_f32_16x16x32_bf16 v[64:67], v[188:191], v[220:223], v[64:67]
	s_setprio 0
	s_barrier
; #define PG8_STAGE(bufoff, gbase, voff) do { _Pragma("unroll") for (int _i = 0; _i < 2; ++_i) \
;         __builtin_amdgcn_global_load_lds((const unsigned*)((const char*)(gbase) + (voff)[_i]), (LAS unsigned*)(lds + (bufoff) + ldsw + _i * 8192), 16, 0, 0); } while (0)
; #define PG8_LDA(dst, b, h) do { _Pragma("unroll") for (int m = 0; m < 4; ++m) _Pragma("unroll") for (int k = 0; k < 2; ++k) dst[m][k] = *(const LAS bf16x8*)(lds + PG8_SA(b, h) + aoff + m * 2048 + k * 1024); } while (0)
; #define PG8_MMA(ai, bj, At, Bt) do { __builtin_amdgcn_s_setprio(1); _Pragma("unroll") for (int m = 0; m < 4; ++m) _Pragma("unroll") for (int n = 0; n < 2; ++n) _Pragma("unroll") for (int k = 0; k < 2; ++k) \
;         acc[ai][bj][m][n] = __builtin_amdgcn_mfma_f32_16x16x32_bf16(Bt[n][k], At[m][k], acc[ai][bj][m][n], 0, 0, 0); __builtin_amdgcn_s_setprio(0); } while (0)
; #define PG8_WAIT_V(n) asm volatile("s_waitcnt vmcnt(" #n ")" ::: "memory")
; #define PG8_WAIT_L(n) asm volatile("s_waitcnt lgkmcnt(" #n ")" ::: "memory")
; #define PG8_BAR __builtin_amdgcn_s_barrier()
; #define PG8_SCHED __builtin_amdgcn_sched_barrier(0)
; template <class Epi, class Sched, bool ALIGN_EPI>
; __device__ __forceinline__ void gemm_phase(LAS unsigned char* lds, const int wid, const int lda_, const int ldb_, const int K_, const Sched& S, const Epi& E) {
;     ...
;             PG8_LDA(At, 1, 1); PG8_STAGE(PG8_SB(1, 0), b3, voffB); PG8_STAGE(PG8_SB(1, 1), b3 + hstepB, voffB); PG8_STAGE(PG8_SA(1, 0), a3, voffA);
;             PG8_WAIT_V(8); PG8_WAIT_L(0); PG8_BAR; PG8_MMA(1, 0, At, B0); PG8_MMA(1, 1, At, B1); PG8_BAR; PG8_SCHED;
;         }
;         if constexpr (ALIGN_EPI) { if (wr == 0) PG8_BAR; }
;         E(acc, cur, S, wr, wc, fr, fq);
;         if (!has_next) break;
;     __device__ __forceinline__ void out(const pg8::Unit& u, char*& o, int& ldo, int& kind) const { ldo = D;
;         if (u.kq < 0) { o = (char*)ws + YOFF + ((size_t)u.pm * 256 * D + (size_t)u.pn * 256) * 2; kind = 0; }
;         else { o = (char*)ws + WS_PART + (((size_t)u.kq * MCTX + (size_t)(u.pm - 64) * 256) * D + (size_t)u.pn * 256) * 2; kind = 0; } }
	s_add_i32 s17, s17, s3
	v_lshl_add_u64 v[224:225], v[224:225], 0, s[24:25]
	s_mov_b32 m0, s17
	ds_read_b128 v[192:195], v139 offset:49152
	ds_read_b128 v[196:199], v139 offset:50176
	ds_read_b128 v[200:203], v139 offset:51200
	ds_read_b128 v[204:207], v139 offset:52224
	ds_read_b128 v[208:211], v139 offset:53248
	ds_read_b128 v[212:215], v139 offset:54272
	ds_read_b128 v[216:219], v139 offset:55296
	ds_read_b128 v[220:223], v139 offset:56320
	global_load_lds_dwordx4 v[224:225], off
	v_lshl_add_u64 v[224:225], v[226:227], 0, s[24:25]
	s_add_i32 m0, s17, 0x2000
	s_add_i32 s17, s27, s3
	global_load_lds_dwordx4 v[224:225], off
	v_lshl_add_u64 v[224:225], v[228:229], 0, s[24:25]
	s_mov_b32 m0, s17
	s_nop 0
	global_load_lds_dwordx4 v[224:225], off
	v_lshl_add_u64 v[224:225], v[230:231], 0, s[24:25]
	s_add_i32 m0, s17, 0x2000
	s_nop 0
	global_load_lds_dwordx4 v[224:225], off
	v_lshl_add_u64 v[224:225], v[232:233], 0, s[24:25]
	s_mov_b32 m0, s72
	s_nop 0
	global_load_lds_dwordx4 v[224:225], off
	v_lshl_add_u64 v[224:225], v[234:235], 0, s[24:25]
	s_mov_b32 m0, s73
	s_nop 0
	global_load_lds_dwordx4 v[224:225], off
	s_waitcnt vmcnt(8)
	s_waitcnt lgkmcnt(0)
	s_barrier
	s_setprio 1
	s_waitcnt lgkmcnt(0)
	v_mfma_f32_16x16x32_bf16 v[60:63], v[156:159], v[192:195], v[60:63]
	v_mfma_f32_16x16x32_bf16 v[56:59], v[164:167], v[192:195], v[56:59]
	v_mfma_f32_16x16x32_bf16 v[52:55], v[156:159], v[200:203], v[52:55]
	v_mfma_f32_16x16x32_bf16 v[48:51], v[164:167], v[200:203], v[48:51]
	v_mfma_f32_16x16x32_bf16 v[36:39], v[156:159], v[208:211], v[36:39]
	v_mfma_f32_16x16x32_bf16 v[32:35], v[164:167], v[208:211], v[32:35]
	v_mfma_f32_16x16x32_bf16 v[20:23], v[156:159], v[216:219], v[20:23]
	v_mfma_f32_16x16x32_bf16 v[16:19], v[164:167], v[216:219], v[16:19]
	v_mfma_f32_16x16x32_bf16 v[60:63], v[160:163], v[196:199], v[60:63]
	v_mfma_f32_16x16x32_bf16 v[56:59], v[168:171], v[196:199], v[56:59]
	v_mfma_f32_16x16x32_bf16 v[52:55], v[160:163], v[204:207], v[52:55]
	v_mfma_f32_16x16x32_bf16 v[48:51], v[168:171], v[204:207], v[48:51]
	v_mfma_f32_16x16x32_bf16 v[36:39], v[160:163], v[212:215], v[36:39]
	v_mfma_f32_16x16x32_bf16 v[32:35], v[168:171], v[212:215], v[32:35]
	v_mfma_f32_16x16x32_bf16 v[20:23], v[160:163], v[220:223], v[20:23]
	v_mfma_f32_16x16x32_bf16 v[16:19], v[168:171], v[220:223], v[16:19]
	s_setprio 0
	s_setprio 1
	v_mfma_f32_16x16x32_bf16 v[44:47], v[172:175], v[192:195], v[44:47]
	v_mfma_f32_16x16x32_bf16 v[40:43], v[184:187], v[192:195], v[40:43]
	v_mfma_f32_16x16x32_bf16 v[28:31], v[172:175], v[200:203], v[28:31]
	v_mfma_f32_16x16x32_bf16 v[24:27], v[184:187], v[200:203], v[24:27]
	v_mfma_f32_16x16x32_bf16 v[12:15], v[172:175], v[208:211], v[12:15]
	v_mfma_f32_16x16x32_bf16 v[8:11], v[184:187], v[208:211], v[8:11]
	v_mfma_f32_16x16x32_bf16 v[4:7], v[172:175], v[216:219], v[4:7]
	v_mfma_f32_16x16x32_bf16 v[0:3], v[184:187], v[216:219], v[0:3]
	v_mfma_f32_16x16x32_bf16 v[44:47], v[180:183], v[196:199], v[44:47]
	v_mfma_f32_16x16x32_bf16 v[40:43], v[188:191], v[196:199], v[40:43]
	v_mfma_f32_16x16x32_bf16 v[28:31], v[180:183], v[204:207], v[28:31]
	v_mfma_f32_16x16x32_bf16 v[24:27], v[188:191], v[204:207], v[24:27]
	v_mfma_f32_16x16x32_bf16 v[12:15], v[180:183], v[212:215], v[12:15]
	v_mfma_f32_16x16x32_bf16 v[8:11], v[188:191], v[212:215], v[8:11]
	v_mfma_f32_16x16x32_bf16 v[4:7], v[180:183], v[220:223], v[4:7]
	v_mfma_f32_16x16x32_bf16 v[0:3], v[188:191], v[220:223], v[0:3]
	s_setprio 0
	s_barrier
	s_add_u32 s94, s94, 0x100
	s_addc_u32 s95, s95, 0
	s_add_u32 s49, s49, 0x100
	s_addc_u32 s76, s76, 0
	s_cmp_ge_u32 s78, s45
	s_mov_b32 s77, s78
	s_cbranch_scc0 .LBB0_962
	s_mov_b64 s[94:95], -1
	s_and_b64 vcc, exec, s[50:51]
	s_cbranch_vccz .LBB0_965
	s_mov_b32 s49, s92
	s_ashr_i32 s47, s46, 31
	s_ashr_i32 s45, s44, 31
	s_lshl_b64 s[4:5], s[46:47], 20
	s_lshl_b64 s[42:43], s[44:45], 9
	s_lshl_b64 s[48:49], s[48:49], 23
	v_readlane_b32 s50, v251, 28
	v_readlane_b32 s51, v251, 29
	s_add_u32 s17, s50, s42
	s_addc_u32 s27, s51, s43
	s_add_u32 s17, s17, s48
	s_addc_u32 s27, s27, s49
	s_add_u32 s4, s17, s4
	s_addc_u32 s5, s27, s5
	s_add_u32 s4, s4, 0xfc000000
	s_addc_u32 s5, s5, -1
	s_mov_b64 s[94:95], 0

; #define PG8_STAGE(bufoff, gbase, voff) do { _Pragma("unroll") for (int _i = 0; _i < 2; ++_i) \
;         __builtin_amdgcn_global_load_lds((const unsigned*)((const char*)(gbase) + (voff)[_i]), (LAS unsigned*)(lds + (bufoff) + ldsw + _i * 8192), 16, 0, 0); } while (0)
; #define PG8_LDA(dst, b, h) do { _Pragma("unroll") for (int m = 0; m < 4; ++m) _Pragma("unroll") for (int k = 0; k < 2; ++k) dst[m][k] = *(const LAS bf16x8*)(lds + PG8_SA(b, h) + aoff + m * 2048 + k * 1024); } while (0)
; #define PG8_LDB(dst, b, h) do { _Pragma("unroll") for (int n = 0; n < 2; ++n) _Pragma("unroll") for (int k = 0; k < 2; ++k) dst[n][k] = *(const LAS bf16x8*)(lds + PG8_SB(b, h) + boff + n * 2048 + k * 1024); } while (0)
; #define PG8_MMA(ai, bj, At, Bt) do { __builtin_amdgcn_s_setprio(1); _Pragma("unroll") for (int m = 0; m < 4; ++m) _Pragma("unroll") for (int n = 0; n < 2; ++n) _Pragma("unroll") for (int k = 0; k < 2; ++k) \
;         acc[ai][bj][m][n] = __builtin_amdgcn_mfma_f32_16x16x32_bf16(Bt[n][k], At[m][k], acc[ai][bj][m][n], 0, 0, 0); __builtin_amdgcn_s_setprio(0); } while (0)
; template <class Epi, class Sched, bool ALIGN_EPI>
; __device__ __forceinline__ void gemm_phase(LAS unsigned char* lds, const int wid, const int lda_, const int ldb_, const int K_, const Sched& S, const Epi& E) {
;     ...
;         const bool has_next = S.next(ui + 1, nxt);
;         const int nt = S.nt(cur);
;         const char* nA = has_next ? S.a(nxt) : cA; const char* nB = has_next ? S.b(nxt) : cB;
; #pragma unroll 1
;         for (int t = 0; t < nt; t += 2) {
;             const bool last = (t == nt - 2);
;             const char* a1 = cA + (size_t)(t + 1) * kstep;
;             const char* a2 = last ? nA : cA + (size_t)(t + 2) * kstep; const char* b2 = last ? nB : cB + (size_t)(t + 2) * kstep;
;             const char* a3 = a2 + kstep; const char* b3 = b2 + kstep;
;             PG8_LDB(B0, 0, 0); PG8_LDB(B1, 0, 1); PG8_SCHED; PG8_LDA(At, 0, 0); PG8_STAGE(PG8_SA(1, 1), a1 + hstepA, voffA);
;             PG8_WAIT_V(8); PG8_WAIT_L(0); PG8_BAR; PG8_MMA(0, 0, At, B0); PG8_MMA(0, 1, At, B1); PG8_BAR; PG8_SCHED;
;     __device__ __forceinline__ const char* a(const pg8::Unit& u) const { return (const char*)ws + WS_A + (size_t)u.pm * 256 * D * 2; }
;     __device__ __forceinline__ const char* b(const pg8::Unit& u) const { return (const char*)ws + boff + (size_t)u.pn * 256 * D * 2; }
.LBB0_1119:
	v_mov_b64_e32 v[0:1], s[0:1]
	s_ashr_i32 s45, s44, 31
	v_cmp_lt_i64_e32 vcc, s[4:5], v[0:1]
	s_lshl_b64 s[4:5], s[44:45], 20
	v_readlane_b32 s46, v253, 52
	v_readlane_b32 s47, v253, 53
	s_add_u32 s46, s46, s4
	s_addc_u32 s47, s47, s5
	s_and_b64 s[4:5], vcc, exec
	s_cselect_b32 s4, s47, s41
	s_cselect_b32 s5, s46, s40
	s_ashr_i32 s43, s42, 31
	s_lshl_b64 s[48:49], s[42:43], 20
	s_add_u32 s48, s15, s48
	s_addc_u32 s49, s26, s49
	s_and_b64 s[76:77], vcc, exec
	s_cselect_b32 s43, s49, s51
	s_cselect_b32 s45, s48, s50
	s_add_u32 s76, s40, 0x80
	s_addc_u32 s77, s41, 0
	v_lshl_add_u64 v[156:157], s[76:77], 0, v[152:153]
	v_lshl_add_u64 v[158:159], s[76:77], 0, v[154:155]
	s_add_u32 s76, s50, 0x100
	s_addc_u32 s77, s51, 0
	s_mov_b32 s78, -2
	s_mov_b64 s[50:51], 0
	s_add_u32 s17, s40, s50
	s_addc_u32 s27, s41, s51
	s_add_u32 s17, s17, 0x100
	s_addc_u32 s27, s27, 0
	s_add_u32 s79, s76, s50
	s_addc_u32 s80, s77, s51
	s_add_i32 s86, 0, 0x10000
	s_cmpk_eq_i32 s50, 0xf00
	s_cselect_b32 s95, s4, s27
	s_cselect_b32 s94, s5, s17
	v_add_u32_e32 v141, s86, v135
	s_cselect_b32 s81, s43, s80
	s_cselect_b32 s80, s45, s79
	s_add_i32 s17, 0, 0x14000
	ds_read_b128 v[160:163], v141
	ds_read_b128 v[164:167], v141 offset:1024
	ds_read_b128 v[168:171], v141 offset:2048
	ds_read_b128 v[172:175], v141 offset:3072
	v_add_u32_e32 v141, s17, v135
	ds_read_b128 v[180:183], v141
	ds_read_b128 v[184:187], v141 offset:1024
	ds_read_b128 v[188:191], v141 offset:2048
	ds_read_b128 v[192:195], v141 offset:3072
	v_lshl_add_u64 v[228:229], v[158:159], 0, s[50:51]
	s_add_i32 m0, s16, 0xc000
	ds_read_b128 v[196:199], v139
	ds_read_b128 v[200:203], v139 offset:1024
	ds_read_b128 v[204:207], v139 offset:2048
	ds_read_b128 v[208:211], v139 offset:3072
	ds_read_b128 v[212:215], v139 offset:4096
	ds_read_b128 v[216:219], v139 offset:5120
	ds_read_b128 v[220:223], v139 offset:6144
	ds_read_b128 v[224:227], v139 offset:7168
	global_load_lds_dwordx4 v[228:229], off
	v_lshl_add_u64 v[228:229], v[156:157], 0, s[50:51]
	s_add_i32 m0, s16, 0xe000
	s_nop 0
	global_load_lds_dwordx4 v[228:229], off
	s_waitcnt vmcnt(8)
	s_waitcnt lgkmcnt(0)
	s_barrier
	s_setprio 1
	s_waitcnt lgkmcnt(0)
	v_mfma_f32_16x16x32_bf16 v[124:127], v[160:163], v[196:199], 0
	v_mfma_f32_16x16x32_bf16 v[120:123], v[168:171], v[196:199], 0
	v_mfma_f32_16x16x32_bf16 v[116:119], v[160:163], v[204:207], 0
	v_mfma_f32_16x16x32_bf16 v[112:115], v[168:171], v[204:207], 0
	v_mfma_f32_16x16x32_bf16 v[100:103], v[160:163], v[212:215], 0
	v_mfma_f32_16x16x32_bf16 v[96:99], v[168:171], v[212:215], 0
	v_mfma_f32_16x16x32_bf16 v[84:87], v[160:163], v[220:223], 0
	v_mfma_f32_16x16x32_bf16 v[80:83], v[168:171], v[220:223], 0
	v_mfma_f32_16x16x32_bf16 v[124:127], v[164:167], v[200:203], v[124:127]
	v_mfma_f32_16x16x32_bf16 v[120:123], v[172:175], v[200:203], v[120:123]
	v_mfma_f32_16x16x32_bf16 v[116:119], v[164:167], v[208:211], v[116:119]
	v_mfma_f32_16x16x32_bf16 v[112:115], v[172:175], v[208:211], v[112:115]
	v_mfma_f32_16x16x32_bf16 v[100:103], v[164:167], v[216:219], v[100:103]
	v_mfma_f32_16x16x32_bf16 v[96:99], v[172:175], v[216:219], v[96:99]
	v_mfma_f32_16x16x32_bf16 v[84:87], v[164:167], v[224:227], v[84:87]
	v_mfma_f32_16x16x32_bf16 v[80:83], v[172:175], v[224:227], v[80:83]
	s_setprio 0
	s_setprio 1
	v_mfma_f32_16x16x32_bf16 v[108:111], v[180:183], v[196:199], 0
	v_mfma_f32_16x16x32_bf16 v[104:107], v[188:191], v[196:199], 0
	v_mfma_f32_16x16x32_bf16 v[92:95], v[180:183], v[204:207], 0
	v_mfma_f32_16x16x32_bf16 v[88:91], v[188:191], v[204:207], 0
	v_mfma_f32_16x16x32_bf16 v[76:79], v[180:183], v[212:215], 0
	v_mfma_f32_16x16x32_bf16 v[72:75], v[188:191], v[212:215], 0
	v_mfma_f32_16x16x32_bf16 v[68:71], v[180:183], v[220:223], 0
	v_mfma_f32_16x16x32_bf16 v[64:67], v[188:191], v[220:223], 0
	v_mfma_f32_16x16x32_bf16 v[108:111], v[184:187], v[200:203], v[108:111]
	v_mfma_f32_16x16x32_bf16 v[104:107], v[192:195], v[200:203], v[104:107]
	v_mfma_f32_16x16x32_bf16 v[92:95], v[184:187], v[208:211], v[92:95]
	v_mfma_f32_16x16x32_bf16 v[88:91], v[192:195], v[208:211], v[88:91]
	v_mfma_f32_16x16x32_bf16 v[76:79], v[184:187], v[216:219], v[76:79]
	v_mfma_f32_16x16x32_bf16 v[72:75], v[192:195], v[216:219], v[72:75]
	v_mfma_f32_16x16x32_bf16 v[68:71], v[184:187], v[224:227], v[68:71]
	v_mfma_f32_16x16x32_bf16 v[64:67], v[192:195], v[224:227], v[64:67]
	s_setprio 0
	s_barrier
; #define PG8_STAGE(bufoff, gbase, voff) do { _Pragma("unroll") for (int _i = 0; _i < 2; ++_i) \
;         __builtin_amdgcn_global_load_lds((const unsigned*)((const char*)(gbase) + (voff)[_i]), (LAS unsigned*)(lds + (bufoff) + ldsw + _i * 8192), 16, 0, 0); } while (0)
; #define PG8_LDA(dst, b, h) do { _Pragma("unroll") for (int m = 0; m < 4; ++m) _Pragma("unroll") for (int k = 0; k < 2; ++k) dst[m][k] = *(const LAS bf16x8*)(lds + PG8_SA(b, h) + aoff + m * 2048 + k * 1024); } while (0)
; #define PG8_MMA(ai, bj, At, Bt) do { __builtin_amdgcn_s_setprio(1); _Pragma("unroll") for (int m = 0; m < 4; ++m) _Pragma("unroll") for (int n = 0; n < 2; ++n) _Pragma("unroll") for (int k = 0; k < 2; ++k) \
;         acc[ai][bj][m][n] = __builtin_amdgcn_mfma_f32_16x16x32_bf16(Bt[n][k], At[m][k], acc[ai][bj][m][n], 0, 0, 0); __builtin_amdgcn_s_setprio(0); } while (0)
; #define PG8_WAIT_V(n) asm volatile("s_waitcnt vmcnt(" #n ")" ::: "memory")
; #define PG8_WAIT_L(n) asm volatile("s_waitcnt lgkmcnt(" #n ")" ::: "memory")
; #define PG8_BAR __builtin_amdgcn_s_barrier()
; #define PG8_SCHED __builtin_amdgcn_sched_barrier(0)
; template <class Epi, class Sched, bool ALIGN_EPI>
; __device__ __forceinline__ void gemm_phase(LAS unsigned char* lds, const int wid, const int lda_, const int ldb_, const int K_, const Sched& S, const Epi& E) {
;     ...
;             PG8_LDA(At, 0, 1); PG8_STAGE(PG8_SB(0, 0), b2, voffB); PG8_STAGE(PG8_SB(0, 1), b2 + hstepB, voffB); PG8_STAGE(PG8_SA(0, 0), a2, voffA);
;             PG8_WAIT_V(8); PG8_WAIT_L(0); PG8_BAR; PG8_MMA(1, 0, At, B0); PG8_MMA(1, 1, At, B1); PG8_BAR; PG8_SCHED;
	s_add_i32 s27, s86, s3
	v_lshl_add_u64 v[228:229], s[80:81], 0, v[176:177]
	s_mov_b32 m0, s27
	ds_read_b128 v[196:199], v139 offset:16384
	ds_read_b128 v[200:203], v139 offset:17408
	ds_read_b128 v[204:207], v139 offset:18432
	ds_read_b128 v[208:211], v139 offset:19456
	ds_read_b128 v[212:215], v139 offset:20480
	ds_read_b128 v[216:219], v139 offset:21504
	ds_read_b128 v[220:223], v139 offset:22528
	ds_read_b128 v[224:227], v139 offset:23552
	global_load_lds_dwordx4 v[228:229], off
	s_add_i32 m0, s27, 0x2000
	v_lshl_add_u64 v[230:231], s[80:81], 0, v[128:129]
	s_add_u32 s80, s80, s30
	s_addc_u32 s81, s81, s31
	s_add_i32 s17, s17, s3
	global_load_lds_dwordx4 v[230:231], off
	v_lshl_add_u64 v[232:233], s[80:81], 0, v[176:177]
	s_mov_b32 m0, s17
	v_lshl_add_u64 v[234:235], s[80:81], 0, v[128:129]
	global_load_lds_dwordx4 v[232:233], off
	s_add_i32 m0, s17, 0x2000
	v_lshl_add_u64 v[236:237], s[94:95], 0, v[132:133]
	global_load_lds_dwordx4 v[234:235], off
	s_mov_b32 m0, s16
	v_lshl_add_u64 v[246:247], s[94:95], 0, v[130:131]
	global_load_lds_dwordx4 v[236:237], off
	s_mov_b32 m0, s35
	s_nop 0
	global_load_lds_dwordx4 v[246:247], off
	s_waitcnt vmcnt(8)
	s_waitcnt lgkmcnt(0)
	s_barrier
	s_setprio 1
	s_waitcnt lgkmcnt(0)
	v_mfma_f32_16x16x32_bf16 v[60:63], v[160:163], v[196:199], 0
	v_mfma_f32_16x16x32_bf16 v[56:59], v[168:171], v[196:199], 0
	v_mfma_f32_16x16x32_bf16 v[52:55], v[160:163], v[204:207], 0
	v_mfma_f32_16x16x32_bf16 v[48:51], v[168:171], v[204:207], 0
	v_mfma_f32_16x16x32_bf16 v[36:39], v[160:163], v[212:215], 0
	v_mfma_f32_16x16x32_bf16 v[32:35], v[168:171], v[212:215], 0
	v_mfma_f32_16x16x32_bf16 v[20:23], v[160:163], v[220:223], 0
	v_mfma_f32_16x16x32_bf16 v[16:19], v[168:171], v[220:223], 0
	v_mfma_f32_16x16x32_bf16 v[60:63], v[164:167], v[200:203], v[60:63]
	v_mfma_f32_16x16x32_bf16 v[56:59], v[172:175], v[200:203], v[56:59]
	v_mfma_f32_16x16x32_bf16 v[52:55], v[164:167], v[208:211], v[52:55]
	v_mfma_f32_16x16x32_bf16 v[48:51], v[172:175], v[208:211], v[48:51]
	v_mfma_f32_16x16x32_bf16 v[36:39], v[164:167], v[216:219], v[36:39]
	v_mfma_f32_16x16x32_bf16 v[32:35], v[172:175], v[216:219], v[32:35]
	v_mfma_f32_16x16x32_bf16 v[20:23], v[164:167], v[224:227], v[20:23]
	v_mfma_f32_16x16x32_bf16 v[16:19], v[172:175], v[224:227], v[16:19]
	s_setprio 0
	s_setprio 1
	v_mfma_f32_16x16x32_bf16 v[44:47], v[180:183], v[196:199], 0
	v_mfma_f32_16x16x32_bf16 v[40:43], v[188:191], v[196:199], 0
	v_mfma_f32_16x16x32_bf16 v[28:31], v[180:183], v[204:207], 0
	v_mfma_f32_16x16x32_bf16 v[24:27], v[188:191], v[204:207], 0
	v_mfma_f32_16x16x32_bf16 v[12:15], v[180:183], v[212:215], 0
	v_mfma_f32_16x16x32_bf16 v[8:11], v[188:191], v[212:215], 0
	v_mfma_f32_16x16x32_bf16 v[4:7], v[180:183], v[220:223], 0
	v_mfma_f32_16x16x32_bf16 v[0:3], v[188:191], v[220:223], 0
	v_mfma_f32_16x16x32_bf16 v[44:47], v[184:187], v[200:203], v[44:47]
	v_mfma_f32_16x16x32_bf16 v[40:43], v[192:195], v[200:203], v[40:43]
	v_mfma_f32_16x16x32_bf16 v[28:31], v[184:187], v[208:211], v[28:31]
	v_mfma_f32_16x16x32_bf16 v[24:27], v[192:195], v[208:211], v[24:27]
	v_mfma_f32_16x16x32_bf16 v[12:15], v[184:187], v[216:219], v[12:15]
	v_mfma_f32_16x16x32_bf16 v[8:11], v[192:195], v[216:219], v[8:11]
	v_mfma_f32_16x16x32_bf16 v[4:7], v[184:187], v[224:227], v[4:7]
	v_mfma_f32_16x16x32_bf16 v[0:3], v[192:195], v[224:227], v[0:3]
	s_setprio 0
	s_barrier
	s_branch .Lgemm_join_1120

; #define PG8_STAGE(bufoff, gbase, voff) do { _Pragma("unroll") for (int _i = 0; _i < 2; ++_i) \
;         __builtin_amdgcn_global_load_lds((const unsigned*)((const char*)(gbase) + (voff)[_i]), (LAS unsigned*)(lds + (bufoff) + ldsw + _i * 8192), 16, 0, 0); } while (0)
; #define PG8_LDA(dst, b, h) do { _Pragma("unroll") for (int m = 0; m < 4; ++m) _Pragma("unroll") for (int k = 0; k < 2; ++k) dst[m][k] = *(const LAS bf16x8*)(lds + PG8_SA(b, h) + aoff + m * 2048 + k * 1024); } while (0)
; #define PG8_LDB(dst, b, h) do { _Pragma("unroll") for (int n = 0; n < 2; ++n) _Pragma("unroll") for (int k = 0; k < 2; ++k) dst[n][k] = *(const LAS bf16x8*)(lds + PG8_SB(b, h) + boff + n * 2048 + k * 1024); } while (0)
; #define PG8_MMA(ai, bj, At, Bt) do { __builtin_amdgcn_s_setprio(1); _Pragma("unroll") for (int m = 0; m < 4; ++m) _Pragma("unroll") for (int n = 0; n < 2; ++n) _Pragma("unroll") for (int k = 0; k < 2; ++k) \
;         acc[ai][bj][m][n] = __builtin_amdgcn_mfma_f32_16x16x32_bf16(Bt[n][k], At[m][k], acc[ai][bj][m][n], 0, 0, 0); __builtin_amdgcn_s_setprio(0); } while (0)
; #define PG8_WAIT_V(n) asm volatile("s_waitcnt vmcnt(" #n ")" ::: "memory")
; #define PG8_WAIT_L(n) asm volatile("s_waitcnt lgkmcnt(" #n ")" ::: "memory")
; #define PG8_BAR __builtin_amdgcn_s_barrier()
; #define PG8_SCHED __builtin_amdgcn_sched_barrier(0)
; template <class Epi, class Sched, bool ALIGN_EPI>
; __device__ __forceinline__ void gemm_phase(LAS unsigned char* lds, const int wid, const int lda_, const int ldb_, const int K_, const Sched& S, const Epi& E) {
;     ...
;             PG8_LDB(B0, 1, 0); PG8_LDB(B1, 1, 1); PG8_SCHED; PG8_LDA(At, 1, 0); PG8_STAGE(PG8_SA(0, 1), a2 + hstepA, voffA);
;             PG8_WAIT_V(8); PG8_WAIT_L(0); PG8_BAR; PG8_MMA(0, 0, At, B0); PG8_MMA(0, 1, At, B1); PG8_BAR; PG8_SCHED;
;             PG8_LDA(At, 1, 1); PG8_STAGE(PG8_SB(1, 0), b3, voffB); PG8_STAGE(PG8_SB(1, 1), b3 + hstepB, voffB); PG8_STAGE(PG8_SA(1, 0), a3, voffA);
;             PG8_WAIT_V(8); PG8_WAIT_L(0); PG8_BAR; PG8_MMA(1, 0, At, B0); PG8_MMA(1, 1, At, B1); PG8_BAR; PG8_SCHED;
.Lgemm_join_1120:
	s_add_i32 s17, 0, 0x18000
	v_add_u32_e32 v141, s17, v135
	s_add_i32 s27, 0, 0x1c000
	ds_read_b128 v[160:163], v141
	ds_read_b128 v[164:167], v141 offset:1024
	ds_read_b128 v[168:171], v141 offset:2048
	ds_read_b128 v[172:175], v141 offset:3072
	v_add_u32_e32 v141, s27, v135
	ds_read_b128 v[180:183], v141
	ds_read_b128 v[184:187], v141 offset:1024
	ds_read_b128 v[188:191], v141 offset:2048
	ds_read_b128 v[192:195], v141 offset:3072
	s_add_u32 s80, s94, s10
	s_addc_u32 s81, s95, s11
	s_mov_b32 m0, s39
	v_lshl_add_u64 v[248:249], s[80:81], 0, v[132:133]
	ds_read_b128 v[196:199], v139 offset:32768
	ds_read_b128 v[200:203], v139 offset:33792
	ds_read_b128 v[204:207], v139 offset:34816
	ds_read_b128 v[208:211], v139 offset:35840
	ds_read_b128 v[212:215], v139 offset:36864
	ds_read_b128 v[216:219], v139 offset:37888
	ds_read_b128 v[220:223], v139 offset:38912
	ds_read_b128 v[224:227], v139 offset:39936
	global_load_lds_dwordx4 v[248:249], off
	v_lshl_add_u64 v[248:249], s[80:81], 0, v[130:131]
	s_mov_b32 m0, s72
	s_nop 0
	global_load_lds_dwordx4 v[248:249], off
	s_waitcnt vmcnt(8)
	s_waitcnt lgkmcnt(0)
	s_barrier
	s_setprio 1
	s_waitcnt lgkmcnt(0)
	v_mfma_f32_16x16x32_bf16 v[124:127], v[160:163], v[196:199], v[124:127]
	v_mfma_f32_16x16x32_bf16 v[120:123], v[168:171], v[196:199], v[120:123]
	v_mfma_f32_16x16x32_bf16 v[116:119], v[160:163], v[204:207], v[116:119]
	v_mfma_f32_16x16x32_bf16 v[112:115], v[168:171], v[204:207], v[112:115]
	v_mfma_f32_16x16x32_bf16 v[100:103], v[160:163], v[212:215], v[100:103]
	v_mfma_f32_16x16x32_bf16 v[96:99], v[168:171], v[212:215], v[96:99]
	v_mfma_f32_16x16x32_bf16 v[84:87], v[160:163], v[220:223], v[84:87]
	v_mfma_f32_16x16x32_bf16 v[80:83], v[168:171], v[220:223], v[80:83]
	v_mfma_f32_16x16x32_bf16 v[124:127], v[164:167], v[200:203], v[124:127]
	v_mfma_f32_16x16x32_bf16 v[120:123], v[172:175], v[200:203], v[120:123]
	v_mfma_f32_16x16x32_bf16 v[116:119], v[164:167], v[208:211], v[116:119]
	v_mfma_f32_16x16x32_bf16 v[112:115], v[172:175], v[208:211], v[112:115]
	v_mfma_f32_16x16x32_bf16 v[100:103], v[164:167], v[216:219], v[100:103]
	v_mfma_f32_16x16x32_bf16 v[96:99], v[172:175], v[216:219], v[96:99]
	v_mfma_f32_16x16x32_bf16 v[84:87], v[164:167], v[224:227], v[84:87]
	v_mfma_f32_16x16x32_bf16 v[80:83], v[172:175], v[224:227], v[80:83]
	s_setprio 0
	s_setprio 1
	v_mfma_f32_16x16x32_bf16 v[108:111], v[180:183], v[196:199], v[108:111]
	v_mfma_f32_16x16x32_bf16 v[104:107], v[188:191], v[196:199], v[104:107]
	v_mfma_f32_16x16x32_bf16 v[92:95], v[180:183], v[204:207], v[92:95]
	v_mfma_f32_16x16x32_bf16 v[88:91], v[188:191], v[204:207], v[88:91]
	v_mfma_f32_16x16x32_bf16 v[76:79], v[180:183], v[212:215], v[76:79]
	v_mfma_f32_16x16x32_bf16 v[72:75], v[188:191], v[212:215], v[72:75]
	v_mfma_f32_16x16x32_bf16 v[68:71], v[180:183], v[220:223], v[68:71]
	v_mfma_f32_16x16x32_bf16 v[64:67], v[188:191], v[220:223], v[64:67]
	v_mfma_f32_16x16x32_bf16 v[108:111], v[184:187], v[200:203], v[108:111]
	v_mfma_f32_16x16x32_bf16 v[104:107], v[192:195], v[200:203], v[104:107]
	v_mfma_f32_16x16x32_bf16 v[92:95], v[184:187], v[208:211], v[92:95]
	v_mfma_f32_16x16x32_bf16 v[88:91], v[192:195], v[208:211], v[88:91]
	v_mfma_f32_16x16x32_bf16 v[76:79], v[184:187], v[216:219], v[76:79]
	v_mfma_f32_16x16x32_bf16 v[72:75], v[192:195], v[216:219], v[72:75]
	v_mfma_f32_16x16x32_bf16 v[68:71], v[184:187], v[224:227], v[68:71]
	v_mfma_f32_16x16x32_bf16 v[64:67], v[192:195], v[224:227], v[64:67]
	s_setprio 0
	s_barrier
	s_add_i32 s17, s17, s3
	v_lshl_add_u64 v[228:229], v[228:229], 0, s[24:25]
	s_mov_b32 m0, s17
	ds_read_b128 v[196:199], v139 offset:49152
	ds_read_b128 v[200:203], v139 offset:50176
	ds_read_b128 v[204:207], v139 offset:51200
	ds_read_b128 v[208:211], v139 offset:52224
	ds_read_b128 v[212:215], v139 offset:53248
	ds_read_b128 v[216:219], v139 offset:54272
	ds_read_b128 v[220:223], v139 offset:55296
	ds_read_b128 v[224:227], v139 offset:56320
	global_load_lds_dwordx4 v[228:229], off
	v_lshl_add_u64 v[228:229], v[230:231], 0, s[24:25]
	s_add_i32 m0, s17, 0x2000
	s_add_i32 s17, s27, s3
	global_load_lds_dwordx4 v[228:229], off
	v_lshl_add_u64 v[228:229], v[232:233], 0, s[24:25]
	s_mov_b32 m0, s17
	s_nop 0
	global_load_lds_dwordx4 v[228:229], off
	v_lshl_add_u64 v[228:229], v[234:235], 0, s[24:25]
	s_add_i32 m0, s17, 0x2000
	s_nop 0
	global_load_lds_dwordx4 v[228:229], off
	v_lshl_add_u64 v[228:229], v[236:237], 0, s[24:25]
	s_mov_b32 m0, s73
	s_nop 0
	global_load_lds_dwordx4 v[228:229], off
	v_lshl_add_u64 v[228:229], v[246:247], 0, s[24:25]
	s_mov_b32 m0, s74
	s_nop 0
	global_load_lds_dwordx4 v[228:229], off
	s_waitcnt vmcnt(8)
	s_waitcnt lgkmcnt(0)
	s_barrier
; __device__ __forceinline__ unsigned cvt_pk_bf16(float lo, float hi) { const f32x2 v = {lo, hi}; return __builtin_bit_cast(unsigned, __builtin_convertvector(v, bf16x2_t)); }
; #define PG8_MMA(ai, bj, At, Bt) do { __builtin_amdgcn_s_setprio(1); _Pragma("unroll") for (int m = 0; m < 4; ++m) _Pragma("unroll") for (int n = 0; n < 2; ++n) _Pragma("unroll") for (int k = 0; k < 2; ++k) \
;         acc[ai][bj][m][n] = __builtin_amdgcn_mfma_f32_16x16x32_bf16(Bt[n][k], At[m][k], acc[ai][bj][m][n], 0, 0, 0); __builtin_amdgcn_s_setprio(0); } while (0)
; #define PG8_WAIT_V(n) asm volatile("s_waitcnt vmcnt(" #n ")" ::: "memory")
; #define PG8_WAIT_L(n) asm volatile("s_waitcnt lgkmcnt(" #n ")" ::: "memory")
; #define PG8_BAR __builtin_amdgcn_s_barrier()
; #define PG8_SCHED __builtin_amdgcn_sched_barrier(0)
;     template <class Sched> __device__ __forceinline__ void operator()(const f32x4 (&acc)[2][2][4][2], const Unit& u, const Sched& S, int wr, int wc, int fr, int fq) const {
;     ...
;                 for (int m = 0; m < 4; ++m) { bf16_t* rowp = base + (size_t)(rl0 + ai * HALF + m * 16) * ldo + cl0;
; #pragma unroll
;                     for (int bj = 0; bj < 2; ++bj) { const f32x4 v0 = acc[ai][bj][m][0], v1 = acc[ai][bj][m][1];
;                         u32x4 w; w.x = cvt_pk_bf16(v0[0], v0[1]); w.y = cvt_pk_bf16(v0[2], v0[3]); w.z = cvt_pk_bf16(v1[0], v1[1]); w.w = cvt_pk_bf16(v1[2], v1[3]);
;                         *(u32x4*)(rowp + bj * HALF) = w; } }
; template <class Epi, class Sched, bool ALIGN_EPI>
; __device__ __forceinline__ void gemm_phase(LAS unsigned char* lds, const int wid, const int lda_, const int ldb_, const int K_, const Sched& S, const Epi& E) {
;     ...
;             PG8_WAIT_V(8); PG8_WAIT_L(0); PG8_BAR; PG8_MMA(1, 0, At, B0); PG8_MMA(1, 1, At, B1); PG8_BAR; PG8_SCHED;
;         }
;         if constexpr (ALIGN_EPI) { if (wr == 0) PG8_BAR; }
;         E(acc, cur, S, wr, wc, fr, fq);
;         if (!has_next) break;
	s_setprio 1
	s_waitcnt lgkmcnt(0)
	v_mfma_f32_16x16x32_bf16 v[60:63], v[160:163], v[196:199], v[60:63]
	v_mfma_f32_16x16x32_bf16 v[56:59], v[168:171], v[196:199], v[56:59]
	v_mfma_f32_16x16x32_bf16 v[52:55], v[160:163], v[204:207], v[52:55]
	v_mfma_f32_16x16x32_bf16 v[48:51], v[168:171], v[204:207], v[48:51]
	v_mfma_f32_16x16x32_bf16 v[36:39], v[160:163], v[212:215], v[36:39]
	v_mfma_f32_16x16x32_bf16 v[32:35], v[168:171], v[212:215], v[32:35]
	v_mfma_f32_16x16x32_bf16 v[20:23], v[160:163], v[220:223], v[20:23]
	v_mfma_f32_16x16x32_bf16 v[16:19], v[168:171], v[220:223], v[16:19]
	v_mfma_f32_16x16x32_bf16 v[60:63], v[164:167], v[200:203], v[60:63]
	v_mfma_f32_16x16x32_bf16 v[56:59], v[172:175], v[200:203], v[56:59]
	v_mfma_f32_16x16x32_bf16 v[52:55], v[164:167], v[208:211], v[52:55]
	v_mfma_f32_16x16x32_bf16 v[48:51], v[172:175], v[208:211], v[48:51]
	v_mfma_f32_16x16x32_bf16 v[36:39], v[164:167], v[216:219], v[36:39]
	v_mfma_f32_16x16x32_bf16 v[32:35], v[172:175], v[216:219], v[32:35]
	v_mfma_f32_16x16x32_bf16 v[20:23], v[164:167], v[224:227], v[20:23]
	v_mfma_f32_16x16x32_bf16 v[16:19], v[172:175], v[224:227], v[16:19]
	s_setprio 0
	s_setprio 1
	v_mfma_f32_16x16x32_bf16 v[44:47], v[180:183], v[196:199], v[44:47]
	v_mfma_f32_16x16x32_bf16 v[40:43], v[188:191], v[196:199], v[40:43]
	v_mfma_f32_16x16x32_bf16 v[28:31], v[180:183], v[204:207], v[28:31]
	v_mfma_f32_16x16x32_bf16 v[24:27], v[188:191], v[204:207], v[24:27]
	v_mfma_f32_16x16x32_bf16 v[12:15], v[180:183], v[212:215], v[12:15]
	v_mfma_f32_16x16x32_bf16 v[8:11], v[188:191], v[212:215], v[8:11]
	v_mfma_f32_16x16x32_bf16 v[4:7], v[180:183], v[220:223], v[4:7]
	v_mfma_f32_16x16x32_bf16 v[0:3], v[188:191], v[220:223], v[0:3]
	v_mfma_f32_16x16x32_bf16 v[44:47], v[184:187], v[200:203], v[44:47]
	v_mfma_f32_16x16x32_bf16 v[40:43], v[192:195], v[200:203], v[40:43]
	v_mfma_f32_16x16x32_bf16 v[28:31], v[184:187], v[208:211], v[28:31]
	v_mfma_f32_16x16x32_bf16 v[24:27], v[192:195], v[208:211], v[24:27]
	v_mfma_f32_16x16x32_bf16 v[12:15], v[184:187], v[216:219], v[12:15]
	v_mfma_f32_16x16x32_bf16 v[8:11], v[192:195], v[216:219], v[8:11]
	v_mfma_f32_16x16x32_bf16 v[4:7], v[184:187], v[224:227], v[4:7]
	v_mfma_f32_16x16x32_bf16 v[0:3], v[192:195], v[224:227], v[0:3]
	s_setprio 0
	s_barrier
	s_add_i32 s78, s78, 2
	s_add_u32 s50, s50, 0x100
	s_addc_u32 s51, s51, 0
	s_cmp_gt_u32 s78, 29
	s_cbranch_scc0 .LBB0_1120
	s_sub_i32 s4, s38, 22
	s_ashr_i32 s5, s38, 31
	s_cmp_lt_i32 s38, 22
	s_cselect_b32 s5, s5, 0
	s_cselect_b32 s4, s38, s4
	s_mov_b32 s17, 0x2bc00000
	s_cselect_b32 s17, 0x1f600000, s17
	s_lshl_b64 s[4:5], s[4:5], 9
	s_add_u32 s4, s66, s4
	s_addc_u32 s5, s67, s5
	s_add_u32 s4, s4, s17
	s_addc_u32 s5, s5, 0
	s_mul_i32 s27, s34, 0x2c0000
	s_mul_hi_i32 s17, s34, 0x2c0000
	s_add_u32 s4, s4, s27
	s_addc_u32 s5, s5, s17
	s_movk_i32 s17, 0x1600
	v_lshl_add_u64 v[156:157], v[136:137], 1, s[4:5]
	v_mad_i64_i32 v[158:159], s[4:5], s17, v134, 0
	v_lshl_add_u64 v[158:159], v[158:159], 1, v[156:157]
	v_cvt_pk_bf16_f32 v108, v108, v109
	v_cvt_pk_bf16_f32 v109, v110, v111
	v_cvt_pk_bf16_f32 v110, v104, v105
	v_cvt_pk_bf16_f32 v111, v106, v107
	v_mad_i64_i32 v[104:105], s[4:5], s17, v138, 0
	v_cvt_pk_bf16_f32 v124, v124, v125
	v_cvt_pk_bf16_f32 v125, v126, v127
	v_cvt_pk_bf16_f32 v126, v120, v121
	v_cvt_pk_bf16_f32 v127, v122, v123
	global_store_dwordx4 v[158:159], v[108:111], off offset:256
	v_cvt_pk_bf16_f32 v92, v92, v93
	v_cvt_pk_bf16_f32 v93, v94, v95
	v_lshl_add_u64 v[108:109], v[104:105], 1, v[156:157]
	v_cvt_pk_bf16_f32 v94, v88, v89
	v_cvt_pk_bf16_f32 v95, v90, v91
	v_mad_i64_i32 v[88:89], s[4:5], s17, v140, 0
	global_store_dwordx4 v[158:159], v[124:127], off
	v_cvt_pk_bf16_f32 v104, v116, v117
	v_cvt_pk_bf16_f32 v105, v118, v119
	v_cvt_pk_bf16_f32 v106, v112, v113
	v_cvt_pk_bf16_f32 v107, v114, v115
	global_store_dwordx4 v[108:109], v[92:95], off offset:256
	v_cvt_pk_bf16_f32 v76, v76, v77
	v_cvt_pk_bf16_f32 v77, v78, v79
	v_lshl_add_u64 v[92:93], v[88:89], 1, v[156:157]
	v_cvt_pk_bf16_f32 v78, v72, v73
	v_cvt_pk_bf16_f32 v79, v74, v75
	v_mad_i64_i32 v[72:73], s[4:5], s17, v142, 0
	v_cvt_pk_bf16_f32 v68, v68, v69
	v_cvt_pk_bf16_f32 v69, v70, v71
	v_cvt_pk_bf16_f32 v70, v64, v65
	v_mad_i64_i32 v[64:65], s[4:5], s17, v144, 0
	global_store_dwordx4 v[108:109], v[104:107], off
	v_cvt_pk_bf16_f32 v88, v100, v101
	v_cvt_pk_bf16_f32 v89, v102, v103
	v_cvt_pk_bf16_f32 v90, v96, v97
	v_cvt_pk_bf16_f32 v91, v98, v99
	global_store_dwordx4 v[92:93], v[76:79], off offset:256
	v_cvt_pk_bf16_f32 v74, v80, v81
	v_cvt_pk_bf16_f32 v75, v82, v83
	v_lshl_add_u64 v[76:77], v[72:73], 1, v[156:157]
	v_cvt_pk_bf16_f32 v72, v84, v85
	v_cvt_pk_bf16_f32 v73, v86, v87
	v_cvt_pk_bf16_f32 v71, v66, v67
	v_lshl_add_u64 v[64:65], v[64:65], 1, v[156:157]
	v_cvt_pk_bf16_f32 v44, v44, v45
	v_cvt_pk_bf16_f32 v45, v46, v47
	v_cvt_pk_bf16_f32 v46, v40, v41
	v_cvt_pk_bf16_f32 v47, v42, v43
	v_mad_i64_i32 v[40:41], s[4:5], s17, v146, 0
	global_store_dwordx4 v[92:93], v[88:91], off
	global_store_dwordx4 v[76:77], v[72:75], off
	global_store_dwordx4 v[76:77], v[68:71], off offset:256
	v_cvt_pk_bf16_f32 v60, v60, v61
	v_cvt_pk_bf16_f32 v61, v62, v63
	v_cvt_pk_bf16_f32 v62, v56, v57
	v_cvt_pk_bf16_f32 v63, v58, v59
	global_store_dwordx4 v[64:65], v[44:47], off offset:256
	v_cvt_pk_bf16_f32 v28, v28, v29
	v_cvt_pk_bf16_f32 v29, v30, v31
	v_lshl_add_u64 v[44:45], v[40:41], 1, v[156:157]
	v_cvt_pk_bf16_f32 v30, v24, v25
	v_cvt_pk_bf16_f32 v31, v26, v27
	v_mad_i64_i32 v[24:25], s[4:5], s17, v148, 0
	global_store_dwordx4 v[64:65], v[60:63], off
	v_cvt_pk_bf16_f32 v40, v52, v53
	v_cvt_pk_bf16_f32 v41, v54, v55
	v_cvt_pk_bf16_f32 v42, v48, v49
	v_cvt_pk_bf16_f32 v43, v50, v51
	global_store_dwordx4 v[44:45], v[28:31], off offset:256
	v_cvt_pk_bf16_f32 v12, v12, v13
	v_cvt_pk_bf16_f32 v13, v14, v15
	v_lshl_add_u64 v[28:29], v[24:25], 1, v[156:157]
	v_cvt_pk_bf16_f32 v14, v8, v9
	v_cvt_pk_bf16_f32 v15, v10, v11
	v_mad_i64_i32 v[8:9], s[4:5], s17, v150, 0
	global_store_dwordx4 v[44:45], v[40:43], off
	v_cvt_pk_bf16_f32 v24, v36, v37
	v_cvt_pk_bf16_f32 v25, v38, v39
	v_cvt_pk_bf16_f32 v26, v32, v33
	v_cvt_pk_bf16_f32 v27, v34, v35
	global_store_dwordx4 v[28:29], v[12:15], off offset:256
	v_cvt_pk_bf16_f32 v10, v16, v17
	v_cvt_pk_bf16_f32 v11, v18, v19
	v_lshl_add_u64 v[12:13], v[8:9], 1, v[156:157]
	v_cvt_pk_bf16_f32 v8, v20, v21
	v_cvt_pk_bf16_f32 v9, v22, v23
	v_cvt_pk_bf16_f32 v4, v4, v5
	v_cvt_pk_bf16_f32 v5, v6, v7
	v_cvt_pk_bf16_f32 v6, v0, v1
	v_cvt_pk_bf16_f32 v7, v2, v3
	s_and_b64 vcc, exec, s[36:37]
	s_mov_b32 s38, s42
	s_mov_b32 s34, s44
	s_mov_b64 s[50:51], s[48:49]
	s_mov_b64 s[40:41], s[46:47]
	global_store_dwordx4 v[28:29], v[24:27], off
	global_store_dwordx4 v[12:13], v[8:11], off
	global_store_dwordx4 v[12:13], v[4:7], off offset:256
	s_cbranch_vccz .LBB0_1117
	v_readlane_b32 s4, v253, 1
	s_waitcnt vmcnt(0)
	v_readlane_b32 s5, v253, 2
	s_andn2_b64 vcc, exec, s[4:5]
	s_cbranch_vccnz .LBB0_1124
	s_barrier

; #define PG8_STAGE(bufoff, gbase, voff) do { _Pragma("unroll") for (int _i = 0; _i < 2; ++_i) \
;         __builtin_amdgcn_global_load_lds((const unsigned*)((const char*)(gbase) + (voff)[_i]), (LAS unsigned*)(lds + (bufoff) + ldsw + _i * 8192), 16, 0, 0); } while (0)
; #define PG8_LDA(dst, b, h) do { _Pragma("unroll") for (int m = 0; m < 4; ++m) _Pragma("unroll") for (int k = 0; k < 2; ++k) dst[m][k] = *(const LAS bf16x8*)(lds + PG8_SA(b, h) + aoff + m * 2048 + k * 1024); } while (0)
; #define PG8_LDB(dst, b, h) do { _Pragma("unroll") for (int n = 0; n < 2; ++n) _Pragma("unroll") for (int k = 0; k < 2; ++k) dst[n][k] = *(const LAS bf16x8*)(lds + PG8_SB(b, h) + boff + n * 2048 + k * 1024); } while (0)
; #define PG8_MMA(ai, bj, At, Bt) do { __builtin_amdgcn_s_setprio(1); _Pragma("unroll") for (int m = 0; m < 4; ++m) _Pragma("unroll") for (int n = 0; n < 2; ++n) _Pragma("unroll") for (int k = 0; k < 2; ++k) \
;         acc[ai][bj][m][n] = __builtin_amdgcn_mfma_f32_16x16x32_bf16(Bt[n][k], At[m][k], acc[ai][bj][m][n], 0, 0, 0); __builtin_amdgcn_s_setprio(0); } while (0)
; template <class Epi, class Sched, bool ALIGN_EPI>
; __device__ __forceinline__ void gemm_phase(LAS unsigned char* lds, const int wid, const int lda_, const int ldb_, const int K_, const Sched& S, const Epi& E) {
;     ...
;         const bool has_next = S.next(ui + 1, nxt);
;         const int nt = S.nt(cur);
;         const char* nA = has_next ? S.a(nxt) : cA; const char* nB = has_next ? S.b(nxt) : cB;
; #pragma unroll 1
;         for (int t = 0; t < nt; t += 2) {
;             const bool last = (t == nt - 2);
;             const char* a1 = cA + (size_t)(t + 1) * kstep;
;             const char* a2 = last ? nA : cA + (size_t)(t + 2) * kstep; const char* b2 = last ? nB : cB + (size_t)(t + 2) * kstep;
;             const char* a3 = a2 + kstep; const char* b3 = b2 + kstep;
;             PG8_LDB(B0, 0, 0); PG8_LDB(B1, 0, 1); PG8_SCHED; PG8_LDA(At, 0, 0); PG8_STAGE(PG8_SA(1, 1), a1 + hstepA, voffA);
;             PG8_WAIT_V(8); PG8_WAIT_L(0); PG8_BAR; PG8_MMA(0, 0, At, B0); PG8_MMA(0, 1, At, B1); PG8_BAR; PG8_SCHED;
;             PG8_LDA(At, 0, 1); PG8_STAGE(PG8_SB(0, 0), b2, voffB); PG8_STAGE(PG8_SB(0, 1), b2 + hstepB, voffB); PG8_STAGE(PG8_SA(0, 0), a2, voffA);
;             PG8_WAIT_V(8); PG8_WAIT_L(0); PG8_BAR; PG8_MMA(1, 0, At, B0); PG8_MMA(1, 1, At, B1); PG8_BAR; PG8_SCHED;
.LBB0_1340:
	s_cmp_gt_i32 s38, -1
	s_cselect_b64 s[44:45], -1, 0
	s_cmp_lt_i32 s38, 0
	s_cselect_b32 s4, 0x58, 22
	s_add_i32 s5, s4, -2
	s_add_u32 s46, s46, 0x80
	s_addc_u32 s47, s47, 0
	s_add_u32 s31, s48, 0x100
	s_mov_b32 s39, 0
	s_addc_u32 s35, s49, 0
	s_add_i32 s76, s39, 2
	s_add_u32 s17, s46, 0x80
	s_addc_u32 s27, s47, 0
	s_add_i32 s77, 0, 0x10000
	s_cmp_eq_u32 s5, s39
	s_cselect_b32 s49, s43, s27
	s_cselect_b32 s48, s42, s17
	v_add_u32_e32 v141, s77, v135
	s_cselect_b32 s79, s37, s35
	s_cselect_b32 s78, s36, s31
	s_add_i32 s17, 0, 0x14000
	ds_read_b128 v[156:159], v141
	ds_read_b128 v[160:163], v141 offset:1024
	ds_read_b128 v[164:167], v141 offset:2048
	ds_read_b128 v[168:171], v141 offset:3072
	v_add_u32_e32 v141, s17, v135
	ds_read_b128 v[172:175], v141
	ds_read_b128 v[180:183], v141 offset:1024
	ds_read_b128 v[184:187], v141 offset:2048
	ds_read_b128 v[188:191], v141 offset:3072
	v_lshl_add_u64 v[224:225], s[46:47], 0, v[152:153]
	s_add_i32 m0, s16, 0xc000
	ds_read_b128 v[192:195], v139
	ds_read_b128 v[196:199], v139 offset:1024
	ds_read_b128 v[200:203], v139 offset:2048
	ds_read_b128 v[204:207], v139 offset:3072
	ds_read_b128 v[208:211], v139 offset:4096
	ds_read_b128 v[212:215], v139 offset:5120
	ds_read_b128 v[216:219], v139 offset:6144
	ds_read_b128 v[220:223], v139 offset:7168
	global_load_lds_dwordx4 v[224:225], off
	v_lshl_add_u64 v[224:225], s[46:47], 0, v[154:155]
	s_add_i32 m0, s16, 0xe000
	s_nop 0
	global_load_lds_dwordx4 v[224:225], off
	s_waitcnt vmcnt(8)
	s_waitcnt lgkmcnt(0)
	s_barrier
	s_setprio 1
	s_waitcnt lgkmcnt(0)
	v_mfma_f32_16x16x32_bf16 v[124:127], v[156:159], v[192:195], 0
	v_mfma_f32_16x16x32_bf16 v[120:123], v[164:167], v[192:195], 0
	v_mfma_f32_16x16x32_bf16 v[116:119], v[156:159], v[200:203], 0
	v_mfma_f32_16x16x32_bf16 v[112:115], v[164:167], v[200:203], 0
	v_mfma_f32_16x16x32_bf16 v[100:103], v[156:159], v[208:211], 0
	v_mfma_f32_16x16x32_bf16 v[96:99], v[164:167], v[208:211], 0
	v_mfma_f32_16x16x32_bf16 v[84:87], v[156:159], v[216:219], 0
	v_mfma_f32_16x16x32_bf16 v[80:83], v[164:167], v[216:219], 0
	v_mfma_f32_16x16x32_bf16 v[124:127], v[160:163], v[196:199], v[124:127]
	v_mfma_f32_16x16x32_bf16 v[120:123], v[168:171], v[196:199], v[120:123]
	v_mfma_f32_16x16x32_bf16 v[116:119], v[160:163], v[204:207], v[116:119]
	v_mfma_f32_16x16x32_bf16 v[112:115], v[168:171], v[204:207], v[112:115]
	v_mfma_f32_16x16x32_bf16 v[100:103], v[160:163], v[212:215], v[100:103]
	v_mfma_f32_16x16x32_bf16 v[96:99], v[168:171], v[212:215], v[96:99]
	v_mfma_f32_16x16x32_bf16 v[84:87], v[160:163], v[220:223], v[84:87]
	v_mfma_f32_16x16x32_bf16 v[80:83], v[168:171], v[220:223], v[80:83]
	s_setprio 0
	s_setprio 1
	v_mfma_f32_16x16x32_bf16 v[108:111], v[172:175], v[192:195], 0
	v_mfma_f32_16x16x32_bf16 v[104:107], v[184:187], v[192:195], 0
	v_mfma_f32_16x16x32_bf16 v[92:95], v[172:175], v[200:203], 0
	v_mfma_f32_16x16x32_bf16 v[88:91], v[184:187], v[200:203], 0
	v_mfma_f32_16x16x32_bf16 v[76:79], v[172:175], v[208:211], 0
	v_mfma_f32_16x16x32_bf16 v[72:75], v[184:187], v[208:211], 0
	v_mfma_f32_16x16x32_bf16 v[68:71], v[172:175], v[216:219], 0
	v_mfma_f32_16x16x32_bf16 v[64:67], v[184:187], v[216:219], 0
	v_mfma_f32_16x16x32_bf16 v[108:111], v[180:183], v[196:199], v[108:111]
	v_mfma_f32_16x16x32_bf16 v[104:107], v[188:191], v[196:199], v[104:107]
	v_mfma_f32_16x16x32_bf16 v[92:95], v[180:183], v[204:207], v[92:95]
	v_mfma_f32_16x16x32_bf16 v[88:91], v[188:191], v[204:207], v[88:91]
	v_mfma_f32_16x16x32_bf16 v[76:79], v[180:183], v[212:215], v[76:79]
	v_mfma_f32_16x16x32_bf16 v[72:75], v[188:191], v[212:215], v[72:75]
	v_mfma_f32_16x16x32_bf16 v[68:71], v[180:183], v[220:223], v[68:71]
	v_mfma_f32_16x16x32_bf16 v[64:67], v[188:191], v[220:223], v[64:67]
	s_setprio 0
	s_barrier
; #define PG8_STAGE(bufoff, gbase, voff) do { _Pragma("unroll") for (int _i = 0; _i < 2; ++_i) \
;         __builtin_amdgcn_global_load_lds((const unsigned*)((const char*)(gbase) + (voff)[_i]), (LAS unsigned*)(lds + (bufoff) + ldsw + _i * 8192), 16, 0, 0); } while (0)
; #define PG8_LDA(dst, b, h) do { _Pragma("unroll") for (int m = 0; m < 4; ++m) _Pragma("unroll") for (int k = 0; k < 2; ++k) dst[m][k] = *(const LAS bf16x8*)(lds + PG8_SA(b, h) + aoff + m * 2048 + k * 1024); } while (0)
; #define PG8_MMA(ai, bj, At, Bt) do { __builtin_amdgcn_s_setprio(1); _Pragma("unroll") for (int m = 0; m < 4; ++m) _Pragma("unroll") for (int n = 0; n < 2; ++n) _Pragma("unroll") for (int k = 0; k < 2; ++k) \
;         acc[ai][bj][m][n] = __builtin_amdgcn_mfma_f32_16x16x32_bf16(Bt[n][k], At[m][k], acc[ai][bj][m][n], 0, 0, 0); __builtin_amdgcn_s_setprio(0); } while (0)
; #define PG8_WAIT_V(n) asm volatile("s_waitcnt vmcnt(" #n ")" ::: "memory")
; #define PG8_WAIT_L(n) asm volatile("s_waitcnt lgkmcnt(" #n ")" ::: "memory")
; #define PG8_BAR __builtin_amdgcn_s_barrier()
; #define PG8_SCHED __builtin_amdgcn_sched_barrier(0)
; template <class Epi, class Sched, bool ALIGN_EPI>
; __device__ __forceinline__ void gemm_phase(LAS unsigned char* lds, const int wid, const int lda_, const int ldb_, const int K_, const Sched& S, const Epi& E) {
;     ...
;             PG8_LDA(At, 0, 1); PG8_STAGE(PG8_SB(0, 0), b2, voffB); PG8_STAGE(PG8_SB(0, 1), b2 + hstepB, voffB); PG8_STAGE(PG8_SA(0, 0), a2, voffA);
;             PG8_WAIT_V(8); PG8_WAIT_L(0); PG8_BAR; PG8_MMA(1, 0, At, B0); PG8_MMA(1, 1, At, B1); PG8_BAR; PG8_SCHED;
	s_add_i32 s27, s77, s3
	v_lshl_add_u64 v[224:225], s[78:79], 0, v[176:177]
	s_mov_b32 m0, s27
	ds_read_b128 v[192:195], v139 offset:16384
	ds_read_b128 v[196:199], v139 offset:17408
	ds_read_b128 v[200:203], v139 offset:18432
	ds_read_b128 v[204:207], v139 offset:19456
	ds_read_b128 v[208:211], v139 offset:20480
	ds_read_b128 v[212:215], v139 offset:21504
	ds_read_b128 v[216:219], v139 offset:22528
	ds_read_b128 v[220:223], v139 offset:23552
	global_load_lds_dwordx4 v[224:225], off
	s_add_i32 m0, s27, 0x2000
	v_lshl_add_u64 v[226:227], s[78:79], 0, v[132:133]
	s_add_u32 s78, s78, s10
	s_addc_u32 s79, s79, s11
	s_add_i32 s17, s17, s3
	global_load_lds_dwordx4 v[226:227], off
	v_lshl_add_u64 v[228:229], s[78:79], 0, v[176:177]
	s_mov_b32 m0, s17
	v_lshl_add_u64 v[230:231], s[78:79], 0, v[132:133]
	global_load_lds_dwordx4 v[228:229], off
	s_add_i32 m0, s17, 0x2000
	v_lshl_add_u64 v[232:233], s[48:49], 0, v[128:129]
	global_load_lds_dwordx4 v[230:231], off
	s_mov_b32 m0, s16
	v_lshl_add_u64 v[234:235], s[48:49], 0, v[130:131]
	global_load_lds_dwordx4 v[232:233], off
	s_mov_b32 m0, s14
	s_nop 0
	global_load_lds_dwordx4 v[234:235], off
	s_waitcnt vmcnt(8)
	s_waitcnt lgkmcnt(0)
	s_barrier
	s_setprio 1
	s_waitcnt lgkmcnt(0)
	v_mfma_f32_16x16x32_bf16 v[60:63], v[156:159], v[192:195], 0
	v_mfma_f32_16x16x32_bf16 v[56:59], v[164:167], v[192:195], 0
	v_mfma_f32_16x16x32_bf16 v[52:55], v[156:159], v[200:203], 0
	v_mfma_f32_16x16x32_bf16 v[48:51], v[164:167], v[200:203], 0
	v_mfma_f32_16x16x32_bf16 v[36:39], v[156:159], v[208:211], 0
	v_mfma_f32_16x16x32_bf16 v[32:35], v[164:167], v[208:211], 0
	v_mfma_f32_16x16x32_bf16 v[20:23], v[156:159], v[216:219], 0
	v_mfma_f32_16x16x32_bf16 v[16:19], v[164:167], v[216:219], 0
	v_mfma_f32_16x16x32_bf16 v[60:63], v[160:163], v[196:199], v[60:63]
	v_mfma_f32_16x16x32_bf16 v[56:59], v[168:171], v[196:199], v[56:59]
	v_mfma_f32_16x16x32_bf16 v[52:55], v[160:163], v[204:207], v[52:55]
	v_mfma_f32_16x16x32_bf16 v[48:51], v[168:171], v[204:207], v[48:51]
	v_mfma_f32_16x16x32_bf16 v[36:39], v[160:163], v[212:215], v[36:39]
	v_mfma_f32_16x16x32_bf16 v[32:35], v[168:171], v[212:215], v[32:35]
	v_mfma_f32_16x16x32_bf16 v[20:23], v[160:163], v[220:223], v[20:23]
	v_mfma_f32_16x16x32_bf16 v[16:19], v[168:171], v[220:223], v[16:19]
	s_setprio 0
	s_setprio 1
	v_mfma_f32_16x16x32_bf16 v[44:47], v[172:175], v[192:195], 0
	v_mfma_f32_16x16x32_bf16 v[40:43], v[184:187], v[192:195], 0
	v_mfma_f32_16x16x32_bf16 v[28:31], v[172:175], v[200:203], 0
	v_mfma_f32_16x16x32_bf16 v[24:27], v[184:187], v[200:203], 0
	v_mfma_f32_16x16x32_bf16 v[12:15], v[172:175], v[208:211], 0
	v_mfma_f32_16x16x32_bf16 v[8:11], v[184:187], v[208:211], 0
	v_mfma_f32_16x16x32_bf16 v[4:7], v[172:175], v[216:219], 0
	v_mfma_f32_16x16x32_bf16 v[0:3], v[184:187], v[216:219], 0
	v_mfma_f32_16x16x32_bf16 v[44:47], v[180:183], v[196:199], v[44:47]
	v_mfma_f32_16x16x32_bf16 v[40:43], v[188:191], v[196:199], v[40:43]
	v_mfma_f32_16x16x32_bf16 v[28:31], v[180:183], v[204:207], v[28:31]
	v_mfma_f32_16x16x32_bf16 v[24:27], v[188:191], v[204:207], v[24:27]
	v_mfma_f32_16x16x32_bf16 v[12:15], v[180:183], v[212:215], v[12:15]
	v_mfma_f32_16x16x32_bf16 v[8:11], v[188:191], v[212:215], v[8:11]
	v_mfma_f32_16x16x32_bf16 v[4:7], v[180:183], v[220:223], v[4:7]
	v_mfma_f32_16x16x32_bf16 v[0:3], v[188:191], v[220:223], v[0:3]
	s_setprio 0
	s_barrier
	s_branch .Lgemm_join_1341

; #define PG8_STAGE(bufoff, gbase, voff) do { _Pragma("unroll") for (int _i = 0; _i < 2; ++_i) \
;         __builtin_amdgcn_global_load_lds((const unsigned*)((const char*)(gbase) + (voff)[_i]), (LAS unsigned*)(lds + (bufoff) + ldsw + _i * 8192), 16, 0, 0); } while (0)
; #define PG8_LDA(dst, b, h) do { _Pragma("unroll") for (int m = 0; m < 4; ++m) _Pragma("unroll") for (int k = 0; k < 2; ++k) dst[m][k] = *(const LAS bf16x8*)(lds + PG8_SA(b, h) + aoff + m * 2048 + k * 1024); } while (0)
; #define PG8_LDB(dst, b, h) do { _Pragma("unroll") for (int n = 0; n < 2; ++n) _Pragma("unroll") for (int k = 0; k < 2; ++k) dst[n][k] = *(const LAS bf16x8*)(lds + PG8_SB(b, h) + boff + n * 2048 + k * 1024); } while (0)
; #define PG8_MMA(ai, bj, At, Bt) do { __builtin_amdgcn_s_setprio(1); _Pragma("unroll") for (int m = 0; m < 4; ++m) _Pragma("unroll") for (int n = 0; n < 2; ++n) _Pragma("unroll") for (int k = 0; k < 2; ++k) \
;         acc[ai][bj][m][n] = __builtin_amdgcn_mfma_f32_16x16x32_bf16(Bt[n][k], At[m][k], acc[ai][bj][m][n], 0, 0, 0); __builtin_amdgcn_s_setprio(0); } while (0)
; #define PG8_WAIT_V(n) asm volatile("s_waitcnt vmcnt(" #n ")" ::: "memory")
; #define PG8_WAIT_L(n) asm volatile("s_waitcnt lgkmcnt(" #n ")" ::: "memory")
; #define PG8_BAR __builtin_amdgcn_s_barrier()
; #define PG8_SCHED __builtin_amdgcn_sched_barrier(0)
; template <class Epi, class Sched, bool ALIGN_EPI>
; __device__ __forceinline__ void gemm_phase(LAS unsigned char* lds, const int wid, const int lda_, const int ldb_, const int K_, const Sched& S, const Epi& E) {
;     ...
;             PG8_LDB(B0, 1, 0); PG8_LDB(B1, 1, 1); PG8_SCHED; PG8_LDA(At, 1, 0); PG8_STAGE(PG8_SA(0, 1), a2 + hstepA, voffA);
;             PG8_WAIT_V(8); PG8_WAIT_L(0); PG8_BAR; PG8_MMA(0, 0, At, B0); PG8_MMA(0, 1, At, B1); PG8_BAR; PG8_SCHED;
.Lgemm_join_1341:
	s_add_i32 s17, 0, 0x18000
	v_add_u32_e32 v141, s17, v135
	s_add_i32 s27, 0, 0x1c000
	ds_read_b128 v[156:159], v141
	ds_read_b128 v[160:163], v141 offset:1024
	ds_read_b128 v[164:167], v141 offset:2048
	ds_read_b128 v[168:171], v141 offset:3072
	v_add_u32_e32 v141, s27, v135
	ds_read_b128 v[172:175], v141
	ds_read_b128 v[180:183], v141 offset:1024
	ds_read_b128 v[184:187], v141 offset:2048
	ds_read_b128 v[188:191], v141 offset:3072
	s_add_u32 s48, s48, s0
	s_addc_u32 s49, s49, s1
	s_mov_b32 m0, s15
	v_lshl_add_u64 v[236:237], s[48:49], 0, v[128:129]
	ds_read_b128 v[192:195], v139 offset:32768
	ds_read_b128 v[196:199], v139 offset:33792
	ds_read_b128 v[200:203], v139 offset:34816
	ds_read_b128 v[204:207], v139 offset:35840
	ds_read_b128 v[208:211], v139 offset:36864
	ds_read_b128 v[212:215], v139 offset:37888
	ds_read_b128 v[216:219], v139 offset:38912
	ds_read_b128 v[220:223], v139 offset:39936
	global_load_lds_dwordx4 v[236:237], off
	v_lshl_add_u64 v[236:237], s[48:49], 0, v[130:131]
	s_mov_b32 m0, s26
	s_nop 0
	global_load_lds_dwordx4 v[236:237], off
	s_waitcnt vmcnt(8)
	s_waitcnt lgkmcnt(0)
	s_barrier
	s_setprio 1
	s_waitcnt lgkmcnt(0)
	v_mfma_f32_16x16x32_bf16 v[124:127], v[156:159], v[192:195], v[124:127]
	v_mfma_f32_16x16x32_bf16 v[120:123], v[164:167], v[192:195], v[120:123]
	v_mfma_f32_16x16x32_bf16 v[116:119], v[156:159], v[200:203], v[116:119]
	v_mfma_f32_16x16x32_bf16 v[112:115], v[164:167], v[200:203], v[112:115]
	v_mfma_f32_16x16x32_bf16 v[100:103], v[156:159], v[208:211], v[100:103]
	v_mfma_f32_16x16x32_bf16 v[96:99], v[164:167], v[208:211], v[96:99]
	v_mfma_f32_16x16x32_bf16 v[84:87], v[156:159], v[216:219], v[84:87]
	v_mfma_f32_16x16x32_bf16 v[80:83], v[164:167], v[216:219], v[80:83]
	v_mfma_f32_16x16x32_bf16 v[124:127], v[160:163], v[196:199], v[124:127]
	v_mfma_f32_16x16x32_bf16 v[120:123], v[168:171], v[196:199], v[120:123]
	v_mfma_f32_16x16x32_bf16 v[116:119], v[160:163], v[204:207], v[116:119]
	v_mfma_f32_16x16x32_bf16 v[112:115], v[168:171], v[204:207], v[112:115]
	v_mfma_f32_16x16x32_bf16 v[100:103], v[160:163], v[212:215], v[100:103]
	v_mfma_f32_16x16x32_bf16 v[96:99], v[168:171], v[212:215], v[96:99]
	v_mfma_f32_16x16x32_bf16 v[84:87], v[160:163], v[220:223], v[84:87]
	v_mfma_f32_16x16x32_bf16 v[80:83], v[168:171], v[220:223], v[80:83]
	s_setprio 0
	s_setprio 1
	v_mfma_f32_16x16x32_bf16 v[108:111], v[172:175], v[192:195], v[108:111]
	v_mfma_f32_16x16x32_bf16 v[104:107], v[184:187], v[192:195], v[104:107]
	v_mfma_f32_16x16x32_bf16 v[92:95], v[172:175], v[200:203], v[92:95]
	v_mfma_f32_16x16x32_bf16 v[88:91], v[184:187], v[200:203], v[88:91]
	v_mfma_f32_16x16x32_bf16 v[76:79], v[172:175], v[208:211], v[76:79]
	v_mfma_f32_16x16x32_bf16 v[72:75], v[184:187], v[208:211], v[72:75]
	v_mfma_f32_16x16x32_bf16 v[68:71], v[172:175], v[216:219], v[68:71]
	v_mfma_f32_16x16x32_bf16 v[64:67], v[184:187], v[216:219], v[64:67]
	v_mfma_f32_16x16x32_bf16 v[108:111], v[180:183], v[196:199], v[108:111]
	v_mfma_f32_16x16x32_bf16 v[104:107], v[188:191], v[196:199], v[104:107]
	v_mfma_f32_16x16x32_bf16 v[92:95], v[180:183], v[204:207], v[92:95]
	v_mfma_f32_16x16x32_bf16 v[88:91], v[188:191], v[204:207], v[88:91]
	v_mfma_f32_16x16x32_bf16 v[76:79], v[180:183], v[212:215], v[76:79]
	v_mfma_f32_16x16x32_bf16 v[72:75], v[188:191], v[212:215], v[72:75]
	v_mfma_f32_16x16x32_bf16 v[68:71], v[180:183], v[220:223], v[68:71]
	v_mfma_f32_16x16x32_bf16 v[64:67], v[188:191], v[220:223], v[64:67]
	s_setprio 0
	s_barrier
; #define PG8_STAGE(bufoff, gbase, voff) do { _Pragma("unroll") for (int _i = 0; _i < 2; ++_i) \
;         __builtin_amdgcn_global_load_lds((const unsigned*)((const char*)(gbase) + (voff)[_i]), (LAS unsigned*)(lds + (bufoff) + ldsw + _i * 8192), 16, 0, 0); } while (0)
; #define PG8_LDA(dst, b, h) do { _Pragma("unroll") for (int m = 0; m < 4; ++m) _Pragma("unroll") for (int k = 0; k < 2; ++k) dst[m][k] = *(const LAS bf16x8*)(lds + PG8_SA(b, h) + aoff + m * 2048 + k * 1024); } while (0)
; #define PG8_MMA(ai, bj, At, Bt) do { __builtin_amdgcn_s_setprio(1); _Pragma("unroll") for (int m = 0; m < 4; ++m) _Pragma("unroll") for (int n = 0; n < 2; ++n) _Pragma("unroll") for (int k = 0; k < 2; ++k) \
;         acc[ai][bj][m][n] = __builtin_amdgcn_mfma_f32_16x16x32_bf16(Bt[n][k], At[m][k], acc[ai][bj][m][n], 0, 0, 0); __builtin_amdgcn_s_setprio(0); } while (0)
; #define PG8_WAIT_V(n) asm volatile("s_waitcnt vmcnt(" #n ")" ::: "memory")
; #define PG8_WAIT_L(n) asm volatile("s_waitcnt lgkmcnt(" #n ")" ::: "memory")
; #define PG8_BAR __builtin_amdgcn_s_barrier()
; #define PG8_SCHED __builtin_amdgcn_sched_barrier(0)
; template <class Epi, class Sched, bool ALIGN_EPI>
; __device__ __forceinline__ void gemm_phase(LAS unsigned char* lds, const int wid, const int lda_, const int ldb_, const int K_, const Sched& S, const Epi& E) {
;     ...
;             PG8_LDA(At, 1, 1); PG8_STAGE(PG8_SB(1, 0), b3, voffB); PG8_STAGE(PG8_SB(1, 1), b3 + hstepB, voffB); PG8_STAGE(PG8_SA(1, 0), a3, voffA);
;             PG8_WAIT_V(8); PG8_WAIT_L(0); PG8_BAR; PG8_MMA(1, 0, At, B0); PG8_MMA(1, 1, At, B1); PG8_BAR; PG8_SCHED;
;         }
;         if constexpr (ALIGN_EPI) { if (wr == 0) PG8_BAR; }
;         E(acc, cur, S, wr, wc, fr, fq);
;         if (!has_next) break;
;     __device__ __forceinline__ void out(const pg8::Unit& u, char*& o, int& ldo, int& kind) const { ldo = D;
;         if (u.kq < 0) { o = (char*)ws + YOFF + ((size_t)u.pm * 256 * D + (size_t)u.pn * 256) * 2; kind = 0; }
;         else { o = (char*)ws + WS_PART + (((size_t)u.kq * MCTX + (size_t)(u.pm - 64) * 256) * D + (size_t)u.pn * 256) * 2; kind = 0; } }
	s_add_i32 s17, s17, s3
	v_lshl_add_u64 v[224:225], v[224:225], 0, s[24:25]
	s_mov_b32 m0, s17
	ds_read_b128 v[192:195], v139 offset:49152
	ds_read_b128 v[196:199], v139 offset:50176
	ds_read_b128 v[200:203], v139 offset:51200
	ds_read_b128 v[204:207], v139 offset:52224
	ds_read_b128 v[208:211], v139 offset:53248
	ds_read_b128 v[212:215], v139 offset:54272
	ds_read_b128 v[216:219], v139 offset:55296
	ds_read_b128 v[220:223], v139 offset:56320
	global_load_lds_dwordx4 v[224:225], off
	v_lshl_add_u64 v[224:225], v[226:227], 0, s[24:25]
	s_add_i32 m0, s17, 0x2000
	s_add_i32 s17, s27, s3
	global_load_lds_dwordx4 v[224:225], off
	v_lshl_add_u64 v[224:225], v[228:229], 0, s[24:25]
	s_mov_b32 m0, s17
	s_nop 0
	global_load_lds_dwordx4 v[224:225], off
	v_lshl_add_u64 v[224:225], v[230:231], 0, s[24:25]
	s_add_i32 m0, s17, 0x2000
	s_nop 0
	global_load_lds_dwordx4 v[224:225], off
	v_lshl_add_u64 v[224:225], v[232:233], 0, s[24:25]
	s_mov_b32 m0, s50
	s_nop 0
	global_load_lds_dwordx4 v[224:225], off
	v_lshl_add_u64 v[224:225], v[234:235], 0, s[24:25]
	s_mov_b32 m0, s51
	s_nop 0
	global_load_lds_dwordx4 v[224:225], off
	s_waitcnt vmcnt(8)
	s_waitcnt lgkmcnt(0)
	s_barrier
	s_setprio 1
	s_waitcnt lgkmcnt(0)
	v_mfma_f32_16x16x32_bf16 v[60:63], v[156:159], v[192:195], v[60:63]
	v_mfma_f32_16x16x32_bf16 v[56:59], v[164:167], v[192:195], v[56:59]
	v_mfma_f32_16x16x32_bf16 v[52:55], v[156:159], v[200:203], v[52:55]
	v_mfma_f32_16x16x32_bf16 v[48:51], v[164:167], v[200:203], v[48:51]
	v_mfma_f32_16x16x32_bf16 v[36:39], v[156:159], v[208:211], v[36:39]
	v_mfma_f32_16x16x32_bf16 v[32:35], v[164:167], v[208:211], v[32:35]
	v_mfma_f32_16x16x32_bf16 v[20:23], v[156:159], v[216:219], v[20:23]
	v_mfma_f32_16x16x32_bf16 v[16:19], v[164:167], v[216:219], v[16:19]
	v_mfma_f32_16x16x32_bf16 v[60:63], v[160:163], v[196:199], v[60:63]
	v_mfma_f32_16x16x32_bf16 v[56:59], v[168:171], v[196:199], v[56:59]
	v_mfma_f32_16x16x32_bf16 v[52:55], v[160:163], v[204:207], v[52:55]
	v_mfma_f32_16x16x32_bf16 v[48:51], v[168:171], v[204:207], v[48:51]
	v_mfma_f32_16x16x32_bf16 v[36:39], v[160:163], v[212:215], v[36:39]
	v_mfma_f32_16x16x32_bf16 v[32:35], v[168:171], v[212:215], v[32:35]
	v_mfma_f32_16x16x32_bf16 v[20:23], v[160:163], v[220:223], v[20:23]
	v_mfma_f32_16x16x32_bf16 v[16:19], v[168:171], v[220:223], v[16:19]
	s_setprio 0
	s_setprio 1
	v_mfma_f32_16x16x32_bf16 v[44:47], v[172:175], v[192:195], v[44:47]
	v_mfma_f32_16x16x32_bf16 v[40:43], v[184:187], v[192:195], v[40:43]
	v_mfma_f32_16x16x32_bf16 v[28:31], v[172:175], v[200:203], v[28:31]
	v_mfma_f32_16x16x32_bf16 v[24:27], v[184:187], v[200:203], v[24:27]
	v_mfma_f32_16x16x32_bf16 v[12:15], v[172:175], v[208:211], v[12:15]
	v_mfma_f32_16x16x32_bf16 v[8:11], v[184:187], v[208:211], v[8:11]
	v_mfma_f32_16x16x32_bf16 v[4:7], v[172:175], v[216:219], v[4:7]
	v_mfma_f32_16x16x32_bf16 v[0:3], v[184:187], v[216:219], v[0:3]
	v_mfma_f32_16x16x32_bf16 v[44:47], v[180:183], v[196:199], v[44:47]
	v_mfma_f32_16x16x32_bf16 v[40:43], v[188:191], v[196:199], v[40:43]
	v_mfma_f32_16x16x32_bf16 v[28:31], v[180:183], v[204:207], v[28:31]
	v_mfma_f32_16x16x32_bf16 v[24:27], v[188:191], v[204:207], v[24:27]
	v_mfma_f32_16x16x32_bf16 v[12:15], v[180:183], v[212:215], v[12:15]
	v_mfma_f32_16x16x32_bf16 v[8:11], v[188:191], v[212:215], v[8:11]
	v_mfma_f32_16x16x32_bf16 v[4:7], v[180:183], v[220:223], v[4:7]
	v_mfma_f32_16x16x32_bf16 v[0:3], v[188:191], v[220:223], v[0:3]
	s_setprio 0
	s_barrier
	s_add_u32 s46, s46, 0x100
	s_addc_u32 s47, s47, 0
	s_add_u32 s31, s31, 0x100
	s_addc_u32 s35, s35, 0
	s_cmp_ge_u32 s76, s4
	s_mov_b32 s39, s76
	s_cbranch_scc0 .LBB0_1341
	s_mov_b64 s[46:47], -1
	s_and_b64 vcc, exec, s[44:45]
	s_cbranch_vccz .LBB0_1344
	s_mov_b32 s39, s92
	s_ashr_i32 s31, s30, 31
	s_ashr_i32 s35, s34, 31
	s_lshl_b64 s[4:5], s[30:31], 20
	s_lshl_b64 s[44:45], s[34:35], 9
	s_lshl_b64 s[38:39], s[38:39], 23
	v_readlane_b32 s46, v251, 28
	v_readlane_b32 s47, v251, 29
	s_add_u32 s17, s46, s44
	s_addc_u32 s27, s47, s45
	s_add_u32 s17, s17, s38
	s_addc_u32 s27, s27, s39
	s_add_u32 s4, s17, s4
	s_addc_u32 s5, s27, s5
	s_add_u32 s4, s4, 0xfc000000
	s_addc_u32 s5, s5, -1
	s_mov_b64 s[46:47], 0
